# first K-iteration of every GEMM unit peeled with C=0 on first accumulation; per-unit zeroing of 128 accumulator VGPRs removed
# baseline (speedup 1.0000x reference)
.LBB0_153:
	s_andn2_b64 vcc, exec, s[36:37]
	s_cbranch_vccnz .LBB0_156
	s_add_u32 s42, s42, 0x80
	s_addc_u32 s43, s43, 0
	s_add_u32 s10, s44, 0x100
	s_addc_u32 s11, s45, 0
	s_mov_b32 s44, 0
	s_cmp_lg_u32 s100, 0
	s_cbranch_scc0 .Llbb_0
	s_barrier
	s_mov_b32 s100, 0
.Llbb_0:
	s_add_i32 s47, s44, 2
	s_add_u32 s4, s42, 0x80
	s_addc_u32 s5, s43, 0
	s_add_i32 s54, 0, 0x10000
	s_cmp_eq_u32 s69, s44
	s_cselect_b32 s45, s13, s5
	s_cselect_b32 s44, s12, s4
	s_cselect_b32 vcc_hi, s1, s11
	s_cselect_b32 vcc_lo, s0, s10
	s_add_i32 s4, 0, 0x14000
	v_add_u32_e32 v140, s54, v223
	v_add_u32_e32 v156, s4, v223
	s_waitcnt lgkmcnt(0)
	ds_read_b128 v[128:131], v140
	ds_read_b128 v[132:135], v140 offset:1024
	ds_read_b128 v[136:139], v140 offset:2048
	ds_read_b128 v[140:143], v140 offset:3072
	ds_read_b128 v[144:147], v156
	ds_read_b128 v[148:151], v156 offset:1024
	ds_read_b128 v[152:155], v156 offset:2048
	ds_read_b128 v[156:159], v156 offset:3072
	v_lshl_add_u64 v[214:215], s[42:43], 0, v[194:195]
	s_add_i32 m0, s59, 0xc000
	ds_read_b128 v[160:163], v228
	ds_read_b128 v[164:167], v228 offset:1024
	ds_read_b128 v[168:171], v228 offset:2048
	ds_read_b128 v[172:175], v228 offset:3072
	ds_read_b128 v[198:201], v228 offset:4096
	ds_read_b128 v[202:205], v228 offset:5120
	ds_read_b128 v[206:209], v228 offset:6144
	ds_read_b128 v[210:213], v228 offset:7168
	global_load_lds_dwordx4 v[214:215], off
	v_lshl_add_u64 v[214:215], s[42:43], 0, v[196:197]
	s_add_i32 m0, s59, 0xe000
	s_nop 0
	global_load_lds_dwordx4 v[214:215], off
	s_waitcnt vmcnt(8)
	s_waitcnt lgkmcnt(0)
	s_barrier
	s_waitcnt lgkmcnt(0)
	v_mfma_f32_16x16x32_bf16 v[120:123], v[128:131], v[160:163], 0
	v_mfma_f32_16x16x32_bf16 v[116:119], v[136:139], v[160:163], 0
	v_mfma_f32_16x16x32_bf16 v[108:111], v[128:131], v[168:171], 0
	v_mfma_f32_16x16x32_bf16 v[100:103], v[136:139], v[168:171], 0
	v_mfma_f32_16x16x32_bf16 v[92:95], v[128:131], v[198:201], 0
	v_mfma_f32_16x16x32_bf16 v[84:87], v[136:139], v[198:201], 0
	v_mfma_f32_16x16x32_bf16 v[76:79], v[128:131], v[206:209], 0
	v_mfma_f32_16x16x32_bf16 v[68:71], v[136:139], v[206:209], 0
	v_mfma_f32_16x16x32_bf16 v[120:123], v[132:135], v[164:167], v[120:123]
	v_mfma_f32_16x16x32_bf16 v[116:119], v[140:143], v[164:167], v[116:119]
	v_mfma_f32_16x16x32_bf16 v[108:111], v[132:135], v[172:175], v[108:111]
	v_mfma_f32_16x16x32_bf16 v[100:103], v[140:143], v[172:175], v[100:103]
	v_mfma_f32_16x16x32_bf16 v[92:95], v[132:135], v[202:205], v[92:95]
	v_mfma_f32_16x16x32_bf16 v[84:87], v[140:143], v[202:205], v[84:87]
	v_mfma_f32_16x16x32_bf16 v[76:79], v[132:135], v[210:213], v[76:79]
	v_mfma_f32_16x16x32_bf16 v[68:71], v[140:143], v[210:213], v[68:71]
	v_mfma_f32_16x16x32_bf16 v[124:127], v[144:147], v[160:163], 0
	v_mfma_f32_16x16x32_bf16 v[112:115], v[152:155], v[160:163], 0
	v_mfma_f32_16x16x32_bf16 v[104:107], v[144:147], v[168:171], 0
	v_mfma_f32_16x16x32_bf16 v[96:99], v[152:155], v[168:171], 0
	v_mfma_f32_16x16x32_bf16 v[88:91], v[144:147], v[198:201], 0
	v_mfma_f32_16x16x32_bf16 v[80:83], v[152:155], v[198:201], 0
	v_mfma_f32_16x16x32_bf16 v[72:75], v[144:147], v[206:209], 0
	v_mfma_f32_16x16x32_bf16 v[64:67], v[152:155], v[206:209], 0
	v_mfma_f32_16x16x32_bf16 v[124:127], v[148:151], v[164:167], v[124:127]
	v_mfma_f32_16x16x32_bf16 v[112:115], v[156:159], v[164:167], v[112:115]
	v_mfma_f32_16x16x32_bf16 v[104:107], v[148:151], v[172:175], v[104:107]
	v_mfma_f32_16x16x32_bf16 v[96:99], v[156:159], v[172:175], v[96:99]
	v_mfma_f32_16x16x32_bf16 v[88:91], v[148:151], v[202:205], v[88:91]
	v_mfma_f32_16x16x32_bf16 v[80:83], v[156:159], v[202:205], v[80:83]
	v_mfma_f32_16x16x32_bf16 v[72:75], v[148:151], v[210:213], v[72:75]
	v_mfma_f32_16x16x32_bf16 v[64:67], v[156:159], v[210:213], v[64:67]
	s_barrier
	s_add_i32 s5, s54, s58
	v_lshl_add_u64 v[214:215], vcc, 0, v[190:191]
	s_mov_b32 m0, s5
	ds_read_b128 v[160:163], v228 offset:16384
	ds_read_b128 v[164:167], v228 offset:17408
	ds_read_b128 v[168:171], v228 offset:18432
	ds_read_b128 v[172:175], v228 offset:19456
	ds_read_b128 v[198:201], v228 offset:20480
	ds_read_b128 v[202:205], v228 offset:21504
	ds_read_b128 v[206:209], v228 offset:22528
	ds_read_b128 v[210:213], v228 offset:23552
	global_load_lds_dwordx4 v[214:215], off
	s_add_i32 m0, s5, 0x2000
	v_lshl_add_u64 v[216:217], vcc, 0, v[186:187]
	s_add_u32 vcc_lo, vcc_lo, s24
	s_addc_u32 vcc_hi, vcc_hi, s25
	s_add_i32 s4, s4, s58
	global_load_lds_dwordx4 v[216:217], off
	v_lshl_add_u64 v[230:231], vcc, 0, v[190:191]
	s_mov_b32 m0, s4
	v_lshl_add_u64 v[232:233], vcc, 0, v[186:187]
	global_load_lds_dwordx4 v[230:231], off
	s_add_i32 m0, s4, 0x2000
	v_lshl_add_u64 v[234:235], s[44:45], 0, v[192:193]
	global_load_lds_dwordx4 v[232:233], off
	s_mov_b32 m0, s59
	v_lshl_add_u64 v[236:237], s[44:45], 0, v[188:189]
	global_load_lds_dwordx4 v[234:235], off
	s_mov_b32 m0, s60
	s_nop 0
	global_load_lds_dwordx4 v[236:237], off
	s_waitcnt vmcnt(8)
	s_waitcnt lgkmcnt(0)
	s_barrier
	s_waitcnt lgkmcnt(0)
	v_mfma_f32_16x16x32_bf16 v[60:63], v[128:131], v[160:163], 0
	v_mfma_f32_16x16x32_bf16 v[52:55], v[136:139], v[160:163], 0
	v_mfma_f32_16x16x32_bf16 v[44:47], v[128:131], v[168:171], 0
	v_mfma_f32_16x16x32_bf16 v[36:39], v[136:139], v[168:171], 0
	v_mfma_f32_16x16x32_bf16 v[28:31], v[128:131], v[198:201], 0
	v_mfma_f32_16x16x32_bf16 v[20:23], v[136:139], v[198:201], 0
	v_mfma_f32_16x16x32_bf16 v[12:15], v[128:131], v[206:209], 0
	v_mfma_f32_16x16x32_bf16 v[4:7], v[136:139], v[206:209], 0
	v_mfma_f32_16x16x32_bf16 v[60:63], v[132:135], v[164:167], v[60:63]
	v_mfma_f32_16x16x32_bf16 v[52:55], v[140:143], v[164:167], v[52:55]
	v_mfma_f32_16x16x32_bf16 v[44:47], v[132:135], v[172:175], v[44:47]
	v_mfma_f32_16x16x32_bf16 v[36:39], v[140:143], v[172:175], v[36:39]
	v_mfma_f32_16x16x32_bf16 v[28:31], v[132:135], v[202:205], v[28:31]
	v_mfma_f32_16x16x32_bf16 v[20:23], v[140:143], v[202:205], v[20:23]
	v_mfma_f32_16x16x32_bf16 v[12:15], v[132:135], v[210:213], v[12:15]
	v_mfma_f32_16x16x32_bf16 v[4:7], v[140:143], v[210:213], v[4:7]
	v_mfma_f32_16x16x32_bf16 v[56:59], v[144:147], v[160:163], 0
	v_mfma_f32_16x16x32_bf16 v[48:51], v[152:155], v[160:163], 0
	v_mfma_f32_16x16x32_bf16 v[40:43], v[144:147], v[168:171], 0
	v_mfma_f32_16x16x32_bf16 v[32:35], v[152:155], v[168:171], 0
	v_mfma_f32_16x16x32_bf16 v[24:27], v[144:147], v[198:201], 0
	v_mfma_f32_16x16x32_bf16 v[16:19], v[152:155], v[198:201], 0
	v_mfma_f32_16x16x32_bf16 v[8:11], v[144:147], v[206:209], 0
	v_mfma_f32_16x16x32_bf16 v[0:3], v[152:155], v[206:209], 0
	v_mfma_f32_16x16x32_bf16 v[56:59], v[148:151], v[164:167], v[56:59]
	v_mfma_f32_16x16x32_bf16 v[48:51], v[156:159], v[164:167], v[48:51]
	v_mfma_f32_16x16x32_bf16 v[40:43], v[148:151], v[172:175], v[40:43]
	v_mfma_f32_16x16x32_bf16 v[32:35], v[156:159], v[172:175], v[32:35]
	v_mfma_f32_16x16x32_bf16 v[24:27], v[148:151], v[202:205], v[24:27]
	v_mfma_f32_16x16x32_bf16 v[16:19], v[156:159], v[202:205], v[16:19]
	v_mfma_f32_16x16x32_bf16 v[8:11], v[148:151], v[210:213], v[8:11]
	v_mfma_f32_16x16x32_bf16 v[0:3], v[156:159], v[210:213], v[0:3]
	s_barrier
	s_add_i32 s4, 0, 0x18000
	s_add_i32 s5, 0, 0x1c000
	v_add_u32_e32 v140, s4, v223
	v_add_u32_e32 v156, s5, v223
	ds_read_b128 v[128:131], v140
	ds_read_b128 v[132:135], v140 offset:1024
	ds_read_b128 v[136:139], v140 offset:2048
	ds_read_b128 v[140:143], v140 offset:3072
	ds_read_b128 v[144:147], v156
	ds_read_b128 v[148:151], v156 offset:1024
	ds_read_b128 v[152:155], v156 offset:2048
	ds_read_b128 v[156:159], v156 offset:3072
	s_add_u32 s44, s44, s24
	s_addc_u32 s45, s45, s25
	s_mov_b32 m0, s61
	v_lshl_add_u64 v[238:239], s[44:45], 0, v[192:193]
	ds_read_b128 v[160:163], v228 offset:32768
	ds_read_b128 v[164:167], v228 offset:33792
	ds_read_b128 v[168:171], v228 offset:34816
	ds_read_b128 v[172:175], v228 offset:35840
	ds_read_b128 v[198:201], v228 offset:36864
	ds_read_b128 v[202:205], v228 offset:37888
	ds_read_b128 v[206:209], v228 offset:38912
	ds_read_b128 v[210:213], v228 offset:39936
	global_load_lds_dwordx4 v[238:239], off
	v_lshl_add_u64 v[238:239], s[44:45], 0, v[188:189]
	s_mov_b32 m0, s62
	s_nop 0
	global_load_lds_dwordx4 v[238:239], off
	s_waitcnt vmcnt(8)
	s_waitcnt lgkmcnt(0)
	s_barrier
	s_waitcnt lgkmcnt(0)
	v_mfma_f32_16x16x32_bf16 v[120:123], v[128:131], v[160:163], v[120:123]
	v_mfma_f32_16x16x32_bf16 v[116:119], v[136:139], v[160:163], v[116:119]
	v_mfma_f32_16x16x32_bf16 v[108:111], v[128:131], v[168:171], v[108:111]
	v_mfma_f32_16x16x32_bf16 v[100:103], v[136:139], v[168:171], v[100:103]
	v_mfma_f32_16x16x32_bf16 v[92:95], v[128:131], v[198:201], v[92:95]
	v_mfma_f32_16x16x32_bf16 v[84:87], v[136:139], v[198:201], v[84:87]
	v_mfma_f32_16x16x32_bf16 v[76:79], v[128:131], v[206:209], v[76:79]
	v_mfma_f32_16x16x32_bf16 v[68:71], v[136:139], v[206:209], v[68:71]
	v_mfma_f32_16x16x32_bf16 v[120:123], v[132:135], v[164:167], v[120:123]
	v_mfma_f32_16x16x32_bf16 v[116:119], v[140:143], v[164:167], v[116:119]
	v_mfma_f32_16x16x32_bf16 v[108:111], v[132:135], v[172:175], v[108:111]
	v_mfma_f32_16x16x32_bf16 v[100:103], v[140:143], v[172:175], v[100:103]
	v_mfma_f32_16x16x32_bf16 v[92:95], v[132:135], v[202:205], v[92:95]
	v_mfma_f32_16x16x32_bf16 v[84:87], v[140:143], v[202:205], v[84:87]
	v_mfma_f32_16x16x32_bf16 v[76:79], v[132:135], v[210:213], v[76:79]
	v_mfma_f32_16x16x32_bf16 v[68:71], v[140:143], v[210:213], v[68:71]
	v_mfma_f32_16x16x32_bf16 v[124:127], v[144:147], v[160:163], v[124:127]
	v_mfma_f32_16x16x32_bf16 v[112:115], v[152:155], v[160:163], v[112:115]
	v_mfma_f32_16x16x32_bf16 v[104:107], v[144:147], v[168:171], v[104:107]
	v_mfma_f32_16x16x32_bf16 v[96:99], v[152:155], v[168:171], v[96:99]
	v_mfma_f32_16x16x32_bf16 v[88:91], v[144:147], v[198:201], v[88:91]
	v_mfma_f32_16x16x32_bf16 v[80:83], v[152:155], v[198:201], v[80:83]
	v_mfma_f32_16x16x32_bf16 v[72:75], v[144:147], v[206:209], v[72:75]
	v_mfma_f32_16x16x32_bf16 v[64:67], v[152:155], v[206:209], v[64:67]
	v_mfma_f32_16x16x32_bf16 v[124:127], v[148:151], v[164:167], v[124:127]
	v_mfma_f32_16x16x32_bf16 v[112:115], v[156:159], v[164:167], v[112:115]
	v_mfma_f32_16x16x32_bf16 v[104:107], v[148:151], v[172:175], v[104:107]
	v_mfma_f32_16x16x32_bf16 v[96:99], v[156:159], v[172:175], v[96:99]
	v_mfma_f32_16x16x32_bf16 v[88:91], v[148:151], v[202:205], v[88:91]
	v_mfma_f32_16x16x32_bf16 v[80:83], v[156:159], v[202:205], v[80:83]
	v_mfma_f32_16x16x32_bf16 v[72:75], v[148:151], v[210:213], v[72:75]
	v_mfma_f32_16x16x32_bf16 v[64:67], v[156:159], v[210:213], v[64:67]
	s_barrier
	s_add_i32 s4, s4, s58
	v_lshl_add_u64 v[214:215], v[214:215], 0, s[14:15]
	s_mov_b32 m0, s4
	ds_read_b128 v[160:163], v228 offset:49152
	ds_read_b128 v[164:167], v228 offset:50176
	ds_read_b128 v[168:171], v228 offset:51200
	ds_read_b128 v[172:175], v228 offset:52224
	ds_read_b128 v[198:201], v228 offset:53248
	ds_read_b128 v[202:205], v228 offset:54272
	ds_read_b128 v[206:209], v228 offset:55296
	ds_read_b128 v[210:213], v228 offset:56320
	global_load_lds_dwordx4 v[214:215], off
	v_lshl_add_u64 v[214:215], v[216:217], 0, s[14:15]
	s_add_i32 m0, s4, 0x2000
	s_add_i32 s4, s5, s58
	global_load_lds_dwordx4 v[214:215], off
	v_lshl_add_u64 v[214:215], v[230:231], 0, s[14:15]
	s_mov_b32 m0, s4
	s_nop 0
	global_load_lds_dwordx4 v[214:215], off
	v_lshl_add_u64 v[214:215], v[232:233], 0, s[14:15]
	s_add_i32 m0, s4, 0x2000
	s_nop 0
	global_load_lds_dwordx4 v[214:215], off
	v_lshl_add_u64 v[214:215], v[234:235], 0, s[14:15]
	s_mov_b32 m0, s63
	s_nop 0
	global_load_lds_dwordx4 v[214:215], off
	v_lshl_add_u64 v[214:215], v[236:237], 0, s[14:15]
	s_mov_b32 m0, s66
	s_nop 0
	global_load_lds_dwordx4 v[214:215], off
	s_waitcnt vmcnt(8)
	s_waitcnt lgkmcnt(0)
	s_barrier
	s_waitcnt lgkmcnt(0)
	v_mfma_f32_16x16x32_bf16 v[60:63], v[128:131], v[160:163], v[60:63]
	v_mfma_f32_16x16x32_bf16 v[52:55], v[136:139], v[160:163], v[52:55]
	v_mfma_f32_16x16x32_bf16 v[44:47], v[128:131], v[168:171], v[44:47]
	v_mfma_f32_16x16x32_bf16 v[36:39], v[136:139], v[168:171], v[36:39]
	v_mfma_f32_16x16x32_bf16 v[28:31], v[128:131], v[198:201], v[28:31]
	v_mfma_f32_16x16x32_bf16 v[20:23], v[136:139], v[198:201], v[20:23]
	v_mfma_f32_16x16x32_bf16 v[12:15], v[128:131], v[206:209], v[12:15]
	v_mfma_f32_16x16x32_bf16 v[4:7], v[136:139], v[206:209], v[4:7]
	v_mfma_f32_16x16x32_bf16 v[60:63], v[132:135], v[164:167], v[60:63]
	v_mfma_f32_16x16x32_bf16 v[52:55], v[140:143], v[164:167], v[52:55]
	v_mfma_f32_16x16x32_bf16 v[44:47], v[132:135], v[172:175], v[44:47]
	v_mfma_f32_16x16x32_bf16 v[36:39], v[140:143], v[172:175], v[36:39]
	v_mfma_f32_16x16x32_bf16 v[28:31], v[132:135], v[202:205], v[28:31]
	v_mfma_f32_16x16x32_bf16 v[20:23], v[140:143], v[202:205], v[20:23]
	v_mfma_f32_16x16x32_bf16 v[12:15], v[132:135], v[210:213], v[12:15]
	v_mfma_f32_16x16x32_bf16 v[4:7], v[140:143], v[210:213], v[4:7]
	v_mfma_f32_16x16x32_bf16 v[56:59], v[144:147], v[160:163], v[56:59]
	v_mfma_f32_16x16x32_bf16 v[48:51], v[152:155], v[160:163], v[48:51]
	v_mfma_f32_16x16x32_bf16 v[40:43], v[144:147], v[168:171], v[40:43]
	v_mfma_f32_16x16x32_bf16 v[32:35], v[152:155], v[168:171], v[32:35]
	v_mfma_f32_16x16x32_bf16 v[24:27], v[144:147], v[198:201], v[24:27]
	v_mfma_f32_16x16x32_bf16 v[16:19], v[152:155], v[198:201], v[16:19]
	v_mfma_f32_16x16x32_bf16 v[8:11], v[144:147], v[206:209], v[8:11]
	v_mfma_f32_16x16x32_bf16 v[0:3], v[152:155], v[206:209], v[0:3]
	v_mfma_f32_16x16x32_bf16 v[56:59], v[148:151], v[164:167], v[56:59]
	v_mfma_f32_16x16x32_bf16 v[48:51], v[156:159], v[164:167], v[48:51]
	v_mfma_f32_16x16x32_bf16 v[40:43], v[148:151], v[172:175], v[40:43]
	v_mfma_f32_16x16x32_bf16 v[32:35], v[156:159], v[172:175], v[32:35]
	v_mfma_f32_16x16x32_bf16 v[24:27], v[148:151], v[202:205], v[24:27]
	v_mfma_f32_16x16x32_bf16 v[16:19], v[156:159], v[202:205], v[16:19]
	v_mfma_f32_16x16x32_bf16 v[8:11], v[148:151], v[210:213], v[8:11]
	v_mfma_f32_16x16x32_bf16 v[0:3], v[156:159], v[210:213], v[0:3]
	s_barrier
	s_add_u32 s42, s42, 0x100
	s_addc_u32 s43, s43, 0
	s_add_u32 s10, s10, 0x100
	s_addc_u32 s11, s11, 0
	s_cmp_ge_i32 s47, s67
	s_mov_b32 s44, s47
	s_cbranch_scc1 .Lpeelx_4

.Lpeelx_4:
.LBB0_156:
	s_and_b64 vcc, exec, s[94:95]
	s_cbranch_vccnz .LBB0_161
	s_lshl_b32 s42, s46, 8
	s_add_i32 s42, s42, s68
	s_cmp_eq_u32 s46, s96
	s_cbranch_scc0 .LBB0_162

.LBB0_260:
	s_andn2_b64 vcc, exec, s[22:23]
	s_waitcnt lgkmcnt(0)
	s_cbranch_vccnz .LBB0_263
	s_add_u32 s30, s30, 0x80
	s_addc_u32 s31, s31, 0
	s_add_u32 s10, s34, 0x100
	s_addc_u32 s11, s35, 0
	s_mov_b32 s34, 0
	s_cmp_lg_u32 s100, 0
	s_cbranch_scc0 .Llbb_1
	s_barrier
	s_mov_b32 s100, 0
.Llbb_1:
	s_add_i32 s44, s34, 2
	s_add_u32 s4, s30, 0x80
	s_addc_u32 s5, s31, 0
	s_add_i32 s45, 0, 0x10000
	s_cmp_eq_u32 s62, s34
	s_cselect_b32 s35, s27, s5
	s_cselect_b32 s34, s26, s4
	s_cselect_b32 s5, s29, s11
	s_cselect_b32 s4, s28, s10
	s_add_i32 s54, 0, 0x14000
	v_add_u32_e32 v140, s45, v195
	v_add_u32_e32 v166, s54, v195
	ds_read_b128 v[128:131], v140
	ds_read_b128 v[132:135], v140 offset:1024
	ds_read_b128 v[136:139], v140 offset:2048
	ds_read_b128 v[140:143], v140 offset:3072
	ds_read_b128 v[144:147], v166
	ds_read_b128 v[148:151], v166 offset:1024
	ds_read_b128 v[152:155], v166 offset:2048
	ds_read_b128 v[166:169], v166 offset:3072
	v_lshl_add_u64 v[174:175], s[30:31], 0, v[162:163]
	s_add_i32 m0, s38, 0xc000
	ds_read_b128 v[170:173], v197
	ds_read_b128 v[186:189], v197 offset:1024
	ds_read_b128 v[190:193], v197 offset:2048
	ds_read_b128 v[198:201], v197 offset:3072
	ds_read_b128 v[202:205], v197 offset:4096
	ds_read_b128 v[206:209], v197 offset:5120
	ds_read_b128 v[210:213], v197 offset:6144
	ds_read_b128 v[214:217], v197 offset:7168
	global_load_lds_dwordx4 v[174:175], off
	v_lshl_add_u64 v[174:175], s[30:31], 0, v[164:165]
	s_add_i32 m0, s38, 0xe000
	s_nop 0
	global_load_lds_dwordx4 v[174:175], off
	s_waitcnt vmcnt(8)
	s_waitcnt lgkmcnt(0)
	s_barrier
	s_waitcnt lgkmcnt(0)
	v_mfma_f32_16x16x32_bf16 v[120:123], v[128:131], v[170:173], 0
	v_mfma_f32_16x16x32_bf16 v[124:127], v[136:139], v[170:173], 0
	v_mfma_f32_16x16x32_bf16 v[108:111], v[128:131], v[190:193], 0
	v_mfma_f32_16x16x32_bf16 v[104:107], v[136:139], v[190:193], 0
	v_mfma_f32_16x16x32_bf16 v[92:95], v[128:131], v[202:205], 0
	v_mfma_f32_16x16x32_bf16 v[88:91], v[136:139], v[202:205], 0
	v_mfma_f32_16x16x32_bf16 v[76:79], v[128:131], v[210:213], 0
	v_mfma_f32_16x16x32_bf16 v[72:75], v[136:139], v[210:213], 0
	v_mfma_f32_16x16x32_bf16 v[120:123], v[132:135], v[186:189], v[120:123]
	v_mfma_f32_16x16x32_bf16 v[124:127], v[140:143], v[186:189], v[124:127]
	v_mfma_f32_16x16x32_bf16 v[108:111], v[132:135], v[198:201], v[108:111]
	v_mfma_f32_16x16x32_bf16 v[104:107], v[140:143], v[198:201], v[104:107]
	v_mfma_f32_16x16x32_bf16 v[92:95], v[132:135], v[206:209], v[92:95]
	v_mfma_f32_16x16x32_bf16 v[88:91], v[140:143], v[206:209], v[88:91]
	v_mfma_f32_16x16x32_bf16 v[76:79], v[132:135], v[214:217], v[76:79]
	v_mfma_f32_16x16x32_bf16 v[72:75], v[140:143], v[214:217], v[72:75]
	v_mfma_f32_16x16x32_bf16 v[116:119], v[144:147], v[170:173], 0
	v_mfma_f32_16x16x32_bf16 v[112:115], v[152:155], v[170:173], 0
	v_mfma_f32_16x16x32_bf16 v[100:103], v[144:147], v[190:193], 0
	v_mfma_f32_16x16x32_bf16 v[96:99], v[152:155], v[190:193], 0
	v_mfma_f32_16x16x32_bf16 v[84:87], v[144:147], v[202:205], 0
	v_mfma_f32_16x16x32_bf16 v[80:83], v[152:155], v[202:205], 0
	v_mfma_f32_16x16x32_bf16 v[68:71], v[144:147], v[210:213], 0
	v_mfma_f32_16x16x32_bf16 v[64:67], v[152:155], v[210:213], 0
	v_mfma_f32_16x16x32_bf16 v[116:119], v[148:151], v[186:189], v[116:119]
	v_mfma_f32_16x16x32_bf16 v[112:115], v[166:169], v[186:189], v[112:115]
	v_mfma_f32_16x16x32_bf16 v[100:103], v[148:151], v[198:201], v[100:103]
	v_mfma_f32_16x16x32_bf16 v[96:99], v[166:169], v[198:201], v[96:99]
	v_mfma_f32_16x16x32_bf16 v[84:87], v[148:151], v[206:209], v[84:87]
	v_mfma_f32_16x16x32_bf16 v[80:83], v[166:169], v[206:209], v[80:83]
	v_mfma_f32_16x16x32_bf16 v[68:71], v[148:151], v[214:217], v[68:71]
	v_mfma_f32_16x16x32_bf16 v[64:67], v[166:169], v[214:217], v[64:67]
	s_barrier
	s_add_i32 s45, s45, s37
	v_lshl_add_u64 v[174:175], s[4:5], 0, v[176:177]
	s_mov_b32 m0, s45
	ds_read_b128 v[170:173], v197 offset:16384
	ds_read_b128 v[186:189], v197 offset:17408
	ds_read_b128 v[190:193], v197 offset:18432
	ds_read_b128 v[198:201], v197 offset:19456
	ds_read_b128 v[202:205], v197 offset:20480
	ds_read_b128 v[206:209], v197 offset:21504
	ds_read_b128 v[210:213], v197 offset:22528
	ds_read_b128 v[214:217], v197 offset:23552
	global_load_lds_dwordx4 v[174:175], off
	s_add_i32 m0, s45, 0x2000
	v_lshl_add_u64 v[222:223], s[4:5], 0, v[156:157]
	s_add_u32 s4, s4, s0
	s_addc_u32 s5, s5, s1
	s_add_i32 s45, s54, s37
	global_load_lds_dwordx4 v[222:223], off
	v_lshl_add_u64 v[224:225], s[4:5], 0, v[176:177]
	s_mov_b32 m0, s45
	v_lshl_add_u64 v[226:227], s[4:5], 0, v[156:157]
	global_load_lds_dwordx4 v[224:225], off
	s_add_i32 m0, s45, 0x2000
	v_lshl_add_u64 v[228:229], s[34:35], 0, v[160:161]
	global_load_lds_dwordx4 v[226:227], off
	s_mov_b32 m0, s38
	v_lshl_add_u64 v[230:231], s[34:35], 0, v[158:159]
	global_load_lds_dwordx4 v[228:229], off
	s_mov_b32 m0, s39
	s_nop 0
	global_load_lds_dwordx4 v[230:231], off
	s_waitcnt vmcnt(8)
	s_waitcnt lgkmcnt(0)
	s_barrier
	s_waitcnt lgkmcnt(0)
	v_mfma_f32_16x16x32_bf16 v[60:63], v[128:131], v[170:173], 0
	v_mfma_f32_16x16x32_bf16 v[56:59], v[136:139], v[170:173], 0
	v_mfma_f32_16x16x32_bf16 v[44:47], v[128:131], v[190:193], 0
	v_mfma_f32_16x16x32_bf16 v[40:43], v[136:139], v[190:193], 0
	v_mfma_f32_16x16x32_bf16 v[28:31], v[128:131], v[202:205], 0
	v_mfma_f32_16x16x32_bf16 v[24:27], v[136:139], v[202:205], 0
	v_mfma_f32_16x16x32_bf16 v[12:15], v[128:131], v[210:213], 0
	v_mfma_f32_16x16x32_bf16 v[8:11], v[136:139], v[210:213], 0
	v_mfma_f32_16x16x32_bf16 v[60:63], v[132:135], v[186:189], v[60:63]
	v_mfma_f32_16x16x32_bf16 v[56:59], v[140:143], v[186:189], v[56:59]
	v_mfma_f32_16x16x32_bf16 v[44:47], v[132:135], v[198:201], v[44:47]
	v_mfma_f32_16x16x32_bf16 v[40:43], v[140:143], v[198:201], v[40:43]
	v_mfma_f32_16x16x32_bf16 v[28:31], v[132:135], v[206:209], v[28:31]
	v_mfma_f32_16x16x32_bf16 v[24:27], v[140:143], v[206:209], v[24:27]
	v_mfma_f32_16x16x32_bf16 v[12:15], v[132:135], v[214:217], v[12:15]
	v_mfma_f32_16x16x32_bf16 v[8:11], v[140:143], v[214:217], v[8:11]
	v_mfma_f32_16x16x32_bf16 v[52:55], v[144:147], v[170:173], 0
	v_mfma_f32_16x16x32_bf16 v[48:51], v[152:155], v[170:173], 0
	v_mfma_f32_16x16x32_bf16 v[36:39], v[144:147], v[190:193], 0
	v_mfma_f32_16x16x32_bf16 v[32:35], v[152:155], v[190:193], 0
	v_mfma_f32_16x16x32_bf16 v[20:23], v[144:147], v[202:205], 0
	v_mfma_f32_16x16x32_bf16 v[16:19], v[152:155], v[202:205], 0
	v_mfma_f32_16x16x32_bf16 v[4:7], v[144:147], v[210:213], 0
	v_mfma_f32_16x16x32_bf16 v[0:3], v[152:155], v[210:213], 0
	v_mfma_f32_16x16x32_bf16 v[52:55], v[148:151], v[186:189], v[52:55]
	v_mfma_f32_16x16x32_bf16 v[48:51], v[166:169], v[186:189], v[48:51]
	v_mfma_f32_16x16x32_bf16 v[36:39], v[148:151], v[198:201], v[36:39]
	v_mfma_f32_16x16x32_bf16 v[32:35], v[166:169], v[198:201], v[32:35]
	v_mfma_f32_16x16x32_bf16 v[20:23], v[148:151], v[206:209], v[20:23]
	v_mfma_f32_16x16x32_bf16 v[16:19], v[166:169], v[206:209], v[16:19]
	v_mfma_f32_16x16x32_bf16 v[4:7], v[148:151], v[214:217], v[4:7]
	v_mfma_f32_16x16x32_bf16 v[0:3], v[166:169], v[214:217], v[0:3]
	s_barrier
	s_add_i32 s45, 0, 0x18000
	s_add_i32 s54, 0, 0x1c000
	v_add_u32_e32 v140, s45, v195
	v_add_u32_e32 v166, s54, v195
	ds_read_b128 v[128:131], v140
	ds_read_b128 v[132:135], v140 offset:1024
	ds_read_b128 v[136:139], v140 offset:2048
	ds_read_b128 v[140:143], v140 offset:3072
	ds_read_b128 v[144:147], v166
	ds_read_b128 v[148:151], v166 offset:1024
	ds_read_b128 v[152:155], v166 offset:2048
	ds_read_b128 v[166:169], v166 offset:3072
	s_add_u32 s4, s34, s0
	s_addc_u32 s5, s35, s1
	s_mov_b32 m0, s48
	v_lshl_add_u64 v[232:233], s[4:5], 0, v[160:161]
	ds_read_b128 v[170:173], v197 offset:32768
	ds_read_b128 v[186:189], v197 offset:33792
	ds_read_b128 v[190:193], v197 offset:34816
	ds_read_b128 v[198:201], v197 offset:35840
	ds_read_b128 v[202:205], v197 offset:36864
	ds_read_b128 v[206:209], v197 offset:37888
	ds_read_b128 v[210:213], v197 offset:38912
	ds_read_b128 v[214:217], v197 offset:39936
	global_load_lds_dwordx4 v[232:233], off
	v_lshl_add_u64 v[232:233], s[4:5], 0, v[158:159]
	s_mov_b32 m0, s49
	s_nop 0
	global_load_lds_dwordx4 v[232:233], off
	s_waitcnt vmcnt(8)
	s_waitcnt lgkmcnt(0)
	s_barrier
	s_waitcnt lgkmcnt(0)
	v_mfma_f32_16x16x32_bf16 v[120:123], v[128:131], v[170:173], v[120:123]
	v_mfma_f32_16x16x32_bf16 v[124:127], v[136:139], v[170:173], v[124:127]
	v_mfma_f32_16x16x32_bf16 v[108:111], v[128:131], v[190:193], v[108:111]
	v_mfma_f32_16x16x32_bf16 v[104:107], v[136:139], v[190:193], v[104:107]
	v_mfma_f32_16x16x32_bf16 v[92:95], v[128:131], v[202:205], v[92:95]
	v_mfma_f32_16x16x32_bf16 v[88:91], v[136:139], v[202:205], v[88:91]
	v_mfma_f32_16x16x32_bf16 v[76:79], v[128:131], v[210:213], v[76:79]
	v_mfma_f32_16x16x32_bf16 v[72:75], v[136:139], v[210:213], v[72:75]
	v_mfma_f32_16x16x32_bf16 v[120:123], v[132:135], v[186:189], v[120:123]
	v_mfma_f32_16x16x32_bf16 v[124:127], v[140:143], v[186:189], v[124:127]
	v_mfma_f32_16x16x32_bf16 v[108:111], v[132:135], v[198:201], v[108:111]
	v_mfma_f32_16x16x32_bf16 v[104:107], v[140:143], v[198:201], v[104:107]
	v_mfma_f32_16x16x32_bf16 v[92:95], v[132:135], v[206:209], v[92:95]
	v_mfma_f32_16x16x32_bf16 v[88:91], v[140:143], v[206:209], v[88:91]
	v_mfma_f32_16x16x32_bf16 v[76:79], v[132:135], v[214:217], v[76:79]
	v_mfma_f32_16x16x32_bf16 v[72:75], v[140:143], v[214:217], v[72:75]
	v_mfma_f32_16x16x32_bf16 v[116:119], v[144:147], v[170:173], v[116:119]
	v_mfma_f32_16x16x32_bf16 v[112:115], v[152:155], v[170:173], v[112:115]
	v_mfma_f32_16x16x32_bf16 v[100:103], v[144:147], v[190:193], v[100:103]
	v_mfma_f32_16x16x32_bf16 v[96:99], v[152:155], v[190:193], v[96:99]
	v_mfma_f32_16x16x32_bf16 v[84:87], v[144:147], v[202:205], v[84:87]
	v_mfma_f32_16x16x32_bf16 v[80:83], v[152:155], v[202:205], v[80:83]
	v_mfma_f32_16x16x32_bf16 v[68:71], v[144:147], v[210:213], v[68:71]
	v_mfma_f32_16x16x32_bf16 v[64:67], v[152:155], v[210:213], v[64:67]
	v_mfma_f32_16x16x32_bf16 v[116:119], v[148:151], v[186:189], v[116:119]
	v_mfma_f32_16x16x32_bf16 v[112:115], v[166:169], v[186:189], v[112:115]
	v_mfma_f32_16x16x32_bf16 v[100:103], v[148:151], v[198:201], v[100:103]
	v_mfma_f32_16x16x32_bf16 v[96:99], v[166:169], v[198:201], v[96:99]
	v_mfma_f32_16x16x32_bf16 v[84:87], v[148:151], v[206:209], v[84:87]
	v_mfma_f32_16x16x32_bf16 v[80:83], v[166:169], v[206:209], v[80:83]
	v_mfma_f32_16x16x32_bf16 v[68:71], v[148:151], v[214:217], v[68:71]
	v_mfma_f32_16x16x32_bf16 v[64:67], v[166:169], v[214:217], v[64:67]
	s_barrier
	s_add_i32 s4, s45, s37
	v_lshl_add_u64 v[174:175], v[174:175], 0, s[14:15]
	s_mov_b32 m0, s4
	ds_read_b128 v[170:173], v197 offset:49152
	ds_read_b128 v[186:189], v197 offset:50176
	ds_read_b128 v[190:193], v197 offset:51200
	ds_read_b128 v[198:201], v197 offset:52224
	ds_read_b128 v[202:205], v197 offset:53248
	ds_read_b128 v[206:209], v197 offset:54272
	ds_read_b128 v[210:213], v197 offset:55296
	ds_read_b128 v[214:217], v197 offset:56320
	global_load_lds_dwordx4 v[174:175], off
	v_lshl_add_u64 v[174:175], v[222:223], 0, s[14:15]
	s_add_i32 m0, s4, 0x2000
	s_add_i32 s4, s54, s37
	global_load_lds_dwordx4 v[174:175], off
	v_lshl_add_u64 v[174:175], v[224:225], 0, s[14:15]
	s_mov_b32 m0, s4
	s_nop 0
	global_load_lds_dwordx4 v[174:175], off
	v_lshl_add_u64 v[174:175], v[226:227], 0, s[14:15]
	s_add_i32 m0, s4, 0x2000
	s_nop 0
	global_load_lds_dwordx4 v[174:175], off
	v_lshl_add_u64 v[174:175], v[228:229], 0, s[14:15]
	s_mov_b32 m0, s60
	s_nop 0
	global_load_lds_dwordx4 v[174:175], off
	v_lshl_add_u64 v[174:175], v[230:231], 0, s[14:15]
	s_mov_b32 m0, s61
	s_nop 0
	global_load_lds_dwordx4 v[174:175], off
	s_waitcnt vmcnt(8)
	s_waitcnt lgkmcnt(0)
	s_barrier
	s_waitcnt lgkmcnt(0)
	v_mfma_f32_16x16x32_bf16 v[60:63], v[128:131], v[170:173], v[60:63]
	v_mfma_f32_16x16x32_bf16 v[56:59], v[136:139], v[170:173], v[56:59]
	v_mfma_f32_16x16x32_bf16 v[44:47], v[128:131], v[190:193], v[44:47]
	v_mfma_f32_16x16x32_bf16 v[40:43], v[136:139], v[190:193], v[40:43]
	v_mfma_f32_16x16x32_bf16 v[28:31], v[128:131], v[202:205], v[28:31]
	v_mfma_f32_16x16x32_bf16 v[24:27], v[136:139], v[202:205], v[24:27]
	v_mfma_f32_16x16x32_bf16 v[12:15], v[128:131], v[210:213], v[12:15]
	v_mfma_f32_16x16x32_bf16 v[8:11], v[136:139], v[210:213], v[8:11]
	v_mfma_f32_16x16x32_bf16 v[60:63], v[132:135], v[186:189], v[60:63]
	v_mfma_f32_16x16x32_bf16 v[56:59], v[140:143], v[186:189], v[56:59]
	v_mfma_f32_16x16x32_bf16 v[44:47], v[132:135], v[198:201], v[44:47]
	v_mfma_f32_16x16x32_bf16 v[40:43], v[140:143], v[198:201], v[40:43]
	v_mfma_f32_16x16x32_bf16 v[28:31], v[132:135], v[206:209], v[28:31]
	v_mfma_f32_16x16x32_bf16 v[24:27], v[140:143], v[206:209], v[24:27]
	v_mfma_f32_16x16x32_bf16 v[12:15], v[132:135], v[214:217], v[12:15]
	v_mfma_f32_16x16x32_bf16 v[8:11], v[140:143], v[214:217], v[8:11]
	v_mfma_f32_16x16x32_bf16 v[52:55], v[144:147], v[170:173], v[52:55]
	v_mfma_f32_16x16x32_bf16 v[48:51], v[152:155], v[170:173], v[48:51]
	v_mfma_f32_16x16x32_bf16 v[36:39], v[144:147], v[190:193], v[36:39]
	v_mfma_f32_16x16x32_bf16 v[32:35], v[152:155], v[190:193], v[32:35]
	v_mfma_f32_16x16x32_bf16 v[20:23], v[144:147], v[202:205], v[20:23]
	v_mfma_f32_16x16x32_bf16 v[16:19], v[152:155], v[202:205], v[16:19]
	v_mfma_f32_16x16x32_bf16 v[4:7], v[144:147], v[210:213], v[4:7]
	v_mfma_f32_16x16x32_bf16 v[0:3], v[152:155], v[210:213], v[0:3]
	v_mfma_f32_16x16x32_bf16 v[52:55], v[148:151], v[186:189], v[52:55]
	v_mfma_f32_16x16x32_bf16 v[48:51], v[166:169], v[186:189], v[48:51]
	v_mfma_f32_16x16x32_bf16 v[36:39], v[148:151], v[198:201], v[36:39]
	v_mfma_f32_16x16x32_bf16 v[32:35], v[166:169], v[198:201], v[32:35]
	v_mfma_f32_16x16x32_bf16 v[20:23], v[148:151], v[206:209], v[20:23]
	v_mfma_f32_16x16x32_bf16 v[16:19], v[166:169], v[206:209], v[16:19]
	v_mfma_f32_16x16x32_bf16 v[4:7], v[148:151], v[214:217], v[4:7]
	v_mfma_f32_16x16x32_bf16 v[0:3], v[166:169], v[214:217], v[0:3]
	s_barrier
	s_add_u32 s30, s30, 0x100
	s_addc_u32 s31, s31, 0
	s_add_u32 s10, s10, 0x100
	s_addc_u32 s11, s11, 0
	s_cmp_ge_i32 s44, s59
	s_mov_b32 s34, s44
	s_cbranch_scc1 .Lpeelx_5

.Lpeelx_5:
.LBB0_263:
	s_and_b64 vcc, exec, s[24:25]
	s_cbranch_vccz .LBB0_265
	s_barrier

.Llbb_2:
	s_add_i32 s44, s34, 2
	s_add_u32 s4, s30, 0x80
	s_addc_u32 s5, s31, 0
	s_add_i32 s45, 0, 0x10000
	s_cmp_eq_u32 s62, s34
	s_cselect_b32 s35, s27, s5
	s_cselect_b32 s34, s26, s4
	s_cselect_b32 s5, s29, s11
	s_cselect_b32 s4, s28, s10
	s_add_i32 s54, 0, 0x14000
	v_add_u32_e32 v140, s45, v163
	v_add_u32_e32 v170, s54, v163
	ds_read_b128 v[128:131], v140
	ds_read_b128 v[132:135], v140 offset:1024
	ds_read_b128 v[136:139], v140 offset:2048
	ds_read_b128 v[140:143], v140 offset:3072
	ds_read_b128 v[154:157], v170
	ds_read_b128 v[158:161], v170 offset:1024
	ds_read_b128 v[166:169], v170 offset:2048
	ds_read_b128 v[170:173], v170 offset:3072
	v_lshl_add_u64 v[174:175], s[30:31], 0, v[150:151]
	s_add_i32 m0, s38, 0xc000
	ds_read_b128 v[186:189], v165
	ds_read_b128 v[190:193], v165 offset:1024
	ds_read_b128 v[194:197], v165 offset:2048
	ds_read_b128 v[198:201], v165 offset:3072
	ds_read_b128 v[202:205], v165 offset:4096
	ds_read_b128 v[206:209], v165 offset:5120
	ds_read_b128 v[210:213], v165 offset:6144
	ds_read_b128 v[214:217], v165 offset:7168
	global_load_lds_dwordx4 v[174:175], off
	v_lshl_add_u64 v[174:175], s[30:31], 0, v[152:153]
	s_add_i32 m0, s38, 0xe000
	s_nop 0
	global_load_lds_dwordx4 v[174:175], off
	s_waitcnt vmcnt(8)
	s_waitcnt lgkmcnt(0)
	s_barrier
	s_waitcnt lgkmcnt(0)
	v_mfma_f32_16x16x32_bf16 v[124:127], v[128:131], v[186:189], 0
	v_mfma_f32_16x16x32_bf16 v[120:123], v[136:139], v[186:189], 0
	v_mfma_f32_16x16x32_bf16 v[108:111], v[128:131], v[194:197], 0
	v_mfma_f32_16x16x32_bf16 v[104:107], v[136:139], v[194:197], 0
	v_mfma_f32_16x16x32_bf16 v[92:95], v[128:131], v[202:205], 0
	v_mfma_f32_16x16x32_bf16 v[88:91], v[136:139], v[202:205], 0
	v_mfma_f32_16x16x32_bf16 v[76:79], v[128:131], v[210:213], 0
	v_mfma_f32_16x16x32_bf16 v[72:75], v[136:139], v[210:213], 0
	v_mfma_f32_16x16x32_bf16 v[124:127], v[132:135], v[190:193], v[124:127]
	v_mfma_f32_16x16x32_bf16 v[120:123], v[140:143], v[190:193], v[120:123]
	v_mfma_f32_16x16x32_bf16 v[108:111], v[132:135], v[198:201], v[108:111]
	v_mfma_f32_16x16x32_bf16 v[104:107], v[140:143], v[198:201], v[104:107]
	v_mfma_f32_16x16x32_bf16 v[92:95], v[132:135], v[206:209], v[92:95]
	v_mfma_f32_16x16x32_bf16 v[88:91], v[140:143], v[206:209], v[88:91]
	v_mfma_f32_16x16x32_bf16 v[76:79], v[132:135], v[214:217], v[76:79]
	v_mfma_f32_16x16x32_bf16 v[72:75], v[140:143], v[214:217], v[72:75]
	v_mfma_f32_16x16x32_bf16 v[116:119], v[154:157], v[186:189], 0
	v_mfma_f32_16x16x32_bf16 v[112:115], v[166:169], v[186:189], 0
	v_mfma_f32_16x16x32_bf16 v[100:103], v[154:157], v[194:197], 0
	v_mfma_f32_16x16x32_bf16 v[96:99], v[166:169], v[194:197], 0
	v_mfma_f32_16x16x32_bf16 v[84:87], v[154:157], v[202:205], 0
	v_mfma_f32_16x16x32_bf16 v[80:83], v[166:169], v[202:205], 0
	v_mfma_f32_16x16x32_bf16 v[68:71], v[154:157], v[210:213], 0
	v_mfma_f32_16x16x32_bf16 v[64:67], v[166:169], v[210:213], 0
	v_mfma_f32_16x16x32_bf16 v[116:119], v[158:161], v[190:193], v[116:119]
	v_mfma_f32_16x16x32_bf16 v[112:115], v[170:173], v[190:193], v[112:115]
	v_mfma_f32_16x16x32_bf16 v[100:103], v[158:161], v[198:201], v[100:103]
	v_mfma_f32_16x16x32_bf16 v[96:99], v[170:173], v[198:201], v[96:99]
	v_mfma_f32_16x16x32_bf16 v[84:87], v[158:161], v[206:209], v[84:87]
	v_mfma_f32_16x16x32_bf16 v[80:83], v[170:173], v[206:209], v[80:83]
	v_mfma_f32_16x16x32_bf16 v[68:71], v[158:161], v[214:217], v[68:71]
	v_mfma_f32_16x16x32_bf16 v[64:67], v[170:173], v[214:217], v[64:67]
	s_barrier
	s_add_i32 s45, s45, s37
	v_lshl_add_u64 v[174:175], s[4:5], 0, v[176:177]
	s_mov_b32 m0, s45
	ds_read_b128 v[186:189], v165 offset:16384
	ds_read_b128 v[190:193], v165 offset:17408
	ds_read_b128 v[194:197], v165 offset:18432
	ds_read_b128 v[198:201], v165 offset:19456
	ds_read_b128 v[202:205], v165 offset:20480
	ds_read_b128 v[206:209], v165 offset:21504
	ds_read_b128 v[210:213], v165 offset:22528
	ds_read_b128 v[214:217], v165 offset:23552
	global_load_lds_dwordx4 v[174:175], off
	s_add_i32 m0, s45, 0x2000
	v_lshl_add_u64 v[222:223], s[4:5], 0, v[144:145]
	s_add_u32 s4, s4, s0
	s_addc_u32 s5, s5, s1
	s_add_i32 s45, s54, s37
	global_load_lds_dwordx4 v[222:223], off
	v_lshl_add_u64 v[224:225], s[4:5], 0, v[176:177]
	s_mov_b32 m0, s45
	v_lshl_add_u64 v[226:227], s[4:5], 0, v[144:145]
	global_load_lds_dwordx4 v[224:225], off
	s_add_i32 m0, s45, 0x2000
	v_lshl_add_u64 v[228:229], s[34:35], 0, v[148:149]
	global_load_lds_dwordx4 v[226:227], off
	s_mov_b32 m0, s38
	v_lshl_add_u64 v[230:231], s[34:35], 0, v[146:147]
	global_load_lds_dwordx4 v[228:229], off
	s_mov_b32 m0, s39
	s_nop 0
	global_load_lds_dwordx4 v[230:231], off
	s_waitcnt vmcnt(8)
	s_waitcnt lgkmcnt(0)
	s_barrier
	s_waitcnt lgkmcnt(0)
	v_mfma_f32_16x16x32_bf16 v[60:63], v[128:131], v[186:189], 0
	v_mfma_f32_16x16x32_bf16 v[56:59], v[136:139], v[186:189], 0
	v_mfma_f32_16x16x32_bf16 v[44:47], v[128:131], v[194:197], 0
	v_mfma_f32_16x16x32_bf16 v[40:43], v[136:139], v[194:197], 0
	v_mfma_f32_16x16x32_bf16 v[28:31], v[128:131], v[202:205], 0
	v_mfma_f32_16x16x32_bf16 v[24:27], v[136:139], v[202:205], 0
	v_mfma_f32_16x16x32_bf16 v[12:15], v[128:131], v[210:213], 0
	v_mfma_f32_16x16x32_bf16 v[8:11], v[136:139], v[210:213], 0
	v_mfma_f32_16x16x32_bf16 v[60:63], v[132:135], v[190:193], v[60:63]
	v_mfma_f32_16x16x32_bf16 v[56:59], v[140:143], v[190:193], v[56:59]
	v_mfma_f32_16x16x32_bf16 v[44:47], v[132:135], v[198:201], v[44:47]
	v_mfma_f32_16x16x32_bf16 v[40:43], v[140:143], v[198:201], v[40:43]
	v_mfma_f32_16x16x32_bf16 v[28:31], v[132:135], v[206:209], v[28:31]
	v_mfma_f32_16x16x32_bf16 v[24:27], v[140:143], v[206:209], v[24:27]
	v_mfma_f32_16x16x32_bf16 v[12:15], v[132:135], v[214:217], v[12:15]
	v_mfma_f32_16x16x32_bf16 v[8:11], v[140:143], v[214:217], v[8:11]
	v_mfma_f32_16x16x32_bf16 v[52:55], v[154:157], v[186:189], 0
	v_mfma_f32_16x16x32_bf16 v[48:51], v[166:169], v[186:189], 0
	v_mfma_f32_16x16x32_bf16 v[36:39], v[154:157], v[194:197], 0
	v_mfma_f32_16x16x32_bf16 v[32:35], v[166:169], v[194:197], 0
	v_mfma_f32_16x16x32_bf16 v[20:23], v[154:157], v[202:205], 0
	v_mfma_f32_16x16x32_bf16 v[16:19], v[166:169], v[202:205], 0
	v_mfma_f32_16x16x32_bf16 v[4:7], v[154:157], v[210:213], 0
	v_mfma_f32_16x16x32_bf16 v[0:3], v[166:169], v[210:213], 0
	v_mfma_f32_16x16x32_bf16 v[52:55], v[158:161], v[190:193], v[52:55]
	v_mfma_f32_16x16x32_bf16 v[48:51], v[170:173], v[190:193], v[48:51]
	v_mfma_f32_16x16x32_bf16 v[36:39], v[158:161], v[198:201], v[36:39]
	v_mfma_f32_16x16x32_bf16 v[32:35], v[170:173], v[198:201], v[32:35]
	v_mfma_f32_16x16x32_bf16 v[20:23], v[158:161], v[206:209], v[20:23]
	v_mfma_f32_16x16x32_bf16 v[16:19], v[170:173], v[206:209], v[16:19]
	v_mfma_f32_16x16x32_bf16 v[4:7], v[158:161], v[214:217], v[4:7]
	v_mfma_f32_16x16x32_bf16 v[0:3], v[170:173], v[214:217], v[0:3]
	s_barrier
	s_add_i32 s45, 0, 0x18000
	s_add_i32 s54, 0, 0x1c000
	v_add_u32_e32 v140, s45, v163
	v_add_u32_e32 v170, s54, v163
	ds_read_b128 v[128:131], v140
	ds_read_b128 v[132:135], v140 offset:1024
	ds_read_b128 v[136:139], v140 offset:2048
	ds_read_b128 v[140:143], v140 offset:3072
	ds_read_b128 v[154:157], v170
	ds_read_b128 v[158:161], v170 offset:1024
	ds_read_b128 v[166:169], v170 offset:2048
	ds_read_b128 v[170:173], v170 offset:3072
	s_add_u32 s4, s34, s0
	s_addc_u32 s5, s35, s1
	s_mov_b32 m0, s48
	v_lshl_add_u64 v[232:233], s[4:5], 0, v[148:149]
	ds_read_b128 v[186:189], v165 offset:32768
	ds_read_b128 v[190:193], v165 offset:33792
	ds_read_b128 v[194:197], v165 offset:34816
	ds_read_b128 v[198:201], v165 offset:35840
	ds_read_b128 v[202:205], v165 offset:36864
	ds_read_b128 v[206:209], v165 offset:37888
	ds_read_b128 v[210:213], v165 offset:38912
	ds_read_b128 v[214:217], v165 offset:39936
	global_load_lds_dwordx4 v[232:233], off
	v_lshl_add_u64 v[232:233], s[4:5], 0, v[146:147]
	s_mov_b32 m0, s49
	s_nop 0
	global_load_lds_dwordx4 v[232:233], off
	s_waitcnt vmcnt(8)
	s_waitcnt lgkmcnt(0)
	s_barrier
	s_waitcnt lgkmcnt(0)
	v_mfma_f32_16x16x32_bf16 v[124:127], v[128:131], v[186:189], v[124:127]
	v_mfma_f32_16x16x32_bf16 v[120:123], v[136:139], v[186:189], v[120:123]
	v_mfma_f32_16x16x32_bf16 v[108:111], v[128:131], v[194:197], v[108:111]
	v_mfma_f32_16x16x32_bf16 v[104:107], v[136:139], v[194:197], v[104:107]
	v_mfma_f32_16x16x32_bf16 v[92:95], v[128:131], v[202:205], v[92:95]
	v_mfma_f32_16x16x32_bf16 v[88:91], v[136:139], v[202:205], v[88:91]
	v_mfma_f32_16x16x32_bf16 v[76:79], v[128:131], v[210:213], v[76:79]
	v_mfma_f32_16x16x32_bf16 v[72:75], v[136:139], v[210:213], v[72:75]
	v_mfma_f32_16x16x32_bf16 v[124:127], v[132:135], v[190:193], v[124:127]
	v_mfma_f32_16x16x32_bf16 v[120:123], v[140:143], v[190:193], v[120:123]
	v_mfma_f32_16x16x32_bf16 v[108:111], v[132:135], v[198:201], v[108:111]
	v_mfma_f32_16x16x32_bf16 v[104:107], v[140:143], v[198:201], v[104:107]
	v_mfma_f32_16x16x32_bf16 v[92:95], v[132:135], v[206:209], v[92:95]
	v_mfma_f32_16x16x32_bf16 v[88:91], v[140:143], v[206:209], v[88:91]
	v_mfma_f32_16x16x32_bf16 v[76:79], v[132:135], v[214:217], v[76:79]
	v_mfma_f32_16x16x32_bf16 v[72:75], v[140:143], v[214:217], v[72:75]
	v_mfma_f32_16x16x32_bf16 v[116:119], v[154:157], v[186:189], v[116:119]
	v_mfma_f32_16x16x32_bf16 v[112:115], v[166:169], v[186:189], v[112:115]
	v_mfma_f32_16x16x32_bf16 v[100:103], v[154:157], v[194:197], v[100:103]
	v_mfma_f32_16x16x32_bf16 v[96:99], v[166:169], v[194:197], v[96:99]
	v_mfma_f32_16x16x32_bf16 v[84:87], v[154:157], v[202:205], v[84:87]
	v_mfma_f32_16x16x32_bf16 v[80:83], v[166:169], v[202:205], v[80:83]
	v_mfma_f32_16x16x32_bf16 v[68:71], v[154:157], v[210:213], v[68:71]
	v_mfma_f32_16x16x32_bf16 v[64:67], v[166:169], v[210:213], v[64:67]
	v_mfma_f32_16x16x32_bf16 v[116:119], v[158:161], v[190:193], v[116:119]
	v_mfma_f32_16x16x32_bf16 v[112:115], v[170:173], v[190:193], v[112:115]
	v_mfma_f32_16x16x32_bf16 v[100:103], v[158:161], v[198:201], v[100:103]
	v_mfma_f32_16x16x32_bf16 v[96:99], v[170:173], v[198:201], v[96:99]
	v_mfma_f32_16x16x32_bf16 v[84:87], v[158:161], v[206:209], v[84:87]
	v_mfma_f32_16x16x32_bf16 v[80:83], v[170:173], v[206:209], v[80:83]
	v_mfma_f32_16x16x32_bf16 v[68:71], v[158:161], v[214:217], v[68:71]
	v_mfma_f32_16x16x32_bf16 v[64:67], v[170:173], v[214:217], v[64:67]
	s_barrier
	s_add_i32 s4, s45, s37
	v_lshl_add_u64 v[174:175], v[174:175], 0, s[14:15]
	s_mov_b32 m0, s4
	ds_read_b128 v[186:189], v165 offset:49152
	ds_read_b128 v[190:193], v165 offset:50176
	ds_read_b128 v[194:197], v165 offset:51200
	ds_read_b128 v[198:201], v165 offset:52224
	ds_read_b128 v[202:205], v165 offset:53248
	ds_read_b128 v[206:209], v165 offset:54272
	ds_read_b128 v[210:213], v165 offset:55296
	ds_read_b128 v[214:217], v165 offset:56320
	global_load_lds_dwordx4 v[174:175], off
	v_lshl_add_u64 v[174:175], v[222:223], 0, s[14:15]
	s_add_i32 m0, s4, 0x2000
	s_add_i32 s4, s54, s37
	global_load_lds_dwordx4 v[174:175], off
	v_lshl_add_u64 v[174:175], v[224:225], 0, s[14:15]
	s_mov_b32 m0, s4
	s_nop 0
	global_load_lds_dwordx4 v[174:175], off
	v_lshl_add_u64 v[174:175], v[226:227], 0, s[14:15]
	s_add_i32 m0, s4, 0x2000
	s_nop 0
	global_load_lds_dwordx4 v[174:175], off
	v_lshl_add_u64 v[174:175], v[228:229], 0, s[14:15]
	s_mov_b32 m0, s60
	s_nop 0
	global_load_lds_dwordx4 v[174:175], off
	v_lshl_add_u64 v[174:175], v[230:231], 0, s[14:15]
	s_mov_b32 m0, s61
	s_nop 0
	global_load_lds_dwordx4 v[174:175], off
	s_waitcnt vmcnt(8)
	s_waitcnt lgkmcnt(0)
	s_barrier
	s_waitcnt lgkmcnt(0)
	v_mfma_f32_16x16x32_bf16 v[60:63], v[128:131], v[186:189], v[60:63]
	v_mfma_f32_16x16x32_bf16 v[56:59], v[136:139], v[186:189], v[56:59]
	v_mfma_f32_16x16x32_bf16 v[44:47], v[128:131], v[194:197], v[44:47]
	v_mfma_f32_16x16x32_bf16 v[40:43], v[136:139], v[194:197], v[40:43]
	v_mfma_f32_16x16x32_bf16 v[28:31], v[128:131], v[202:205], v[28:31]
	v_mfma_f32_16x16x32_bf16 v[24:27], v[136:139], v[202:205], v[24:27]
	v_mfma_f32_16x16x32_bf16 v[12:15], v[128:131], v[210:213], v[12:15]
	v_mfma_f32_16x16x32_bf16 v[8:11], v[136:139], v[210:213], v[8:11]
	v_mfma_f32_16x16x32_bf16 v[60:63], v[132:135], v[190:193], v[60:63]
	v_mfma_f32_16x16x32_bf16 v[56:59], v[140:143], v[190:193], v[56:59]
	v_mfma_f32_16x16x32_bf16 v[44:47], v[132:135], v[198:201], v[44:47]
	v_mfma_f32_16x16x32_bf16 v[40:43], v[140:143], v[198:201], v[40:43]
	v_mfma_f32_16x16x32_bf16 v[28:31], v[132:135], v[206:209], v[28:31]
	v_mfma_f32_16x16x32_bf16 v[24:27], v[140:143], v[206:209], v[24:27]
	v_mfma_f32_16x16x32_bf16 v[12:15], v[132:135], v[214:217], v[12:15]
	v_mfma_f32_16x16x32_bf16 v[8:11], v[140:143], v[214:217], v[8:11]
	v_mfma_f32_16x16x32_bf16 v[52:55], v[154:157], v[186:189], v[52:55]
	v_mfma_f32_16x16x32_bf16 v[48:51], v[166:169], v[186:189], v[48:51]
	v_mfma_f32_16x16x32_bf16 v[36:39], v[154:157], v[194:197], v[36:39]
	v_mfma_f32_16x16x32_bf16 v[32:35], v[166:169], v[194:197], v[32:35]
	v_mfma_f32_16x16x32_bf16 v[20:23], v[154:157], v[202:205], v[20:23]
	v_mfma_f32_16x16x32_bf16 v[16:19], v[166:169], v[202:205], v[16:19]
	v_mfma_f32_16x16x32_bf16 v[4:7], v[154:157], v[210:213], v[4:7]
	v_mfma_f32_16x16x32_bf16 v[0:3], v[166:169], v[210:213], v[0:3]
	v_mfma_f32_16x16x32_bf16 v[52:55], v[158:161], v[190:193], v[52:55]
	v_mfma_f32_16x16x32_bf16 v[48:51], v[170:173], v[190:193], v[48:51]
	v_mfma_f32_16x16x32_bf16 v[36:39], v[158:161], v[198:201], v[36:39]
	v_mfma_f32_16x16x32_bf16 v[32:35], v[170:173], v[198:201], v[32:35]
	v_mfma_f32_16x16x32_bf16 v[20:23], v[158:161], v[206:209], v[20:23]
	v_mfma_f32_16x16x32_bf16 v[16:19], v[170:173], v[206:209], v[16:19]
	v_mfma_f32_16x16x32_bf16 v[4:7], v[158:161], v[214:217], v[4:7]
	v_mfma_f32_16x16x32_bf16 v[0:3], v[170:173], v[214:217], v[0:3]
	s_barrier
	s_add_u32 s30, s30, 0x100
	s_addc_u32 s31, s31, 0
	s_add_u32 s10, s10, 0x100
	s_addc_u32 s11, s11, 0
	s_cmp_ge_i32 s44, s59
	s_mov_b32 s34, s44
	s_cbranch_scc1 .Lpeelx_6

.Lpeelx_6:
.LBB0_306:
	s_mov_b64 s[46:47], s[90:91]
	s_mov_b64 s[96:97], s[88:89]
	s_mov_b64 s[54:55], s[86:87]
	s_mov_b64 s[70:71], s[84:85]
	s_mov_b64 s[64:65], s[82:83]
	s_mov_b64 s[44:45], s[80:81]
	s_mov_b64 s[34:35], s[78:79]
	s_mov_b64 s[30:31], s[76:77]
	s_and_b64 vcc, exec, s[24:25]
	s_cbranch_vccz .LBB0_308
	s_barrier

.LBB0_392:
	s_andn2_b64 vcc, exec, s[20:21]
	s_cbranch_vccnz .LBB0_395
	s_add_u32 s28, s28, 0x80
	s_addc_u32 s29, s29, 0
	s_add_u32 s10, s30, 0x100
	s_addc_u32 s11, s31, 0
	s_mov_b32 s30, 0
	s_cmp_lg_u32 s100, 0
	s_cbranch_scc0 .Llbb_3
	s_barrier
	s_mov_b32 s100, 0
.Llbb_3:
	s_add_i32 s44, s30, 2
	s_add_u32 s4, s28, 0x80
	s_addc_u32 s5, s29, 0
	s_add_i32 s45, 0, 0x10000
	s_cmp_eq_u32 s61, s30
	s_cselect_b32 s31, s25, s5
	s_cselect_b32 s30, s24, s4
	s_cselect_b32 s5, s27, s11
	s_cselect_b32 s4, s26, s10
	s_add_i32 s54, 0, 0x14000
	v_add_u32_e32 v156, s45, v151
	v_add_u32_e32 v172, s54, v151
	ds_read_b128 v[128:131], v156
	ds_read_b128 v[142:145], v156 offset:1024
	ds_read_b128 v[146:149], v156 offset:2048
	ds_read_b128 v[156:159], v156 offset:3072
	ds_read_b128 v[160:163], v172
	ds_read_b128 v[164:167], v172 offset:1024
	ds_read_b128 v[168:171], v172 offset:2048
	ds_read_b128 v[172:175], v172 offset:3072
	v_lshl_add_u64 v[222:223], s[28:29], 0, v[138:139]
	s_add_i32 m0, s37, 0xc000
	ds_read_b128 v[186:189], v155
	ds_read_b128 v[190:193], v155 offset:1024
	ds_read_b128 v[194:197], v155 offset:2048
	ds_read_b128 v[198:201], v155 offset:3072
	ds_read_b128 v[202:205], v155 offset:4096
	ds_read_b128 v[206:209], v155 offset:5120
	ds_read_b128 v[210:213], v155 offset:6144
	ds_read_b128 v[214:217], v155 offset:7168
	global_load_lds_dwordx4 v[222:223], off
	v_lshl_add_u64 v[222:223], s[28:29], 0, v[140:141]
	s_add_i32 m0, s37, 0xe000
	s_nop 0
	global_load_lds_dwordx4 v[222:223], off
	s_waitcnt vmcnt(8)
	s_waitcnt lgkmcnt(0)
	s_barrier
	s_waitcnt lgkmcnt(0)
	v_mfma_f32_16x16x32_bf16 v[120:123], v[128:131], v[186:189], 0
	v_mfma_f32_16x16x32_bf16 v[116:119], v[146:149], v[186:189], 0
	v_mfma_f32_16x16x32_bf16 v[108:111], v[128:131], v[194:197], 0
	v_mfma_f32_16x16x32_bf16 v[100:103], v[146:149], v[194:197], 0
	v_mfma_f32_16x16x32_bf16 v[92:95], v[128:131], v[202:205], 0
	v_mfma_f32_16x16x32_bf16 v[84:87], v[146:149], v[202:205], 0
	v_mfma_f32_16x16x32_bf16 v[76:79], v[128:131], v[210:213], 0
	v_mfma_f32_16x16x32_bf16 v[68:71], v[146:149], v[210:213], 0
	v_mfma_f32_16x16x32_bf16 v[120:123], v[142:145], v[190:193], v[120:123]
	v_mfma_f32_16x16x32_bf16 v[116:119], v[156:159], v[190:193], v[116:119]
	v_mfma_f32_16x16x32_bf16 v[108:111], v[142:145], v[198:201], v[108:111]
	v_mfma_f32_16x16x32_bf16 v[100:103], v[156:159], v[198:201], v[100:103]
	v_mfma_f32_16x16x32_bf16 v[92:95], v[142:145], v[206:209], v[92:95]
	v_mfma_f32_16x16x32_bf16 v[84:87], v[156:159], v[206:209], v[84:87]
	v_mfma_f32_16x16x32_bf16 v[76:79], v[142:145], v[214:217], v[76:79]
	v_mfma_f32_16x16x32_bf16 v[68:71], v[156:159], v[214:217], v[68:71]
	v_mfma_f32_16x16x32_bf16 v[124:127], v[160:163], v[186:189], 0
	v_mfma_f32_16x16x32_bf16 v[112:115], v[168:171], v[186:189], 0
	v_mfma_f32_16x16x32_bf16 v[104:107], v[160:163], v[194:197], 0
	v_mfma_f32_16x16x32_bf16 v[96:99], v[168:171], v[194:197], 0
	v_mfma_f32_16x16x32_bf16 v[88:91], v[160:163], v[202:205], 0
	v_mfma_f32_16x16x32_bf16 v[80:83], v[168:171], v[202:205], 0
	v_mfma_f32_16x16x32_bf16 v[72:75], v[160:163], v[210:213], 0
	v_mfma_f32_16x16x32_bf16 v[64:67], v[168:171], v[210:213], 0
	v_mfma_f32_16x16x32_bf16 v[124:127], v[164:167], v[190:193], v[124:127]
	v_mfma_f32_16x16x32_bf16 v[112:115], v[172:175], v[190:193], v[112:115]
	v_mfma_f32_16x16x32_bf16 v[104:107], v[164:167], v[198:201], v[104:107]
	v_mfma_f32_16x16x32_bf16 v[96:99], v[172:175], v[198:201], v[96:99]
	v_mfma_f32_16x16x32_bf16 v[88:91], v[164:167], v[206:209], v[88:91]
	v_mfma_f32_16x16x32_bf16 v[80:83], v[172:175], v[206:209], v[80:83]
	v_mfma_f32_16x16x32_bf16 v[72:75], v[164:167], v[214:217], v[72:75]
	v_mfma_f32_16x16x32_bf16 v[64:67], v[172:175], v[214:217], v[64:67]
	s_barrier
	s_add_i32 s45, s45, s36
	v_lshl_add_u64 v[222:223], s[4:5], 0, v[176:177]
	s_mov_b32 m0, s45
	ds_read_b128 v[186:189], v155 offset:16384
	ds_read_b128 v[190:193], v155 offset:17408
	ds_read_b128 v[194:197], v155 offset:18432
	ds_read_b128 v[198:201], v155 offset:19456
	ds_read_b128 v[202:205], v155 offset:20480
	ds_read_b128 v[206:209], v155 offset:21504
	ds_read_b128 v[210:213], v155 offset:22528
	ds_read_b128 v[214:217], v155 offset:23552
	global_load_lds_dwordx4 v[222:223], off
	s_add_i32 m0, s45, 0x2000
	v_lshl_add_u64 v[224:225], s[4:5], 0, v[132:133]
	s_add_u32 s4, s4, s6
	s_addc_u32 s5, s5, s7
	s_add_i32 s45, s54, s36
	global_load_lds_dwordx4 v[224:225], off
	v_lshl_add_u64 v[226:227], s[4:5], 0, v[176:177]
	s_mov_b32 m0, s45
	v_lshl_add_u64 v[228:229], s[4:5], 0, v[132:133]
	global_load_lds_dwordx4 v[226:227], off
	s_add_i32 m0, s45, 0x2000
	v_lshl_add_u64 v[230:231], s[30:31], 0, v[136:137]
	global_load_lds_dwordx4 v[228:229], off
	s_mov_b32 m0, s37
	v_lshl_add_u64 v[232:233], s[30:31], 0, v[134:135]
	global_load_lds_dwordx4 v[230:231], off
	s_mov_b32 m0, s38
	s_nop 0
	global_load_lds_dwordx4 v[232:233], off
	s_waitcnt vmcnt(8)
	s_waitcnt lgkmcnt(0)
	s_barrier
	s_waitcnt lgkmcnt(0)
	v_mfma_f32_16x16x32_bf16 v[60:63], v[128:131], v[186:189], 0
	v_mfma_f32_16x16x32_bf16 v[52:55], v[146:149], v[186:189], 0
	v_mfma_f32_16x16x32_bf16 v[44:47], v[128:131], v[194:197], 0
	v_mfma_f32_16x16x32_bf16 v[36:39], v[146:149], v[194:197], 0
	v_mfma_f32_16x16x32_bf16 v[28:31], v[128:131], v[202:205], 0
	v_mfma_f32_16x16x32_bf16 v[20:23], v[146:149], v[202:205], 0
	v_mfma_f32_16x16x32_bf16 v[12:15], v[128:131], v[210:213], 0
	v_mfma_f32_16x16x32_bf16 v[4:7], v[146:149], v[210:213], 0
	v_mfma_f32_16x16x32_bf16 v[60:63], v[142:145], v[190:193], v[60:63]
	v_mfma_f32_16x16x32_bf16 v[52:55], v[156:159], v[190:193], v[52:55]
	v_mfma_f32_16x16x32_bf16 v[44:47], v[142:145], v[198:201], v[44:47]
	v_mfma_f32_16x16x32_bf16 v[36:39], v[156:159], v[198:201], v[36:39]
	v_mfma_f32_16x16x32_bf16 v[28:31], v[142:145], v[206:209], v[28:31]
	v_mfma_f32_16x16x32_bf16 v[20:23], v[156:159], v[206:209], v[20:23]
	v_mfma_f32_16x16x32_bf16 v[12:15], v[142:145], v[214:217], v[12:15]
	v_mfma_f32_16x16x32_bf16 v[4:7], v[156:159], v[214:217], v[4:7]
	v_mfma_f32_16x16x32_bf16 v[56:59], v[160:163], v[186:189], 0
	v_mfma_f32_16x16x32_bf16 v[48:51], v[168:171], v[186:189], 0
	v_mfma_f32_16x16x32_bf16 v[40:43], v[160:163], v[194:197], 0
	v_mfma_f32_16x16x32_bf16 v[32:35], v[168:171], v[194:197], 0
	v_mfma_f32_16x16x32_bf16 v[24:27], v[160:163], v[202:205], 0
	v_mfma_f32_16x16x32_bf16 v[16:19], v[168:171], v[202:205], 0
	v_mfma_f32_16x16x32_bf16 v[8:11], v[160:163], v[210:213], 0
	v_mfma_f32_16x16x32_bf16 v[0:3], v[168:171], v[210:213], 0
	v_mfma_f32_16x16x32_bf16 v[56:59], v[164:167], v[190:193], v[56:59]
	v_mfma_f32_16x16x32_bf16 v[48:51], v[172:175], v[190:193], v[48:51]
	v_mfma_f32_16x16x32_bf16 v[40:43], v[164:167], v[198:201], v[40:43]
	v_mfma_f32_16x16x32_bf16 v[32:35], v[172:175], v[198:201], v[32:35]
	v_mfma_f32_16x16x32_bf16 v[24:27], v[164:167], v[206:209], v[24:27]
	v_mfma_f32_16x16x32_bf16 v[16:19], v[172:175], v[206:209], v[16:19]
	v_mfma_f32_16x16x32_bf16 v[8:11], v[164:167], v[214:217], v[8:11]
	v_mfma_f32_16x16x32_bf16 v[0:3], v[172:175], v[214:217], v[0:3]
	s_barrier
	s_add_i32 s45, 0, 0x18000
	s_add_i32 s54, 0, 0x1c000
	v_add_u32_e32 v156, s45, v151
	v_add_u32_e32 v172, s54, v151
	ds_read_b128 v[128:131], v156
	ds_read_b128 v[142:145], v156 offset:1024
	ds_read_b128 v[146:149], v156 offset:2048
	ds_read_b128 v[156:159], v156 offset:3072
	ds_read_b128 v[160:163], v172
	ds_read_b128 v[164:167], v172 offset:1024
	ds_read_b128 v[168:171], v172 offset:2048
	ds_read_b128 v[172:175], v172 offset:3072
	s_add_u32 s4, s30, s6
	s_addc_u32 s5, s31, s7
	s_mov_b32 m0, s39
	v_lshl_add_u64 v[234:235], s[4:5], 0, v[136:137]
	ds_read_b128 v[186:189], v155 offset:32768
	ds_read_b128 v[190:193], v155 offset:33792
	ds_read_b128 v[194:197], v155 offset:34816
	ds_read_b128 v[198:201], v155 offset:35840
	ds_read_b128 v[202:205], v155 offset:36864
	ds_read_b128 v[206:209], v155 offset:37888
	ds_read_b128 v[210:213], v155 offset:38912
	ds_read_b128 v[214:217], v155 offset:39936
	global_load_lds_dwordx4 v[234:235], off
	v_lshl_add_u64 v[234:235], s[4:5], 0, v[134:135]
	s_mov_b32 m0, s48
	s_nop 0
	global_load_lds_dwordx4 v[234:235], off
	s_waitcnt vmcnt(8)
	s_waitcnt lgkmcnt(0)
	s_barrier
	s_waitcnt lgkmcnt(0)
	v_mfma_f32_16x16x32_bf16 v[120:123], v[128:131], v[186:189], v[120:123]
	v_mfma_f32_16x16x32_bf16 v[116:119], v[146:149], v[186:189], v[116:119]
	v_mfma_f32_16x16x32_bf16 v[108:111], v[128:131], v[194:197], v[108:111]
	v_mfma_f32_16x16x32_bf16 v[100:103], v[146:149], v[194:197], v[100:103]
	v_mfma_f32_16x16x32_bf16 v[92:95], v[128:131], v[202:205], v[92:95]
	v_mfma_f32_16x16x32_bf16 v[84:87], v[146:149], v[202:205], v[84:87]
	v_mfma_f32_16x16x32_bf16 v[76:79], v[128:131], v[210:213], v[76:79]
	v_mfma_f32_16x16x32_bf16 v[68:71], v[146:149], v[210:213], v[68:71]
	v_mfma_f32_16x16x32_bf16 v[120:123], v[142:145], v[190:193], v[120:123]
	v_mfma_f32_16x16x32_bf16 v[116:119], v[156:159], v[190:193], v[116:119]
	v_mfma_f32_16x16x32_bf16 v[108:111], v[142:145], v[198:201], v[108:111]
	v_mfma_f32_16x16x32_bf16 v[100:103], v[156:159], v[198:201], v[100:103]
	v_mfma_f32_16x16x32_bf16 v[92:95], v[142:145], v[206:209], v[92:95]
	v_mfma_f32_16x16x32_bf16 v[84:87], v[156:159], v[206:209], v[84:87]
	v_mfma_f32_16x16x32_bf16 v[76:79], v[142:145], v[214:217], v[76:79]
	v_mfma_f32_16x16x32_bf16 v[68:71], v[156:159], v[214:217], v[68:71]
	v_mfma_f32_16x16x32_bf16 v[124:127], v[160:163], v[186:189], v[124:127]
	v_mfma_f32_16x16x32_bf16 v[112:115], v[168:171], v[186:189], v[112:115]
	v_mfma_f32_16x16x32_bf16 v[104:107], v[160:163], v[194:197], v[104:107]
	v_mfma_f32_16x16x32_bf16 v[96:99], v[168:171], v[194:197], v[96:99]
	v_mfma_f32_16x16x32_bf16 v[88:91], v[160:163], v[202:205], v[88:91]
	v_mfma_f32_16x16x32_bf16 v[80:83], v[168:171], v[202:205], v[80:83]
	v_mfma_f32_16x16x32_bf16 v[72:75], v[160:163], v[210:213], v[72:75]
	v_mfma_f32_16x16x32_bf16 v[64:67], v[168:171], v[210:213], v[64:67]
	v_mfma_f32_16x16x32_bf16 v[124:127], v[164:167], v[190:193], v[124:127]
	v_mfma_f32_16x16x32_bf16 v[112:115], v[172:175], v[190:193], v[112:115]
	v_mfma_f32_16x16x32_bf16 v[104:107], v[164:167], v[198:201], v[104:107]
	v_mfma_f32_16x16x32_bf16 v[96:99], v[172:175], v[198:201], v[96:99]
	v_mfma_f32_16x16x32_bf16 v[88:91], v[164:167], v[206:209], v[88:91]
	v_mfma_f32_16x16x32_bf16 v[80:83], v[172:175], v[206:209], v[80:83]
	v_mfma_f32_16x16x32_bf16 v[72:75], v[164:167], v[214:217], v[72:75]
	v_mfma_f32_16x16x32_bf16 v[64:67], v[172:175], v[214:217], v[64:67]
	s_barrier
	s_add_i32 s4, s45, s36
	v_lshl_add_u64 v[222:223], v[222:223], 0, s[14:15]
	s_mov_b32 m0, s4
	ds_read_b128 v[186:189], v155 offset:49152
	ds_read_b128 v[190:193], v155 offset:50176
	ds_read_b128 v[194:197], v155 offset:51200
	ds_read_b128 v[198:201], v155 offset:52224
	ds_read_b128 v[202:205], v155 offset:53248
	ds_read_b128 v[206:209], v155 offset:54272
	ds_read_b128 v[210:213], v155 offset:55296
	ds_read_b128 v[214:217], v155 offset:56320
	global_load_lds_dwordx4 v[222:223], off
	v_lshl_add_u64 v[222:223], v[224:225], 0, s[14:15]
	s_add_i32 m0, s4, 0x2000
	s_add_i32 s4, s54, s36
	global_load_lds_dwordx4 v[222:223], off
	v_lshl_add_u64 v[222:223], v[226:227], 0, s[14:15]
	s_mov_b32 m0, s4
	s_nop 0
	global_load_lds_dwordx4 v[222:223], off
	v_lshl_add_u64 v[222:223], v[228:229], 0, s[14:15]
	s_add_i32 m0, s4, 0x2000
	s_nop 0
	global_load_lds_dwordx4 v[222:223], off
	v_lshl_add_u64 v[222:223], v[230:231], 0, s[14:15]
	s_mov_b32 m0, s59
	s_nop 0
	global_load_lds_dwordx4 v[222:223], off
	v_lshl_add_u64 v[222:223], v[232:233], 0, s[14:15]
	s_mov_b32 m0, s60
	s_nop 0
	global_load_lds_dwordx4 v[222:223], off
	s_waitcnt vmcnt(8)
	s_waitcnt lgkmcnt(0)
	s_barrier
	s_waitcnt lgkmcnt(0)
	v_mfma_f32_16x16x32_bf16 v[60:63], v[128:131], v[186:189], v[60:63]
	v_mfma_f32_16x16x32_bf16 v[52:55], v[146:149], v[186:189], v[52:55]
	v_mfma_f32_16x16x32_bf16 v[44:47], v[128:131], v[194:197], v[44:47]
	v_mfma_f32_16x16x32_bf16 v[36:39], v[146:149], v[194:197], v[36:39]
	v_mfma_f32_16x16x32_bf16 v[28:31], v[128:131], v[202:205], v[28:31]
	v_mfma_f32_16x16x32_bf16 v[20:23], v[146:149], v[202:205], v[20:23]
	v_mfma_f32_16x16x32_bf16 v[12:15], v[128:131], v[210:213], v[12:15]
	v_mfma_f32_16x16x32_bf16 v[4:7], v[146:149], v[210:213], v[4:7]
	v_mfma_f32_16x16x32_bf16 v[60:63], v[142:145], v[190:193], v[60:63]
	v_mfma_f32_16x16x32_bf16 v[52:55], v[156:159], v[190:193], v[52:55]
	v_mfma_f32_16x16x32_bf16 v[44:47], v[142:145], v[198:201], v[44:47]
	v_mfma_f32_16x16x32_bf16 v[36:39], v[156:159], v[198:201], v[36:39]
	v_mfma_f32_16x16x32_bf16 v[28:31], v[142:145], v[206:209], v[28:31]
	v_mfma_f32_16x16x32_bf16 v[20:23], v[156:159], v[206:209], v[20:23]
	v_mfma_f32_16x16x32_bf16 v[12:15], v[142:145], v[214:217], v[12:15]
	v_mfma_f32_16x16x32_bf16 v[4:7], v[156:159], v[214:217], v[4:7]
	v_mfma_f32_16x16x32_bf16 v[56:59], v[160:163], v[186:189], v[56:59]
	v_mfma_f32_16x16x32_bf16 v[48:51], v[168:171], v[186:189], v[48:51]
	v_mfma_f32_16x16x32_bf16 v[40:43], v[160:163], v[194:197], v[40:43]
	v_mfma_f32_16x16x32_bf16 v[32:35], v[168:171], v[194:197], v[32:35]
	v_mfma_f32_16x16x32_bf16 v[24:27], v[160:163], v[202:205], v[24:27]
	v_mfma_f32_16x16x32_bf16 v[16:19], v[168:171], v[202:205], v[16:19]
	v_mfma_f32_16x16x32_bf16 v[8:11], v[160:163], v[210:213], v[8:11]
	v_mfma_f32_16x16x32_bf16 v[0:3], v[168:171], v[210:213], v[0:3]
	v_mfma_f32_16x16x32_bf16 v[56:59], v[164:167], v[190:193], v[56:59]
	v_mfma_f32_16x16x32_bf16 v[48:51], v[172:175], v[190:193], v[48:51]
	v_mfma_f32_16x16x32_bf16 v[40:43], v[164:167], v[198:201], v[40:43]
	v_mfma_f32_16x16x32_bf16 v[32:35], v[172:175], v[198:201], v[32:35]
	v_mfma_f32_16x16x32_bf16 v[24:27], v[164:167], v[206:209], v[24:27]
	v_mfma_f32_16x16x32_bf16 v[16:19], v[172:175], v[206:209], v[16:19]
	v_mfma_f32_16x16x32_bf16 v[8:11], v[164:167], v[214:217], v[8:11]
	v_mfma_f32_16x16x32_bf16 v[0:3], v[172:175], v[214:217], v[0:3]
	s_barrier
	s_add_u32 s28, s28, 0x100
	s_addc_u32 s29, s29, 0
	s_add_u32 s10, s10, 0x100
	s_addc_u32 s11, s11, 0
	s_cmp_ge_i32 s44, s49
	s_mov_b32 s30, s44
	s_cbranch_scc1 .Lpeelx_7

.Lpeelx_7:
.LBB0_395:
	s_and_b64 vcc, exec, s[22:23]
	s_cbranch_vccz .LBB0_397
	s_barrier

.LBB0_473:
	s_andn2_b64 vcc, exec, s[20:21]
	s_waitcnt lgkmcnt(0)
	s_cbranch_vccnz .LBB0_476
	s_add_u32 s28, s28, 0x80
	s_addc_u32 s29, s29, 0
	s_add_u32 s10, s30, 0x100
	s_addc_u32 s11, s31, 0
	s_mov_b32 s30, 0
	s_cmp_lg_u32 s100, 0
	s_cbranch_scc0 .Llbb_4
	s_barrier
	s_mov_b32 s100, 0
.Llbb_4:
	s_add_i32 s44, s30, 2
	s_add_u32 s4, s28, 0x80
	s_addc_u32 s5, s29, 0
	s_add_i32 s45, 0, 0x10000
	s_cmp_eq_u32 s61, s30
	s_cselect_b32 s31, s25, s5
	s_cselect_b32 s30, s24, s4
	s_cselect_b32 s5, s27, s11
	s_cselect_b32 s4, s26, s10
	s_add_i32 s54, 0, 0x14000
	v_add_u32_e32 v140, s45, v195
	v_add_u32_e32 v166, s54, v195
	ds_read_b128 v[128:131], v140
	ds_read_b128 v[132:135], v140 offset:1024
	ds_read_b128 v[136:139], v140 offset:2048
	ds_read_b128 v[140:143], v140 offset:3072
	ds_read_b128 v[144:147], v166
	ds_read_b128 v[148:151], v166 offset:1024
	ds_read_b128 v[152:155], v166 offset:2048
	ds_read_b128 v[166:169], v166 offset:3072
	v_lshl_add_u64 v[174:175], s[28:29], 0, v[162:163]
	s_add_i32 m0, s38, 0xc000
	ds_read_b128 v[170:173], v197
	ds_read_b128 v[186:189], v197 offset:1024
	ds_read_b128 v[190:193], v197 offset:2048
	ds_read_b128 v[198:201], v197 offset:3072
	ds_read_b128 v[202:205], v197 offset:4096
	ds_read_b128 v[206:209], v197 offset:5120
	ds_read_b128 v[210:213], v197 offset:6144
	ds_read_b128 v[214:217], v197 offset:7168
	global_load_lds_dwordx4 v[174:175], off
	v_lshl_add_u64 v[174:175], s[28:29], 0, v[164:165]
	s_add_i32 m0, s38, 0xe000
	s_nop 0
	global_load_lds_dwordx4 v[174:175], off
	s_waitcnt vmcnt(8)
	s_waitcnt lgkmcnt(0)
	s_barrier
	s_waitcnt lgkmcnt(0)
	v_mfma_f32_16x16x32_bf16 v[120:123], v[128:131], v[170:173], 0
	v_mfma_f32_16x16x32_bf16 v[124:127], v[136:139], v[170:173], 0
	v_mfma_f32_16x16x32_bf16 v[108:111], v[128:131], v[190:193], 0
	v_mfma_f32_16x16x32_bf16 v[104:107], v[136:139], v[190:193], 0
	v_mfma_f32_16x16x32_bf16 v[92:95], v[128:131], v[202:205], 0
	v_mfma_f32_16x16x32_bf16 v[88:91], v[136:139], v[202:205], 0
	v_mfma_f32_16x16x32_bf16 v[76:79], v[128:131], v[210:213], 0
	v_mfma_f32_16x16x32_bf16 v[72:75], v[136:139], v[210:213], 0
	v_mfma_f32_16x16x32_bf16 v[120:123], v[132:135], v[186:189], v[120:123]
	v_mfma_f32_16x16x32_bf16 v[124:127], v[140:143], v[186:189], v[124:127]
	v_mfma_f32_16x16x32_bf16 v[108:111], v[132:135], v[198:201], v[108:111]
	v_mfma_f32_16x16x32_bf16 v[104:107], v[140:143], v[198:201], v[104:107]
	v_mfma_f32_16x16x32_bf16 v[92:95], v[132:135], v[206:209], v[92:95]
	v_mfma_f32_16x16x32_bf16 v[88:91], v[140:143], v[206:209], v[88:91]
	v_mfma_f32_16x16x32_bf16 v[76:79], v[132:135], v[214:217], v[76:79]
	v_mfma_f32_16x16x32_bf16 v[72:75], v[140:143], v[214:217], v[72:75]
	v_mfma_f32_16x16x32_bf16 v[116:119], v[144:147], v[170:173], 0
	v_mfma_f32_16x16x32_bf16 v[112:115], v[152:155], v[170:173], 0
	v_mfma_f32_16x16x32_bf16 v[100:103], v[144:147], v[190:193], 0
	v_mfma_f32_16x16x32_bf16 v[96:99], v[152:155], v[190:193], 0
	v_mfma_f32_16x16x32_bf16 v[84:87], v[144:147], v[202:205], 0
	v_mfma_f32_16x16x32_bf16 v[80:83], v[152:155], v[202:205], 0
	v_mfma_f32_16x16x32_bf16 v[68:71], v[144:147], v[210:213], 0
	v_mfma_f32_16x16x32_bf16 v[64:67], v[152:155], v[210:213], 0
	v_mfma_f32_16x16x32_bf16 v[116:119], v[148:151], v[186:189], v[116:119]
	v_mfma_f32_16x16x32_bf16 v[112:115], v[166:169], v[186:189], v[112:115]
	v_mfma_f32_16x16x32_bf16 v[100:103], v[148:151], v[198:201], v[100:103]
	v_mfma_f32_16x16x32_bf16 v[96:99], v[166:169], v[198:201], v[96:99]
	v_mfma_f32_16x16x32_bf16 v[84:87], v[148:151], v[206:209], v[84:87]
	v_mfma_f32_16x16x32_bf16 v[80:83], v[166:169], v[206:209], v[80:83]
	v_mfma_f32_16x16x32_bf16 v[68:71], v[148:151], v[214:217], v[68:71]
	v_mfma_f32_16x16x32_bf16 v[64:67], v[166:169], v[214:217], v[64:67]
	s_barrier
	s_add_i32 s45, s45, s37
	v_lshl_add_u64 v[174:175], s[4:5], 0, v[176:177]
	s_mov_b32 m0, s45
	ds_read_b128 v[170:173], v197 offset:16384
	ds_read_b128 v[186:189], v197 offset:17408
	ds_read_b128 v[190:193], v197 offset:18432
	ds_read_b128 v[198:201], v197 offset:19456
	ds_read_b128 v[202:205], v197 offset:20480
	ds_read_b128 v[206:209], v197 offset:21504
	ds_read_b128 v[210:213], v197 offset:22528
	ds_read_b128 v[214:217], v197 offset:23552
	global_load_lds_dwordx4 v[174:175], off
	s_add_i32 m0, s45, 0x2000
	v_lshl_add_u64 v[222:223], s[4:5], 0, v[156:157]
	s_add_u32 s4, s4, s6
	s_addc_u32 s5, s5, s7
	s_add_i32 s45, s54, s37
	global_load_lds_dwordx4 v[222:223], off
	v_lshl_add_u64 v[224:225], s[4:5], 0, v[176:177]
	s_mov_b32 m0, s45
	v_lshl_add_u64 v[226:227], s[4:5], 0, v[156:157]
	global_load_lds_dwordx4 v[224:225], off
	s_add_i32 m0, s45, 0x2000
	v_lshl_add_u64 v[228:229], s[30:31], 0, v[160:161]
	global_load_lds_dwordx4 v[226:227], off
	s_mov_b32 m0, s38
	v_lshl_add_u64 v[230:231], s[30:31], 0, v[158:159]
	global_load_lds_dwordx4 v[228:229], off
	s_mov_b32 m0, s39
	s_nop 0
	global_load_lds_dwordx4 v[230:231], off
	s_waitcnt vmcnt(8)
	s_waitcnt lgkmcnt(0)
	s_barrier
	s_waitcnt lgkmcnt(0)
	v_mfma_f32_16x16x32_bf16 v[60:63], v[128:131], v[170:173], 0
	v_mfma_f32_16x16x32_bf16 v[56:59], v[136:139], v[170:173], 0
	v_mfma_f32_16x16x32_bf16 v[44:47], v[128:131], v[190:193], 0
	v_mfma_f32_16x16x32_bf16 v[40:43], v[136:139], v[190:193], 0
	v_mfma_f32_16x16x32_bf16 v[28:31], v[128:131], v[202:205], 0
	v_mfma_f32_16x16x32_bf16 v[24:27], v[136:139], v[202:205], 0
	v_mfma_f32_16x16x32_bf16 v[12:15], v[128:131], v[210:213], 0
	v_mfma_f32_16x16x32_bf16 v[8:11], v[136:139], v[210:213], 0
	v_mfma_f32_16x16x32_bf16 v[60:63], v[132:135], v[186:189], v[60:63]
	v_mfma_f32_16x16x32_bf16 v[56:59], v[140:143], v[186:189], v[56:59]
	v_mfma_f32_16x16x32_bf16 v[44:47], v[132:135], v[198:201], v[44:47]
	v_mfma_f32_16x16x32_bf16 v[40:43], v[140:143], v[198:201], v[40:43]
	v_mfma_f32_16x16x32_bf16 v[28:31], v[132:135], v[206:209], v[28:31]
	v_mfma_f32_16x16x32_bf16 v[24:27], v[140:143], v[206:209], v[24:27]
	v_mfma_f32_16x16x32_bf16 v[12:15], v[132:135], v[214:217], v[12:15]
	v_mfma_f32_16x16x32_bf16 v[8:11], v[140:143], v[214:217], v[8:11]
	v_mfma_f32_16x16x32_bf16 v[52:55], v[144:147], v[170:173], 0
	v_mfma_f32_16x16x32_bf16 v[48:51], v[152:155], v[170:173], 0
	v_mfma_f32_16x16x32_bf16 v[36:39], v[144:147], v[190:193], 0
	v_mfma_f32_16x16x32_bf16 v[32:35], v[152:155], v[190:193], 0
	v_mfma_f32_16x16x32_bf16 v[20:23], v[144:147], v[202:205], 0
	v_mfma_f32_16x16x32_bf16 v[16:19], v[152:155], v[202:205], 0
	v_mfma_f32_16x16x32_bf16 v[4:7], v[144:147], v[210:213], 0
	v_mfma_f32_16x16x32_bf16 v[0:3], v[152:155], v[210:213], 0
	v_mfma_f32_16x16x32_bf16 v[52:55], v[148:151], v[186:189], v[52:55]
	v_mfma_f32_16x16x32_bf16 v[48:51], v[166:169], v[186:189], v[48:51]
	v_mfma_f32_16x16x32_bf16 v[36:39], v[148:151], v[198:201], v[36:39]
	v_mfma_f32_16x16x32_bf16 v[32:35], v[166:169], v[198:201], v[32:35]
	v_mfma_f32_16x16x32_bf16 v[20:23], v[148:151], v[206:209], v[20:23]
	v_mfma_f32_16x16x32_bf16 v[16:19], v[166:169], v[206:209], v[16:19]
	v_mfma_f32_16x16x32_bf16 v[4:7], v[148:151], v[214:217], v[4:7]
	v_mfma_f32_16x16x32_bf16 v[0:3], v[166:169], v[214:217], v[0:3]
	s_barrier
	s_add_i32 s45, 0, 0x18000
	s_add_i32 s54, 0, 0x1c000
	v_add_u32_e32 v140, s45, v195
	v_add_u32_e32 v166, s54, v195
	ds_read_b128 v[128:131], v140
	ds_read_b128 v[132:135], v140 offset:1024
	ds_read_b128 v[136:139], v140 offset:2048
	ds_read_b128 v[140:143], v140 offset:3072
	ds_read_b128 v[144:147], v166
	ds_read_b128 v[148:151], v166 offset:1024
	ds_read_b128 v[152:155], v166 offset:2048
	ds_read_b128 v[166:169], v166 offset:3072
	s_add_u32 s4, s30, s6
	s_addc_u32 s5, s31, s7
	s_mov_b32 m0, s48
	v_lshl_add_u64 v[232:233], s[4:5], 0, v[160:161]
	ds_read_b128 v[170:173], v197 offset:32768
	ds_read_b128 v[186:189], v197 offset:33792
	ds_read_b128 v[190:193], v197 offset:34816
	ds_read_b128 v[198:201], v197 offset:35840
	ds_read_b128 v[202:205], v197 offset:36864
	ds_read_b128 v[206:209], v197 offset:37888
	ds_read_b128 v[210:213], v197 offset:38912
	ds_read_b128 v[214:217], v197 offset:39936
	global_load_lds_dwordx4 v[232:233], off
	v_lshl_add_u64 v[232:233], s[4:5], 0, v[158:159]
	s_mov_b32 m0, s49
	s_nop 0
	global_load_lds_dwordx4 v[232:233], off
	s_waitcnt vmcnt(8)
	s_waitcnt lgkmcnt(0)
	s_barrier
	s_waitcnt lgkmcnt(0)
	v_mfma_f32_16x16x32_bf16 v[120:123], v[128:131], v[170:173], v[120:123]
	v_mfma_f32_16x16x32_bf16 v[124:127], v[136:139], v[170:173], v[124:127]
	v_mfma_f32_16x16x32_bf16 v[108:111], v[128:131], v[190:193], v[108:111]
	v_mfma_f32_16x16x32_bf16 v[104:107], v[136:139], v[190:193], v[104:107]
	v_mfma_f32_16x16x32_bf16 v[92:95], v[128:131], v[202:205], v[92:95]
	v_mfma_f32_16x16x32_bf16 v[88:91], v[136:139], v[202:205], v[88:91]
	v_mfma_f32_16x16x32_bf16 v[76:79], v[128:131], v[210:213], v[76:79]
	v_mfma_f32_16x16x32_bf16 v[72:75], v[136:139], v[210:213], v[72:75]
	v_mfma_f32_16x16x32_bf16 v[120:123], v[132:135], v[186:189], v[120:123]
	v_mfma_f32_16x16x32_bf16 v[124:127], v[140:143], v[186:189], v[124:127]
	v_mfma_f32_16x16x32_bf16 v[108:111], v[132:135], v[198:201], v[108:111]
	v_mfma_f32_16x16x32_bf16 v[104:107], v[140:143], v[198:201], v[104:107]
	v_mfma_f32_16x16x32_bf16 v[92:95], v[132:135], v[206:209], v[92:95]
	v_mfma_f32_16x16x32_bf16 v[88:91], v[140:143], v[206:209], v[88:91]
	v_mfma_f32_16x16x32_bf16 v[76:79], v[132:135], v[214:217], v[76:79]
	v_mfma_f32_16x16x32_bf16 v[72:75], v[140:143], v[214:217], v[72:75]
	v_mfma_f32_16x16x32_bf16 v[116:119], v[144:147], v[170:173], v[116:119]
	v_mfma_f32_16x16x32_bf16 v[112:115], v[152:155], v[170:173], v[112:115]
	v_mfma_f32_16x16x32_bf16 v[100:103], v[144:147], v[190:193], v[100:103]
	v_mfma_f32_16x16x32_bf16 v[96:99], v[152:155], v[190:193], v[96:99]
	v_mfma_f32_16x16x32_bf16 v[84:87], v[144:147], v[202:205], v[84:87]
	v_mfma_f32_16x16x32_bf16 v[80:83], v[152:155], v[202:205], v[80:83]
	v_mfma_f32_16x16x32_bf16 v[68:71], v[144:147], v[210:213], v[68:71]
	v_mfma_f32_16x16x32_bf16 v[64:67], v[152:155], v[210:213], v[64:67]
	v_mfma_f32_16x16x32_bf16 v[116:119], v[148:151], v[186:189], v[116:119]
	v_mfma_f32_16x16x32_bf16 v[112:115], v[166:169], v[186:189], v[112:115]
	v_mfma_f32_16x16x32_bf16 v[100:103], v[148:151], v[198:201], v[100:103]
	v_mfma_f32_16x16x32_bf16 v[96:99], v[166:169], v[198:201], v[96:99]
	v_mfma_f32_16x16x32_bf16 v[84:87], v[148:151], v[206:209], v[84:87]
	v_mfma_f32_16x16x32_bf16 v[80:83], v[166:169], v[206:209], v[80:83]
	v_mfma_f32_16x16x32_bf16 v[68:71], v[148:151], v[214:217], v[68:71]
	v_mfma_f32_16x16x32_bf16 v[64:67], v[166:169], v[214:217], v[64:67]
	s_barrier
	s_add_i32 s4, s45, s37
	v_lshl_add_u64 v[174:175], v[174:175], 0, s[14:15]
	s_mov_b32 m0, s4
	ds_read_b128 v[170:173], v197 offset:49152
	ds_read_b128 v[186:189], v197 offset:50176
	ds_read_b128 v[190:193], v197 offset:51200
	ds_read_b128 v[198:201], v197 offset:52224
	ds_read_b128 v[202:205], v197 offset:53248
	ds_read_b128 v[206:209], v197 offset:54272
	ds_read_b128 v[210:213], v197 offset:55296
	ds_read_b128 v[214:217], v197 offset:56320
	global_load_lds_dwordx4 v[174:175], off
	v_lshl_add_u64 v[174:175], v[222:223], 0, s[14:15]
	s_add_i32 m0, s4, 0x2000
	s_add_i32 s4, s54, s37
	global_load_lds_dwordx4 v[174:175], off
	v_lshl_add_u64 v[174:175], v[224:225], 0, s[14:15]
	s_mov_b32 m0, s4
	s_nop 0
	global_load_lds_dwordx4 v[174:175], off
	v_lshl_add_u64 v[174:175], v[226:227], 0, s[14:15]
	s_add_i32 m0, s4, 0x2000
	s_nop 0
	global_load_lds_dwordx4 v[174:175], off
	v_lshl_add_u64 v[174:175], v[228:229], 0, s[14:15]
	s_mov_b32 m0, s59
	s_nop 0
	global_load_lds_dwordx4 v[174:175], off
	v_lshl_add_u64 v[174:175], v[230:231], 0, s[14:15]
	s_mov_b32 m0, s60
	s_nop 0
	global_load_lds_dwordx4 v[174:175], off
	s_waitcnt vmcnt(8)
	s_waitcnt lgkmcnt(0)
	s_barrier
	s_waitcnt lgkmcnt(0)
	v_mfma_f32_16x16x32_bf16 v[60:63], v[128:131], v[170:173], v[60:63]
	v_mfma_f32_16x16x32_bf16 v[56:59], v[136:139], v[170:173], v[56:59]
	v_mfma_f32_16x16x32_bf16 v[44:47], v[128:131], v[190:193], v[44:47]
	v_mfma_f32_16x16x32_bf16 v[40:43], v[136:139], v[190:193], v[40:43]
	v_mfma_f32_16x16x32_bf16 v[28:31], v[128:131], v[202:205], v[28:31]
	v_mfma_f32_16x16x32_bf16 v[24:27], v[136:139], v[202:205], v[24:27]
	v_mfma_f32_16x16x32_bf16 v[12:15], v[128:131], v[210:213], v[12:15]
	v_mfma_f32_16x16x32_bf16 v[8:11], v[136:139], v[210:213], v[8:11]
	v_mfma_f32_16x16x32_bf16 v[60:63], v[132:135], v[186:189], v[60:63]
	v_mfma_f32_16x16x32_bf16 v[56:59], v[140:143], v[186:189], v[56:59]
	v_mfma_f32_16x16x32_bf16 v[44:47], v[132:135], v[198:201], v[44:47]
	v_mfma_f32_16x16x32_bf16 v[40:43], v[140:143], v[198:201], v[40:43]
	v_mfma_f32_16x16x32_bf16 v[28:31], v[132:135], v[206:209], v[28:31]
	v_mfma_f32_16x16x32_bf16 v[24:27], v[140:143], v[206:209], v[24:27]
	v_mfma_f32_16x16x32_bf16 v[12:15], v[132:135], v[214:217], v[12:15]
	v_mfma_f32_16x16x32_bf16 v[8:11], v[140:143], v[214:217], v[8:11]
	v_mfma_f32_16x16x32_bf16 v[52:55], v[144:147], v[170:173], v[52:55]
	v_mfma_f32_16x16x32_bf16 v[48:51], v[152:155], v[170:173], v[48:51]
	v_mfma_f32_16x16x32_bf16 v[36:39], v[144:147], v[190:193], v[36:39]
	v_mfma_f32_16x16x32_bf16 v[32:35], v[152:155], v[190:193], v[32:35]
	v_mfma_f32_16x16x32_bf16 v[20:23], v[144:147], v[202:205], v[20:23]
	v_mfma_f32_16x16x32_bf16 v[16:19], v[152:155], v[202:205], v[16:19]
	v_mfma_f32_16x16x32_bf16 v[4:7], v[144:147], v[210:213], v[4:7]
	v_mfma_f32_16x16x32_bf16 v[0:3], v[152:155], v[210:213], v[0:3]
	v_mfma_f32_16x16x32_bf16 v[52:55], v[148:151], v[186:189], v[52:55]
	v_mfma_f32_16x16x32_bf16 v[48:51], v[166:169], v[186:189], v[48:51]
	v_mfma_f32_16x16x32_bf16 v[36:39], v[148:151], v[198:201], v[36:39]
	v_mfma_f32_16x16x32_bf16 v[32:35], v[166:169], v[198:201], v[32:35]
	v_mfma_f32_16x16x32_bf16 v[20:23], v[148:151], v[206:209], v[20:23]
	v_mfma_f32_16x16x32_bf16 v[16:19], v[166:169], v[206:209], v[16:19]
	v_mfma_f32_16x16x32_bf16 v[4:7], v[148:151], v[214:217], v[4:7]
	v_mfma_f32_16x16x32_bf16 v[0:3], v[166:169], v[214:217], v[0:3]
	s_barrier
	s_add_u32 s28, s28, 0x100
	s_addc_u32 s29, s29, 0
	s_add_u32 s10, s10, 0x100
	s_addc_u32 s11, s11, 0
	s_cmp_ge_i32 s44, s58
	s_mov_b32 s30, s44
	s_cbranch_scc1 .Lpeelx_8

.LBB0_574:
	s_andn2_b64 vcc, exec, s[36:37]
	s_cbranch_vccnz .LBB0_577
	s_add_u32 s0, s0, 0x80
	s_addc_u32 s1, s1, 0
	s_add_u32 s38, s38, 0x100
	s_addc_u32 s39, s39, 0
	s_mov_b32 s16, 0
	s_cmp_lg_u32 s100, 0
	s_cbranch_scc0 .Llbb_5
	s_barrier
	s_mov_b32 s100, 0
.Llbb_5:
	s_add_i32 s44, s16, 2
	s_add_u32 s45, s0, 0x80
	s_addc_u32 s17, s1, 0
	s_add_i32 s64, 0, 0x10000
	s_cmp_eq_u32 s63, s16
	s_cselect_b32 s17, s57, s17
	s_cselect_b32 s16, s56, s45
	v_add_u32_e32 v152, s64, v153
	s_cselect_b32 s47, s9, s39
	s_cselect_b32 s46, s8, s38
	s_add_i32 s45, 0, 0x14000
	ds_read_b128 v[128:131], v152
	s_waitcnt vmcnt(0)
	ds_read_b128 v[158:161], v152 offset:1024
	ds_read_b128 v[162:165], v152 offset:2048
	ds_read_b128 v[166:169], v152 offset:3072
	v_add_u32_e32 v152, s45, v153
	ds_read_b128 v[170:173], v152
	ds_read_b128 v[174:177], v152 offset:1024
	ds_read_b128 v[194:197], v152 offset:2048
	ds_read_b128 v[206:209], v152 offset:3072
	v_lshl_add_u64 v[178:179], s[0:1], 0, v[148:149]
	s_add_i32 m0, s52, 0xc000
	ds_read_b128 v[210:213], v157
	ds_read_b128 v[214:217], v157 offset:1024
	ds_read_b128 v[220:223], v157 offset:2048
	ds_read_b128 v[224:227], v157 offset:3072
	ds_read_b128 v[228:231], v157 offset:4096
	ds_read_b128 v[232:235], v157 offset:5120
	ds_read_b128 v[236:239], v157 offset:6144
	ds_read_b128 v[240:243], v157 offset:7168
	global_load_lds_dwordx4 v[178:179], off
	v_lshl_add_u64 v[178:179], s[0:1], 0, v[150:151]
	s_add_i32 m0, s52, 0xe000
	s_nop 0
	global_load_lds_dwordx4 v[178:179], off
	s_waitcnt vmcnt(8)
	s_waitcnt lgkmcnt(0)
	s_barrier
	s_waitcnt lgkmcnt(0)
	v_mfma_f32_16x16x32_bf16 v[124:127], v[128:131], v[210:213], 0
	v_mfma_f32_16x16x32_bf16 v[120:123], v[162:165], v[210:213], 0
	v_mfma_f32_16x16x32_bf16 v[108:111], v[128:131], v[220:223], 0
	v_mfma_f32_16x16x32_bf16 v[104:107], v[162:165], v[220:223], 0
	v_mfma_f32_16x16x32_bf16 v[92:95], v[128:131], v[228:231], 0
	v_mfma_f32_16x16x32_bf16 v[88:91], v[162:165], v[228:231], 0
	v_mfma_f32_16x16x32_bf16 v[76:79], v[128:131], v[236:239], 0
	v_mfma_f32_16x16x32_bf16 v[72:75], v[162:165], v[236:239], 0
	v_mfma_f32_16x16x32_bf16 v[124:127], v[158:161], v[214:217], v[124:127]
	v_mfma_f32_16x16x32_bf16 v[120:123], v[166:169], v[214:217], v[120:123]
	v_mfma_f32_16x16x32_bf16 v[108:111], v[158:161], v[224:227], v[108:111]
	v_mfma_f32_16x16x32_bf16 v[104:107], v[166:169], v[224:227], v[104:107]
	v_mfma_f32_16x16x32_bf16 v[92:95], v[158:161], v[232:235], v[92:95]
	v_mfma_f32_16x16x32_bf16 v[88:91], v[166:169], v[232:235], v[88:91]
	v_mfma_f32_16x16x32_bf16 v[76:79], v[158:161], v[240:243], v[76:79]
	v_mfma_f32_16x16x32_bf16 v[72:75], v[166:169], v[240:243], v[72:75]
	v_mfma_f32_16x16x32_bf16 v[116:119], v[170:173], v[210:213], 0
	v_mfma_f32_16x16x32_bf16 v[112:115], v[194:197], v[210:213], 0
	v_mfma_f32_16x16x32_bf16 v[100:103], v[170:173], v[220:223], 0
	v_mfma_f32_16x16x32_bf16 v[96:99], v[194:197], v[220:223], 0
	v_mfma_f32_16x16x32_bf16 v[84:87], v[170:173], v[228:231], 0
	v_mfma_f32_16x16x32_bf16 v[80:83], v[194:197], v[228:231], 0
	v_mfma_f32_16x16x32_bf16 v[68:71], v[170:173], v[236:239], 0
	v_mfma_f32_16x16x32_bf16 v[64:67], v[194:197], v[236:239], 0
	v_mfma_f32_16x16x32_bf16 v[116:119], v[174:177], v[214:217], v[116:119]
	v_mfma_f32_16x16x32_bf16 v[112:115], v[206:209], v[214:217], v[112:115]
	v_mfma_f32_16x16x32_bf16 v[100:103], v[174:177], v[224:227], v[100:103]
	v_mfma_f32_16x16x32_bf16 v[96:99], v[206:209], v[224:227], v[96:99]
	v_mfma_f32_16x16x32_bf16 v[84:87], v[174:177], v[232:235], v[84:87]
	v_mfma_f32_16x16x32_bf16 v[80:83], v[206:209], v[232:235], v[80:83]
	v_mfma_f32_16x16x32_bf16 v[68:71], v[174:177], v[240:243], v[68:71]
	v_mfma_f32_16x16x32_bf16 v[64:67], v[206:209], v[240:243], v[64:67]
	s_barrier
	s_add_i32 s64, s64, s4
	v_lshl_add_u64 v[178:179], s[46:47], 0, v[134:135]
	s_mov_b32 m0, s64
	ds_read_b128 v[210:213], v157 offset:16384
	ds_read_b128 v[214:217], v157 offset:17408
	ds_read_b128 v[220:223], v157 offset:18432
	ds_read_b128 v[224:227], v157 offset:19456
	ds_read_b128 v[228:231], v157 offset:20480
	ds_read_b128 v[232:235], v157 offset:21504
	ds_read_b128 v[236:239], v157 offset:22528
	ds_read_b128 v[240:243], v157 offset:23552
	global_load_lds_dwordx4 v[178:179], off
	s_add_i32 m0, s64, 0x2000
	v_lshl_add_u64 v[198:199], s[46:47], 0, v[138:139]
	s_add_u32 s46, s46, s24
	s_addc_u32 s47, s47, s25
	s_add_i32 s45, s45, s4
	global_load_lds_dwordx4 v[198:199], off
	v_lshl_add_u64 v[244:245], s[46:47], 0, v[134:135]
	s_mov_b32 m0, s45
	v_lshl_add_u64 v[246:247], s[46:47], 0, v[138:139]
	global_load_lds_dwordx4 v[244:245], off
	s_add_i32 m0, s45, 0x2000
	v_lshl_add_u64 v[248:249], s[16:17], 0, v[132:133]
	global_load_lds_dwordx4 v[246:247], off
	s_mov_b32 m0, s52
	v_lshl_add_u64 v[250:251], s[16:17], 0, v[136:137]
	global_load_lds_dwordx4 v[248:249], off
	s_mov_b32 m0, s18
	s_nop 0
	global_load_lds_dwordx4 v[250:251], off
	s_waitcnt vmcnt(8)
	s_waitcnt lgkmcnt(0)
	s_barrier
	s_waitcnt lgkmcnt(0)
	v_mfma_f32_16x16x32_bf16 v[60:63], v[128:131], v[210:213], 0
	v_mfma_f32_16x16x32_bf16 v[56:59], v[162:165], v[210:213], 0
	v_mfma_f32_16x16x32_bf16 v[44:47], v[128:131], v[220:223], 0
	v_mfma_f32_16x16x32_bf16 v[40:43], v[162:165], v[220:223], 0
	v_mfma_f32_16x16x32_bf16 v[28:31], v[128:131], v[228:231], 0
	v_mfma_f32_16x16x32_bf16 v[24:27], v[162:165], v[228:231], 0
	v_mfma_f32_16x16x32_bf16 v[12:15], v[128:131], v[236:239], 0
	v_mfma_f32_16x16x32_bf16 v[8:11], v[162:165], v[236:239], 0
	v_mfma_f32_16x16x32_bf16 v[60:63], v[158:161], v[214:217], v[60:63]
	v_mfma_f32_16x16x32_bf16 v[56:59], v[166:169], v[214:217], v[56:59]
	v_mfma_f32_16x16x32_bf16 v[44:47], v[158:161], v[224:227], v[44:47]
	v_mfma_f32_16x16x32_bf16 v[40:43], v[166:169], v[224:227], v[40:43]
	v_mfma_f32_16x16x32_bf16 v[28:31], v[158:161], v[232:235], v[28:31]
	v_mfma_f32_16x16x32_bf16 v[24:27], v[166:169], v[232:235], v[24:27]
	v_mfma_f32_16x16x32_bf16 v[12:15], v[158:161], v[240:243], v[12:15]
	v_mfma_f32_16x16x32_bf16 v[8:11], v[166:169], v[240:243], v[8:11]
	v_mfma_f32_16x16x32_bf16 v[52:55], v[170:173], v[210:213], 0
	v_mfma_f32_16x16x32_bf16 v[48:51], v[194:197], v[210:213], 0
	v_mfma_f32_16x16x32_bf16 v[36:39], v[170:173], v[220:223], 0
	v_mfma_f32_16x16x32_bf16 v[32:35], v[194:197], v[220:223], 0
	v_mfma_f32_16x16x32_bf16 v[20:23], v[170:173], v[228:231], 0
	v_mfma_f32_16x16x32_bf16 v[16:19], v[194:197], v[228:231], 0
	v_mfma_f32_16x16x32_bf16 v[4:7], v[170:173], v[236:239], 0
	v_mfma_f32_16x16x32_bf16 v[0:3], v[194:197], v[236:239], 0
	v_mfma_f32_16x16x32_bf16 v[52:55], v[174:177], v[214:217], v[52:55]
	v_mfma_f32_16x16x32_bf16 v[48:51], v[206:209], v[214:217], v[48:51]
	v_mfma_f32_16x16x32_bf16 v[36:39], v[174:177], v[224:227], v[36:39]
	v_mfma_f32_16x16x32_bf16 v[32:35], v[206:209], v[224:227], v[32:35]
	v_mfma_f32_16x16x32_bf16 v[20:23], v[174:177], v[232:235], v[20:23]
	v_mfma_f32_16x16x32_bf16 v[16:19], v[206:209], v[232:235], v[16:19]
	v_mfma_f32_16x16x32_bf16 v[4:7], v[174:177], v[240:243], v[4:7]
	v_mfma_f32_16x16x32_bf16 v[0:3], v[206:209], v[240:243], v[0:3]
	s_barrier
	s_add_i32 s45, 0, 0x18000
	v_add_u32_e32 v152, s45, v153
	s_add_i32 s46, 0, 0x1c000
	ds_read_b128 v[128:131], v152
	ds_read_b128 v[158:161], v152 offset:1024
	ds_read_b128 v[162:165], v152 offset:2048
	ds_read_b128 v[166:169], v152 offset:3072
	v_add_u32_e32 v152, s46, v153
	ds_read_b128 v[170:173], v152
	ds_read_b128 v[174:177], v152 offset:1024
	ds_read_b128 v[194:197], v152 offset:2048
	ds_read_b128 v[206:209], v152 offset:3072
	s_add_u32 s16, s16, s24
	s_addc_u32 s17, s17, s25
	s_mov_b32 m0, s19
	v_lshl_add_u64 v[202:203], s[16:17], 0, v[132:133]
	ds_read_b128 v[210:213], v157 offset:32768
	ds_read_b128 v[214:217], v157 offset:33792
	ds_read_b128 v[220:223], v157 offset:34816
	ds_read_b128 v[224:227], v157 offset:35840
	ds_read_b128 v[228:231], v157 offset:36864
	ds_read_b128 v[232:235], v157 offset:37888
	ds_read_b128 v[236:239], v157 offset:38912
	ds_read_b128 v[240:243], v157 offset:39936
	global_load_lds_dwordx4 v[202:203], off
	v_lshl_add_u64 v[202:203], s[16:17], 0, v[136:137]
	s_mov_b32 m0, s33
	s_nop 0
	global_load_lds_dwordx4 v[202:203], off
	s_waitcnt vmcnt(8)
	s_waitcnt lgkmcnt(0)
	s_barrier
	s_waitcnt lgkmcnt(0)
	v_mfma_f32_16x16x32_bf16 v[124:127], v[128:131], v[210:213], v[124:127]
	v_mfma_f32_16x16x32_bf16 v[120:123], v[162:165], v[210:213], v[120:123]
	v_mfma_f32_16x16x32_bf16 v[108:111], v[128:131], v[220:223], v[108:111]
	v_mfma_f32_16x16x32_bf16 v[104:107], v[162:165], v[220:223], v[104:107]
	v_mfma_f32_16x16x32_bf16 v[92:95], v[128:131], v[228:231], v[92:95]
	v_mfma_f32_16x16x32_bf16 v[88:91], v[162:165], v[228:231], v[88:91]
	v_mfma_f32_16x16x32_bf16 v[76:79], v[128:131], v[236:239], v[76:79]
	v_mfma_f32_16x16x32_bf16 v[72:75], v[162:165], v[236:239], v[72:75]
	v_mfma_f32_16x16x32_bf16 v[124:127], v[158:161], v[214:217], v[124:127]
	v_mfma_f32_16x16x32_bf16 v[120:123], v[166:169], v[214:217], v[120:123]
	v_mfma_f32_16x16x32_bf16 v[108:111], v[158:161], v[224:227], v[108:111]
	v_mfma_f32_16x16x32_bf16 v[104:107], v[166:169], v[224:227], v[104:107]
	v_mfma_f32_16x16x32_bf16 v[92:95], v[158:161], v[232:235], v[92:95]
	v_mfma_f32_16x16x32_bf16 v[88:91], v[166:169], v[232:235], v[88:91]
	v_mfma_f32_16x16x32_bf16 v[76:79], v[158:161], v[240:243], v[76:79]
	v_mfma_f32_16x16x32_bf16 v[72:75], v[166:169], v[240:243], v[72:75]
	v_mfma_f32_16x16x32_bf16 v[116:119], v[170:173], v[210:213], v[116:119]
	v_mfma_f32_16x16x32_bf16 v[112:115], v[194:197], v[210:213], v[112:115]
	v_mfma_f32_16x16x32_bf16 v[100:103], v[170:173], v[220:223], v[100:103]
	v_mfma_f32_16x16x32_bf16 v[96:99], v[194:197], v[220:223], v[96:99]
	v_mfma_f32_16x16x32_bf16 v[84:87], v[170:173], v[228:231], v[84:87]
	v_mfma_f32_16x16x32_bf16 v[80:83], v[194:197], v[228:231], v[80:83]
	v_mfma_f32_16x16x32_bf16 v[68:71], v[170:173], v[236:239], v[68:71]
	v_mfma_f32_16x16x32_bf16 v[64:67], v[194:197], v[236:239], v[64:67]
	v_mfma_f32_16x16x32_bf16 v[116:119], v[174:177], v[214:217], v[116:119]
	v_mfma_f32_16x16x32_bf16 v[112:115], v[206:209], v[214:217], v[112:115]
	v_mfma_f32_16x16x32_bf16 v[100:103], v[174:177], v[224:227], v[100:103]
	v_mfma_f32_16x16x32_bf16 v[96:99], v[206:209], v[224:227], v[96:99]
	v_mfma_f32_16x16x32_bf16 v[84:87], v[174:177], v[232:235], v[84:87]
	v_mfma_f32_16x16x32_bf16 v[80:83], v[206:209], v[232:235], v[80:83]
	v_mfma_f32_16x16x32_bf16 v[68:71], v[174:177], v[240:243], v[68:71]
	v_mfma_f32_16x16x32_bf16 v[64:67], v[206:209], v[240:243], v[64:67]
	s_barrier
	s_add_i32 s16, s45, s4
	v_lshl_add_u64 v[178:179], v[178:179], 0, s[12:13]
	s_mov_b32 m0, s16
	ds_read_b128 v[210:213], v157 offset:49152
	ds_read_b128 v[214:217], v157 offset:50176
	ds_read_b128 v[220:223], v157 offset:51200
	ds_read_b128 v[224:227], v157 offset:52224
	ds_read_b128 v[228:231], v157 offset:53248
	ds_read_b128 v[232:235], v157 offset:54272
	ds_read_b128 v[236:239], v157 offset:55296
	ds_read_b128 v[240:243], v157 offset:56320
	global_load_lds_dwordx4 v[178:179], off
	v_lshl_add_u64 v[178:179], v[198:199], 0, s[12:13]
	s_add_i32 m0, s16, 0x2000
	s_add_i32 s16, s46, s4
	global_load_lds_dwordx4 v[178:179], off
	v_lshl_add_u64 v[178:179], v[244:245], 0, s[12:13]
	s_mov_b32 m0, s16
	s_nop 0
	global_load_lds_dwordx4 v[178:179], off
	v_lshl_add_u64 v[178:179], v[246:247], 0, s[12:13]
	s_add_i32 m0, s16, 0x2000
	s_nop 0
	global_load_lds_dwordx4 v[178:179], off
	v_lshl_add_u64 v[178:179], v[248:249], 0, s[12:13]
	s_mov_b32 m0, s59
	s_nop 0
	global_load_lds_dwordx4 v[178:179], off
	v_lshl_add_u64 v[178:179], v[250:251], 0, s[12:13]
	s_mov_b32 m0, s60
	s_nop 0
	global_load_lds_dwordx4 v[178:179], off
	s_waitcnt vmcnt(8)
	s_waitcnt lgkmcnt(0)
	s_barrier
	s_waitcnt lgkmcnt(0)
	v_mfma_f32_16x16x32_bf16 v[60:63], v[128:131], v[210:213], v[60:63]
	v_mfma_f32_16x16x32_bf16 v[56:59], v[162:165], v[210:213], v[56:59]
	v_mfma_f32_16x16x32_bf16 v[44:47], v[128:131], v[220:223], v[44:47]
	v_mfma_f32_16x16x32_bf16 v[40:43], v[162:165], v[220:223], v[40:43]
	v_mfma_f32_16x16x32_bf16 v[28:31], v[128:131], v[228:231], v[28:31]
	v_mfma_f32_16x16x32_bf16 v[24:27], v[162:165], v[228:231], v[24:27]
	v_mfma_f32_16x16x32_bf16 v[12:15], v[128:131], v[236:239], v[12:15]
	v_mfma_f32_16x16x32_bf16 v[8:11], v[162:165], v[236:239], v[8:11]
	v_mfma_f32_16x16x32_bf16 v[60:63], v[158:161], v[214:217], v[60:63]
	v_mfma_f32_16x16x32_bf16 v[56:59], v[166:169], v[214:217], v[56:59]
	v_mfma_f32_16x16x32_bf16 v[44:47], v[158:161], v[224:227], v[44:47]
	v_mfma_f32_16x16x32_bf16 v[40:43], v[166:169], v[224:227], v[40:43]
	v_mfma_f32_16x16x32_bf16 v[28:31], v[158:161], v[232:235], v[28:31]
	v_mfma_f32_16x16x32_bf16 v[24:27], v[166:169], v[232:235], v[24:27]
	v_mfma_f32_16x16x32_bf16 v[12:15], v[158:161], v[240:243], v[12:15]
	v_mfma_f32_16x16x32_bf16 v[8:11], v[166:169], v[240:243], v[8:11]
	v_mfma_f32_16x16x32_bf16 v[52:55], v[170:173], v[210:213], v[52:55]
	v_mfma_f32_16x16x32_bf16 v[48:51], v[194:197], v[210:213], v[48:51]
	v_mfma_f32_16x16x32_bf16 v[36:39], v[170:173], v[220:223], v[36:39]
	v_mfma_f32_16x16x32_bf16 v[32:35], v[194:197], v[220:223], v[32:35]
	v_mfma_f32_16x16x32_bf16 v[20:23], v[170:173], v[228:231], v[20:23]
	v_mfma_f32_16x16x32_bf16 v[16:19], v[194:197], v[228:231], v[16:19]
	v_mfma_f32_16x16x32_bf16 v[4:7], v[170:173], v[236:239], v[4:7]
	v_mfma_f32_16x16x32_bf16 v[0:3], v[194:197], v[236:239], v[0:3]
	v_mfma_f32_16x16x32_bf16 v[52:55], v[174:177], v[214:217], v[52:55]
	v_mfma_f32_16x16x32_bf16 v[48:51], v[206:209], v[214:217], v[48:51]
	v_mfma_f32_16x16x32_bf16 v[36:39], v[174:177], v[224:227], v[36:39]
	v_mfma_f32_16x16x32_bf16 v[32:35], v[206:209], v[224:227], v[32:35]
	v_mfma_f32_16x16x32_bf16 v[20:23], v[174:177], v[232:235], v[20:23]
	v_mfma_f32_16x16x32_bf16 v[16:19], v[206:209], v[232:235], v[16:19]
	v_mfma_f32_16x16x32_bf16 v[4:7], v[174:177], v[240:243], v[4:7]
	v_mfma_f32_16x16x32_bf16 v[0:3], v[206:209], v[240:243], v[0:3]
	s_barrier
	s_add_u32 s0, s0, 0x100
	s_addc_u32 s1, s1, 0
	s_add_u32 s38, s38, 0x100
	s_addc_u32 s39, s39, 0
	s_cmp_ge_i32 s44, s68
	s_mov_b32 s16, s44
	s_cbranch_scc1 .Lpeelx_9

.Lpeelx_9:
.LBB0_577:
	s_and_b64 vcc, exec, s[6:7]
	s_cbranch_vccz .LBB0_579
	s_barrier

.LBB0_796:
	s_andn2_b64 vcc, exec, s[20:21]
	s_cbranch_vccnz .LBB0_799
	s_add_u32 s28, s16, 0x80
	s_addc_u32 s29, s17, 0
	s_add_u32 s10, s30, 0x100
	s_addc_u32 s11, s31, 0
	s_mov_b32 s16, 0
	s_cmp_lg_u32 s100, 0
	s_cbranch_scc0 .Llbb_6
	s_barrier
	s_mov_b32 s100, 0
.Llbb_6:
	s_add_i32 s30, s16, 2
	s_add_u32 s31, s28, 0x80
	s_addc_u32 s17, s29, 0
	s_add_i32 s59, 0, 0x10000
	s_cmp_eq_u32 s48, s16
	s_cselect_b32 s17, s25, s17
	s_cselect_b32 s16, s24, s31
	v_add_u32_e32 v140, s59, v143
	s_cselect_b32 s43, s27, s11
	s_cselect_b32 s42, s26, s10
	s_add_i32 s31, 0, 0x14000
	ds_read_b128 v[146:149], v140
	ds_read_b128 v[150:153], v140 offset:1024
	ds_read_b128 v[154:157], v140 offset:2048
	s_waitcnt vmcnt(0)
	ds_read_b128 v[158:161], v140 offset:3072
	v_add_u32_e32 v140, s31, v143
	ds_read_b128 v[162:165], v140
	ds_read_b128 v[166:169], v140 offset:1024
	ds_read_b128 v[170:173], v140 offset:2048
	ds_read_b128 v[174:177], v140 offset:3072
	v_lshl_add_u64 v[178:179], s[28:29], 0, v[136:137]
	s_add_i32 m0, s37, 0xc000
	ds_read_b128 v[194:197], v145
	ds_read_b128 v[206:209], v145 offset:1024
	ds_read_b128 v[210:213], v145 offset:2048
	ds_read_b128 v[214:217], v145 offset:3072
	ds_read_b128 v[220:223], v145 offset:4096
	ds_read_b128 v[224:227], v145 offset:5120
	ds_read_b128 v[228:231], v145 offset:6144
	ds_read_b128 v[232:235], v145 offset:7168
	global_load_lds_dwordx4 v[178:179], off
	v_lshl_add_u64 v[178:179], s[28:29], 0, v[138:139]
	s_add_i32 m0, s37, 0xe000
	s_nop 0
	global_load_lds_dwordx4 v[178:179], off
	s_waitcnt vmcnt(8)
	s_waitcnt lgkmcnt(0)
	s_barrier
	s_waitcnt lgkmcnt(0)
	v_mfma_f32_16x16x32_bf16 v[124:127], v[146:149], v[194:197], 0
	v_mfma_f32_16x16x32_bf16 v[120:123], v[154:157], v[194:197], 0
	v_mfma_f32_16x16x32_bf16 v[108:111], v[146:149], v[210:213], 0
	v_mfma_f32_16x16x32_bf16 v[104:107], v[154:157], v[210:213], 0
	v_mfma_f32_16x16x32_bf16 v[92:95], v[146:149], v[220:223], 0
	v_mfma_f32_16x16x32_bf16 v[88:91], v[154:157], v[220:223], 0
	v_mfma_f32_16x16x32_bf16 v[76:79], v[146:149], v[228:231], 0
	v_mfma_f32_16x16x32_bf16 v[72:75], v[154:157], v[228:231], 0
	v_mfma_f32_16x16x32_bf16 v[124:127], v[150:153], v[206:209], v[124:127]
	v_mfma_f32_16x16x32_bf16 v[120:123], v[158:161], v[206:209], v[120:123]
	v_mfma_f32_16x16x32_bf16 v[108:111], v[150:153], v[214:217], v[108:111]
	v_mfma_f32_16x16x32_bf16 v[104:107], v[158:161], v[214:217], v[104:107]
	v_mfma_f32_16x16x32_bf16 v[92:95], v[150:153], v[224:227], v[92:95]
	v_mfma_f32_16x16x32_bf16 v[88:91], v[158:161], v[224:227], v[88:91]
	v_mfma_f32_16x16x32_bf16 v[76:79], v[150:153], v[232:235], v[76:79]
	v_mfma_f32_16x16x32_bf16 v[72:75], v[158:161], v[232:235], v[72:75]
	v_mfma_f32_16x16x32_bf16 v[116:119], v[162:165], v[194:197], 0
	v_mfma_f32_16x16x32_bf16 v[112:115], v[170:173], v[194:197], 0
	v_mfma_f32_16x16x32_bf16 v[100:103], v[162:165], v[210:213], 0
	v_mfma_f32_16x16x32_bf16 v[96:99], v[170:173], v[210:213], 0
	v_mfma_f32_16x16x32_bf16 v[84:87], v[162:165], v[220:223], 0
	v_mfma_f32_16x16x32_bf16 v[80:83], v[170:173], v[220:223], 0
	v_mfma_f32_16x16x32_bf16 v[68:71], v[162:165], v[228:231], 0
	v_mfma_f32_16x16x32_bf16 v[64:67], v[170:173], v[228:231], 0
	v_mfma_f32_16x16x32_bf16 v[116:119], v[166:169], v[206:209], v[116:119]
	v_mfma_f32_16x16x32_bf16 v[112:115], v[174:177], v[206:209], v[112:115]
	v_mfma_f32_16x16x32_bf16 v[100:103], v[166:169], v[214:217], v[100:103]
	v_mfma_f32_16x16x32_bf16 v[96:99], v[174:177], v[214:217], v[96:99]
	v_mfma_f32_16x16x32_bf16 v[84:87], v[166:169], v[224:227], v[84:87]
	v_mfma_f32_16x16x32_bf16 v[80:83], v[174:177], v[224:227], v[80:83]
	v_mfma_f32_16x16x32_bf16 v[68:71], v[166:169], v[232:235], v[68:71]
	v_mfma_f32_16x16x32_bf16 v[64:67], v[174:177], v[232:235], v[64:67]
	s_barrier
	s_add_i32 s59, s59, s36
	v_lshl_add_u64 v[178:179], s[42:43], 0, v[132:133]
	s_mov_b32 m0, s59
	ds_read_b128 v[194:197], v145 offset:16384
	ds_read_b128 v[206:209], v145 offset:17408
	ds_read_b128 v[210:213], v145 offset:18432
	ds_read_b128 v[214:217], v145 offset:19456
	ds_read_b128 v[220:223], v145 offset:20480
	ds_read_b128 v[224:227], v145 offset:21504
	ds_read_b128 v[228:231], v145 offset:22528
	ds_read_b128 v[232:235], v145 offset:23552
	global_load_lds_dwordx4 v[178:179], off
	s_add_i32 m0, s59, 0x2000
	v_lshl_add_u64 v[198:199], s[42:43], 0, v[128:129]
	s_add_u32 s42, s42, s0
	s_addc_u32 s43, s43, s1
	s_add_i32 s31, s31, s36
	global_load_lds_dwordx4 v[198:199], off
	v_lshl_add_u64 v[202:203], s[42:43], 0, v[132:133]
	s_mov_b32 m0, s31
	v_lshl_add_u64 v[236:237], s[42:43], 0, v[128:129]
	global_load_lds_dwordx4 v[202:203], off
	s_add_i32 m0, s31, 0x2000
	v_lshl_add_u64 v[238:239], s[16:17], 0, v[134:135]
	global_load_lds_dwordx4 v[236:237], off
	s_mov_b32 m0, s37
	v_lshl_add_u64 v[240:241], s[16:17], 0, v[130:131]
	global_load_lds_dwordx4 v[238:239], off
	s_mov_b32 m0, s38
	s_nop 0
	global_load_lds_dwordx4 v[240:241], off
	s_waitcnt vmcnt(8)
	s_waitcnt lgkmcnt(0)
	s_barrier
	s_waitcnt lgkmcnt(0)
	v_mfma_f32_16x16x32_bf16 v[60:63], v[146:149], v[194:197], 0
	v_mfma_f32_16x16x32_bf16 v[56:59], v[154:157], v[194:197], 0
	v_mfma_f32_16x16x32_bf16 v[44:47], v[146:149], v[210:213], 0
	v_mfma_f32_16x16x32_bf16 v[40:43], v[154:157], v[210:213], 0
	v_mfma_f32_16x16x32_bf16 v[28:31], v[146:149], v[220:223], 0
	v_mfma_f32_16x16x32_bf16 v[24:27], v[154:157], v[220:223], 0
	v_mfma_f32_16x16x32_bf16 v[12:15], v[146:149], v[228:231], 0
	v_mfma_f32_16x16x32_bf16 v[8:11], v[154:157], v[228:231], 0
	v_mfma_f32_16x16x32_bf16 v[60:63], v[150:153], v[206:209], v[60:63]
	v_mfma_f32_16x16x32_bf16 v[56:59], v[158:161], v[206:209], v[56:59]
	v_mfma_f32_16x16x32_bf16 v[44:47], v[150:153], v[214:217], v[44:47]
	v_mfma_f32_16x16x32_bf16 v[40:43], v[158:161], v[214:217], v[40:43]
	v_mfma_f32_16x16x32_bf16 v[28:31], v[150:153], v[224:227], v[28:31]
	v_mfma_f32_16x16x32_bf16 v[24:27], v[158:161], v[224:227], v[24:27]
	v_mfma_f32_16x16x32_bf16 v[12:15], v[150:153], v[232:235], v[12:15]
	v_mfma_f32_16x16x32_bf16 v[8:11], v[158:161], v[232:235], v[8:11]
	v_mfma_f32_16x16x32_bf16 v[52:55], v[162:165], v[194:197], 0
	v_mfma_f32_16x16x32_bf16 v[48:51], v[170:173], v[194:197], 0
	v_mfma_f32_16x16x32_bf16 v[36:39], v[162:165], v[210:213], 0
	v_mfma_f32_16x16x32_bf16 v[32:35], v[170:173], v[210:213], 0
	v_mfma_f32_16x16x32_bf16 v[20:23], v[162:165], v[220:223], 0
	v_mfma_f32_16x16x32_bf16 v[16:19], v[170:173], v[220:223], 0
	v_mfma_f32_16x16x32_bf16 v[4:7], v[162:165], v[228:231], 0
	v_mfma_f32_16x16x32_bf16 v[0:3], v[170:173], v[228:231], 0
	v_mfma_f32_16x16x32_bf16 v[52:55], v[166:169], v[206:209], v[52:55]
	v_mfma_f32_16x16x32_bf16 v[48:51], v[174:177], v[206:209], v[48:51]
	v_mfma_f32_16x16x32_bf16 v[36:39], v[166:169], v[214:217], v[36:39]
	v_mfma_f32_16x16x32_bf16 v[32:35], v[174:177], v[214:217], v[32:35]
	v_mfma_f32_16x16x32_bf16 v[20:23], v[166:169], v[224:227], v[20:23]
	v_mfma_f32_16x16x32_bf16 v[16:19], v[174:177], v[224:227], v[16:19]
	v_mfma_f32_16x16x32_bf16 v[4:7], v[166:169], v[232:235], v[4:7]
	v_mfma_f32_16x16x32_bf16 v[0:3], v[174:177], v[232:235], v[0:3]
	s_barrier
	s_add_i32 s31, 0, 0x18000
	v_add_u32_e32 v140, s31, v143
	s_add_i32 s42, 0, 0x1c000
	ds_read_b128 v[146:149], v140
	ds_read_b128 v[150:153], v140 offset:1024
	ds_read_b128 v[154:157], v140 offset:2048
	ds_read_b128 v[158:161], v140 offset:3072
	v_add_u32_e32 v140, s42, v143
	ds_read_b128 v[162:165], v140
	ds_read_b128 v[166:169], v140 offset:1024
	ds_read_b128 v[170:173], v140 offset:2048
	ds_read_b128 v[174:177], v140 offset:3072
	s_add_u32 s16, s16, s0
	s_addc_u32 s17, s17, s1
	s_mov_b32 m0, s39
	v_lshl_add_u64 v[242:243], s[16:17], 0, v[134:135]
	ds_read_b128 v[194:197], v145 offset:32768
	ds_read_b128 v[206:209], v145 offset:33792
	ds_read_b128 v[210:213], v145 offset:34816
	ds_read_b128 v[214:217], v145 offset:35840
	ds_read_b128 v[220:223], v145 offset:36864
	ds_read_b128 v[224:227], v145 offset:37888
	ds_read_b128 v[228:231], v145 offset:38912
	ds_read_b128 v[232:235], v145 offset:39936
	global_load_lds_dwordx4 v[242:243], off
	v_lshl_add_u64 v[242:243], s[16:17], 0, v[130:131]
	s_mov_b32 m0, s44
	s_nop 0
	global_load_lds_dwordx4 v[242:243], off
	s_waitcnt vmcnt(8)
	s_waitcnt lgkmcnt(0)
	s_barrier
	s_waitcnt lgkmcnt(0)
	v_mfma_f32_16x16x32_bf16 v[124:127], v[146:149], v[194:197], v[124:127]
	v_mfma_f32_16x16x32_bf16 v[120:123], v[154:157], v[194:197], v[120:123]
	v_mfma_f32_16x16x32_bf16 v[108:111], v[146:149], v[210:213], v[108:111]
	v_mfma_f32_16x16x32_bf16 v[104:107], v[154:157], v[210:213], v[104:107]
	v_mfma_f32_16x16x32_bf16 v[92:95], v[146:149], v[220:223], v[92:95]
	v_mfma_f32_16x16x32_bf16 v[88:91], v[154:157], v[220:223], v[88:91]
	v_mfma_f32_16x16x32_bf16 v[76:79], v[146:149], v[228:231], v[76:79]
	v_mfma_f32_16x16x32_bf16 v[72:75], v[154:157], v[228:231], v[72:75]
	v_mfma_f32_16x16x32_bf16 v[124:127], v[150:153], v[206:209], v[124:127]
	v_mfma_f32_16x16x32_bf16 v[120:123], v[158:161], v[206:209], v[120:123]
	v_mfma_f32_16x16x32_bf16 v[108:111], v[150:153], v[214:217], v[108:111]
	v_mfma_f32_16x16x32_bf16 v[104:107], v[158:161], v[214:217], v[104:107]
	v_mfma_f32_16x16x32_bf16 v[92:95], v[150:153], v[224:227], v[92:95]
	v_mfma_f32_16x16x32_bf16 v[88:91], v[158:161], v[224:227], v[88:91]
	v_mfma_f32_16x16x32_bf16 v[76:79], v[150:153], v[232:235], v[76:79]
	v_mfma_f32_16x16x32_bf16 v[72:75], v[158:161], v[232:235], v[72:75]
	v_mfma_f32_16x16x32_bf16 v[116:119], v[162:165], v[194:197], v[116:119]
	v_mfma_f32_16x16x32_bf16 v[112:115], v[170:173], v[194:197], v[112:115]
	v_mfma_f32_16x16x32_bf16 v[100:103], v[162:165], v[210:213], v[100:103]
	v_mfma_f32_16x16x32_bf16 v[96:99], v[170:173], v[210:213], v[96:99]
	v_mfma_f32_16x16x32_bf16 v[84:87], v[162:165], v[220:223], v[84:87]
	v_mfma_f32_16x16x32_bf16 v[80:83], v[170:173], v[220:223], v[80:83]
	v_mfma_f32_16x16x32_bf16 v[68:71], v[162:165], v[228:231], v[68:71]
	v_mfma_f32_16x16x32_bf16 v[64:67], v[170:173], v[228:231], v[64:67]
	v_mfma_f32_16x16x32_bf16 v[116:119], v[166:169], v[206:209], v[116:119]
	v_mfma_f32_16x16x32_bf16 v[112:115], v[174:177], v[206:209], v[112:115]
	v_mfma_f32_16x16x32_bf16 v[100:103], v[166:169], v[214:217], v[100:103]
	v_mfma_f32_16x16x32_bf16 v[96:99], v[174:177], v[214:217], v[96:99]
	v_mfma_f32_16x16x32_bf16 v[84:87], v[166:169], v[224:227], v[84:87]
	v_mfma_f32_16x16x32_bf16 v[80:83], v[174:177], v[224:227], v[80:83]
	v_mfma_f32_16x16x32_bf16 v[68:71], v[166:169], v[232:235], v[68:71]
	v_mfma_f32_16x16x32_bf16 v[64:67], v[174:177], v[232:235], v[64:67]
	s_barrier
	s_add_i32 s16, s31, s36
	v_lshl_add_u64 v[178:179], v[178:179], 0, s[12:13]
	s_mov_b32 m0, s16
	ds_read_b128 v[194:197], v145 offset:49152
	ds_read_b128 v[206:209], v145 offset:50176
	ds_read_b128 v[210:213], v145 offset:51200
	ds_read_b128 v[214:217], v145 offset:52224
	ds_read_b128 v[220:223], v145 offset:53248
	ds_read_b128 v[224:227], v145 offset:54272
	ds_read_b128 v[228:231], v145 offset:55296
	ds_read_b128 v[232:235], v145 offset:56320
	global_load_lds_dwordx4 v[178:179], off
	v_lshl_add_u64 v[178:179], v[198:199], 0, s[12:13]
	s_add_i32 m0, s16, 0x2000
	s_add_i32 s16, s42, s36
	global_load_lds_dwordx4 v[178:179], off
	v_lshl_add_u64 v[178:179], v[202:203], 0, s[12:13]
	s_mov_b32 m0, s16
	s_nop 0
	global_load_lds_dwordx4 v[178:179], off
	v_lshl_add_u64 v[178:179], v[236:237], 0, s[12:13]
	s_add_i32 m0, s16, 0x2000
	s_nop 0
	global_load_lds_dwordx4 v[178:179], off
	v_lshl_add_u64 v[178:179], v[238:239], 0, s[12:13]
	s_mov_b32 m0, s45
	s_nop 0
	global_load_lds_dwordx4 v[178:179], off
	v_lshl_add_u64 v[178:179], v[240:241], 0, s[12:13]
	s_mov_b32 m0, s46
	s_nop 0
	global_load_lds_dwordx4 v[178:179], off
	s_waitcnt vmcnt(8)
	s_waitcnt lgkmcnt(0)
	s_barrier
	s_waitcnt lgkmcnt(0)
	v_mfma_f32_16x16x32_bf16 v[60:63], v[146:149], v[194:197], v[60:63]
	v_mfma_f32_16x16x32_bf16 v[56:59], v[154:157], v[194:197], v[56:59]
	v_mfma_f32_16x16x32_bf16 v[44:47], v[146:149], v[210:213], v[44:47]
	v_mfma_f32_16x16x32_bf16 v[40:43], v[154:157], v[210:213], v[40:43]
	v_mfma_f32_16x16x32_bf16 v[28:31], v[146:149], v[220:223], v[28:31]
	v_mfma_f32_16x16x32_bf16 v[24:27], v[154:157], v[220:223], v[24:27]
	v_mfma_f32_16x16x32_bf16 v[12:15], v[146:149], v[228:231], v[12:15]
	v_mfma_f32_16x16x32_bf16 v[8:11], v[154:157], v[228:231], v[8:11]
	v_mfma_f32_16x16x32_bf16 v[60:63], v[150:153], v[206:209], v[60:63]
	v_mfma_f32_16x16x32_bf16 v[56:59], v[158:161], v[206:209], v[56:59]
	v_mfma_f32_16x16x32_bf16 v[44:47], v[150:153], v[214:217], v[44:47]
	v_mfma_f32_16x16x32_bf16 v[40:43], v[158:161], v[214:217], v[40:43]
	v_mfma_f32_16x16x32_bf16 v[28:31], v[150:153], v[224:227], v[28:31]
	v_mfma_f32_16x16x32_bf16 v[24:27], v[158:161], v[224:227], v[24:27]
	v_mfma_f32_16x16x32_bf16 v[12:15], v[150:153], v[232:235], v[12:15]
	v_mfma_f32_16x16x32_bf16 v[8:11], v[158:161], v[232:235], v[8:11]
	v_mfma_f32_16x16x32_bf16 v[52:55], v[162:165], v[194:197], v[52:55]
	v_mfma_f32_16x16x32_bf16 v[48:51], v[170:173], v[194:197], v[48:51]
	v_mfma_f32_16x16x32_bf16 v[36:39], v[162:165], v[210:213], v[36:39]
	v_mfma_f32_16x16x32_bf16 v[32:35], v[170:173], v[210:213], v[32:35]
	v_mfma_f32_16x16x32_bf16 v[20:23], v[162:165], v[220:223], v[20:23]
	v_mfma_f32_16x16x32_bf16 v[16:19], v[170:173], v[220:223], v[16:19]
	v_mfma_f32_16x16x32_bf16 v[4:7], v[162:165], v[228:231], v[4:7]
	v_mfma_f32_16x16x32_bf16 v[0:3], v[170:173], v[228:231], v[0:3]
	v_mfma_f32_16x16x32_bf16 v[52:55], v[166:169], v[206:209], v[52:55]
	v_mfma_f32_16x16x32_bf16 v[48:51], v[174:177], v[206:209], v[48:51]
	v_mfma_f32_16x16x32_bf16 v[36:39], v[166:169], v[214:217], v[36:39]
	v_mfma_f32_16x16x32_bf16 v[32:35], v[174:177], v[214:217], v[32:35]
	v_mfma_f32_16x16x32_bf16 v[20:23], v[166:169], v[224:227], v[20:23]
	v_mfma_f32_16x16x32_bf16 v[16:19], v[174:177], v[224:227], v[16:19]
	v_mfma_f32_16x16x32_bf16 v[4:7], v[166:169], v[232:235], v[4:7]
	v_mfma_f32_16x16x32_bf16 v[0:3], v[174:177], v[232:235], v[0:3]
	s_barrier
	s_add_u32 s28, s28, 0x100
	s_addc_u32 s29, s29, 0
	s_add_u32 s10, s10, 0x100
	s_addc_u32 s11, s11, 0
	s_cmp_ge_i32 s30, s47
	s_mov_b32 s16, s30
	s_cbranch_scc1 .Lpeelx_10

.LBB0_821:
	s_andn2_b64 vcc, exec, s[18:19]
	s_cbranch_vccnz .LBB0_824
	s_add_u32 s26, s26, 0x80
	s_addc_u32 s27, s27, 0
	s_add_u32 s10, s28, 0x100
	s_addc_u32 s11, s29, 0
	s_mov_b32 s16, 0
	s_cmp_lg_u32 s100, 0
	s_cbranch_scc0 .Llbb_7
	s_barrier
	s_mov_b32 s100, 0
.Llbb_7:
	s_add_i32 s28, s16, 2
	s_add_u32 s29, s26, 0x80
	s_addc_u32 s17, s27, 0
	s_add_i32 s59, 0, 0x10000
	s_cmp_eq_u32 s48, s16
	s_cselect_b32 s17, s23, s17
	s_cselect_b32 s16, s22, s29
	v_add_u32_e32 v140, s59, v143
	s_cselect_b32 s43, s25, s11
	s_cselect_b32 s42, s24, s10
	s_add_i32 s29, 0, 0x14000
	ds_read_b128 v[146:149], v140
	ds_read_b128 v[150:153], v140 offset:1024
	ds_read_b128 v[154:157], v140 offset:2048
	s_waitcnt vmcnt(0)
	ds_read_b128 v[158:161], v140 offset:3072
	v_add_u32_e32 v140, s29, v143
	ds_read_b128 v[162:165], v140
	ds_read_b128 v[166:169], v140 offset:1024
	ds_read_b128 v[170:173], v140 offset:2048
	ds_read_b128 v[174:177], v140 offset:3072
	v_lshl_add_u64 v[140:141], s[26:27], 0, v[136:137]
	s_add_i32 m0, s35, 0xc000
	ds_read_b128 v[194:197], v145
	ds_read_b128 v[206:209], v145 offset:1024
	ds_read_b128 v[210:213], v145 offset:2048
	ds_read_b128 v[214:217], v145 offset:3072
	ds_read_b128 v[220:223], v145 offset:4096
	ds_read_b128 v[224:227], v145 offset:5120
	ds_read_b128 v[228:231], v145 offset:6144
	ds_read_b128 v[232:235], v145 offset:7168
	global_load_lds_dwordx4 v[140:141], off
	v_lshl_add_u64 v[140:141], s[26:27], 0, v[138:139]
	s_add_i32 m0, s35, 0xe000
	s_nop 0
	global_load_lds_dwordx4 v[140:141], off
	s_waitcnt vmcnt(8)
	s_waitcnt lgkmcnt(0)
	s_barrier
	s_waitcnt lgkmcnt(0)
	v_mfma_f32_16x16x32_bf16 v[120:123], v[146:149], v[194:197], 0
	v_mfma_f32_16x16x32_bf16 v[124:127], v[154:157], v[194:197], 0
	v_mfma_f32_16x16x32_bf16 v[116:119], v[146:149], v[210:213], 0
	v_mfma_f32_16x16x32_bf16 v[112:115], v[154:157], v[210:213], 0
	v_mfma_f32_16x16x32_bf16 v[108:111], v[146:149], v[220:223], 0
	v_mfma_f32_16x16x32_bf16 v[104:107], v[154:157], v[220:223], 0
	v_mfma_f32_16x16x32_bf16 v[100:103], v[146:149], v[228:231], 0
	v_mfma_f32_16x16x32_bf16 v[96:99], v[154:157], v[228:231], 0
	v_mfma_f32_16x16x32_bf16 v[120:123], v[150:153], v[206:209], v[120:123]
	v_mfma_f32_16x16x32_bf16 v[124:127], v[158:161], v[206:209], v[124:127]
	v_mfma_f32_16x16x32_bf16 v[116:119], v[150:153], v[214:217], v[116:119]
	v_mfma_f32_16x16x32_bf16 v[112:115], v[158:161], v[214:217], v[112:115]
	v_mfma_f32_16x16x32_bf16 v[108:111], v[150:153], v[224:227], v[108:111]
	v_mfma_f32_16x16x32_bf16 v[104:107], v[158:161], v[224:227], v[104:107]
	v_mfma_f32_16x16x32_bf16 v[100:103], v[150:153], v[232:235], v[100:103]
	v_mfma_f32_16x16x32_bf16 v[96:99], v[158:161], v[232:235], v[96:99]
	v_mfma_f32_16x16x32_bf16 v[60:63], v[162:165], v[194:197], 0
	v_mfma_f32_16x16x32_bf16 v[56:59], v[170:173], v[194:197], 0
	v_mfma_f32_16x16x32_bf16 v[52:55], v[162:165], v[210:213], 0
	v_mfma_f32_16x16x32_bf16 v[48:51], v[170:173], v[210:213], 0
	v_mfma_f32_16x16x32_bf16 v[44:47], v[162:165], v[220:223], 0
	v_mfma_f32_16x16x32_bf16 v[40:43], v[170:173], v[220:223], 0
	v_mfma_f32_16x16x32_bf16 v[36:39], v[162:165], v[228:231], 0
	v_mfma_f32_16x16x32_bf16 v[32:35], v[170:173], v[228:231], 0
	v_mfma_f32_16x16x32_bf16 v[60:63], v[166:169], v[206:209], v[60:63]
	v_mfma_f32_16x16x32_bf16 v[56:59], v[174:177], v[206:209], v[56:59]
	v_mfma_f32_16x16x32_bf16 v[52:55], v[166:169], v[214:217], v[52:55]
	v_mfma_f32_16x16x32_bf16 v[48:51], v[174:177], v[214:217], v[48:51]
	v_mfma_f32_16x16x32_bf16 v[44:47], v[166:169], v[224:227], v[44:47]
	v_mfma_f32_16x16x32_bf16 v[40:43], v[174:177], v[224:227], v[40:43]
	v_mfma_f32_16x16x32_bf16 v[36:39], v[166:169], v[232:235], v[36:39]
	v_mfma_f32_16x16x32_bf16 v[32:35], v[174:177], v[232:235], v[32:35]
	s_barrier
	s_add_i32 s59, s59, s34
	v_lshl_add_u64 v[140:141], s[42:43], 0, v[132:133]
	s_mov_b32 m0, s59
	ds_read_b128 v[194:197], v145 offset:16384
	ds_read_b128 v[206:209], v145 offset:17408
	ds_read_b128 v[210:213], v145 offset:18432
	ds_read_b128 v[214:217], v145 offset:19456
	ds_read_b128 v[220:223], v145 offset:20480
	ds_read_b128 v[224:227], v145 offset:21504
	ds_read_b128 v[228:231], v145 offset:22528
	ds_read_b128 v[232:235], v145 offset:23552
	global_load_lds_dwordx4 v[140:141], off
	s_add_i32 m0, s59, 0x2000
	v_lshl_add_u64 v[178:179], s[42:43], 0, v[128:129]
	s_add_u32 s42, s42, s0
	s_addc_u32 s43, s43, s1
	s_add_i32 s29, s29, s34
	global_load_lds_dwordx4 v[178:179], off
	v_lshl_add_u64 v[198:199], s[42:43], 0, v[132:133]
	s_mov_b32 m0, s29
	v_lshl_add_u64 v[202:203], s[42:43], 0, v[128:129]
	global_load_lds_dwordx4 v[198:199], off
	s_add_i32 m0, s29, 0x2000
	v_lshl_add_u64 v[236:237], s[16:17], 0, v[134:135]
	global_load_lds_dwordx4 v[202:203], off
	s_mov_b32 m0, s35
	v_lshl_add_u64 v[238:239], s[16:17], 0, v[130:131]
	global_load_lds_dwordx4 v[236:237], off
	s_mov_b32 m0, s36
	s_nop 0
	global_load_lds_dwordx4 v[238:239], off
	s_waitcnt vmcnt(8)
	s_waitcnt lgkmcnt(0)
	s_barrier
	s_waitcnt lgkmcnt(0)
	v_mfma_f32_16x16x32_bf16 v[92:95], v[146:149], v[194:197], 0
	v_mfma_f32_16x16x32_bf16 v[88:91], v[154:157], v[194:197], 0
	v_mfma_f32_16x16x32_bf16 v[84:87], v[146:149], v[210:213], 0
	v_mfma_f32_16x16x32_bf16 v[80:83], v[154:157], v[210:213], 0
	v_mfma_f32_16x16x32_bf16 v[76:79], v[146:149], v[220:223], 0
	v_mfma_f32_16x16x32_bf16 v[72:75], v[154:157], v[220:223], 0
	v_mfma_f32_16x16x32_bf16 v[68:71], v[146:149], v[228:231], 0
	v_mfma_f32_16x16x32_bf16 v[64:67], v[154:157], v[228:231], 0
	v_mfma_f32_16x16x32_bf16 v[92:95], v[150:153], v[206:209], v[92:95]
	v_mfma_f32_16x16x32_bf16 v[88:91], v[158:161], v[206:209], v[88:91]
	v_mfma_f32_16x16x32_bf16 v[84:87], v[150:153], v[214:217], v[84:87]
	v_mfma_f32_16x16x32_bf16 v[80:83], v[158:161], v[214:217], v[80:83]
	v_mfma_f32_16x16x32_bf16 v[76:79], v[150:153], v[224:227], v[76:79]
	v_mfma_f32_16x16x32_bf16 v[72:75], v[158:161], v[224:227], v[72:75]
	v_mfma_f32_16x16x32_bf16 v[68:71], v[150:153], v[232:235], v[68:71]
	v_mfma_f32_16x16x32_bf16 v[64:67], v[158:161], v[232:235], v[64:67]
	v_mfma_f32_16x16x32_bf16 v[28:31], v[162:165], v[194:197], 0
	v_mfma_f32_16x16x32_bf16 v[24:27], v[170:173], v[194:197], 0
	v_mfma_f32_16x16x32_bf16 v[20:23], v[162:165], v[210:213], 0
	v_mfma_f32_16x16x32_bf16 v[16:19], v[170:173], v[210:213], 0
	v_mfma_f32_16x16x32_bf16 v[12:15], v[162:165], v[220:223], 0
	v_mfma_f32_16x16x32_bf16 v[8:11], v[170:173], v[220:223], 0
	v_mfma_f32_16x16x32_bf16 v[4:7], v[162:165], v[228:231], 0
	v_mfma_f32_16x16x32_bf16 v[0:3], v[170:173], v[228:231], 0
	v_mfma_f32_16x16x32_bf16 v[28:31], v[166:169], v[206:209], v[28:31]
	v_mfma_f32_16x16x32_bf16 v[24:27], v[174:177], v[206:209], v[24:27]
	v_mfma_f32_16x16x32_bf16 v[20:23], v[166:169], v[214:217], v[20:23]
	v_mfma_f32_16x16x32_bf16 v[16:19], v[174:177], v[214:217], v[16:19]
	v_mfma_f32_16x16x32_bf16 v[12:15], v[166:169], v[224:227], v[12:15]
	v_mfma_f32_16x16x32_bf16 v[8:11], v[174:177], v[224:227], v[8:11]
	v_mfma_f32_16x16x32_bf16 v[4:7], v[166:169], v[232:235], v[4:7]
	v_mfma_f32_16x16x32_bf16 v[0:3], v[174:177], v[232:235], v[0:3]
	s_barrier
	s_add_i32 s29, 0, 0x18000
	s_add_i32 s42, 0, 0x1c000
	v_add_u32_e32 v158, s29, v143
	v_add_u32_e32 v174, s42, v143
	ds_read_b128 v[146:149], v158
	ds_read_b128 v[150:153], v158 offset:1024
	ds_read_b128 v[154:157], v158 offset:2048
	ds_read_b128 v[158:161], v158 offset:3072
	ds_read_b128 v[162:165], v174
	ds_read_b128 v[166:169], v174 offset:1024
	ds_read_b128 v[170:173], v174 offset:2048
	ds_read_b128 v[174:177], v174 offset:3072
	s_add_u32 s16, s16, s0
	s_addc_u32 s17, s17, s1
	s_mov_b32 m0, s37
	v_lshl_add_u64 v[240:241], s[16:17], 0, v[134:135]
	ds_read_b128 v[194:197], v145 offset:32768
	ds_read_b128 v[206:209], v145 offset:33792
	ds_read_b128 v[210:213], v145 offset:34816
	ds_read_b128 v[214:217], v145 offset:35840
	ds_read_b128 v[220:223], v145 offset:36864
	ds_read_b128 v[224:227], v145 offset:37888
	ds_read_b128 v[228:231], v145 offset:38912
	ds_read_b128 v[232:235], v145 offset:39936
	global_load_lds_dwordx4 v[240:241], off
	v_lshl_add_u64 v[240:241], s[16:17], 0, v[130:131]
	s_mov_b32 m0, s38
	s_nop 0
	global_load_lds_dwordx4 v[240:241], off
	s_waitcnt vmcnt(8)
	s_waitcnt lgkmcnt(0)
	s_barrier
	s_waitcnt lgkmcnt(0)
	v_mfma_f32_16x16x32_bf16 v[120:123], v[146:149], v[194:197], v[120:123]
	v_mfma_f32_16x16x32_bf16 v[124:127], v[154:157], v[194:197], v[124:127]
	v_mfma_f32_16x16x32_bf16 v[116:119], v[146:149], v[210:213], v[116:119]
	v_mfma_f32_16x16x32_bf16 v[112:115], v[154:157], v[210:213], v[112:115]
	v_mfma_f32_16x16x32_bf16 v[108:111], v[146:149], v[220:223], v[108:111]
	v_mfma_f32_16x16x32_bf16 v[104:107], v[154:157], v[220:223], v[104:107]
	v_mfma_f32_16x16x32_bf16 v[100:103], v[146:149], v[228:231], v[100:103]
	v_mfma_f32_16x16x32_bf16 v[96:99], v[154:157], v[228:231], v[96:99]
	v_mfma_f32_16x16x32_bf16 v[120:123], v[150:153], v[206:209], v[120:123]
	v_mfma_f32_16x16x32_bf16 v[124:127], v[158:161], v[206:209], v[124:127]
	v_mfma_f32_16x16x32_bf16 v[116:119], v[150:153], v[214:217], v[116:119]
	v_mfma_f32_16x16x32_bf16 v[112:115], v[158:161], v[214:217], v[112:115]
	v_mfma_f32_16x16x32_bf16 v[108:111], v[150:153], v[224:227], v[108:111]
	v_mfma_f32_16x16x32_bf16 v[104:107], v[158:161], v[224:227], v[104:107]
	v_mfma_f32_16x16x32_bf16 v[100:103], v[150:153], v[232:235], v[100:103]
	v_mfma_f32_16x16x32_bf16 v[96:99], v[158:161], v[232:235], v[96:99]
	v_mfma_f32_16x16x32_bf16 v[60:63], v[162:165], v[194:197], v[60:63]
	v_mfma_f32_16x16x32_bf16 v[56:59], v[170:173], v[194:197], v[56:59]
	v_mfma_f32_16x16x32_bf16 v[52:55], v[162:165], v[210:213], v[52:55]
	v_mfma_f32_16x16x32_bf16 v[48:51], v[170:173], v[210:213], v[48:51]
	v_mfma_f32_16x16x32_bf16 v[44:47], v[162:165], v[220:223], v[44:47]
	v_mfma_f32_16x16x32_bf16 v[40:43], v[170:173], v[220:223], v[40:43]
	v_mfma_f32_16x16x32_bf16 v[36:39], v[162:165], v[228:231], v[36:39]
	v_mfma_f32_16x16x32_bf16 v[32:35], v[170:173], v[228:231], v[32:35]
	v_mfma_f32_16x16x32_bf16 v[60:63], v[166:169], v[206:209], v[60:63]
	v_mfma_f32_16x16x32_bf16 v[56:59], v[174:177], v[206:209], v[56:59]
	v_mfma_f32_16x16x32_bf16 v[52:55], v[166:169], v[214:217], v[52:55]
	v_mfma_f32_16x16x32_bf16 v[48:51], v[174:177], v[214:217], v[48:51]
	v_mfma_f32_16x16x32_bf16 v[44:47], v[166:169], v[224:227], v[44:47]
	v_mfma_f32_16x16x32_bf16 v[40:43], v[174:177], v[224:227], v[40:43]
	v_mfma_f32_16x16x32_bf16 v[36:39], v[166:169], v[232:235], v[36:39]
	v_mfma_f32_16x16x32_bf16 v[32:35], v[174:177], v[232:235], v[32:35]
	s_barrier
	s_add_i32 s16, s29, s34
	v_lshl_add_u64 v[140:141], v[140:141], 0, s[12:13]
	s_mov_b32 m0, s16
	ds_read_b128 v[194:197], v145 offset:49152
	ds_read_b128 v[206:209], v145 offset:50176
	ds_read_b128 v[210:213], v145 offset:51200
	ds_read_b128 v[214:217], v145 offset:52224
	ds_read_b128 v[220:223], v145 offset:53248
	ds_read_b128 v[224:227], v145 offset:54272
	ds_read_b128 v[228:231], v145 offset:55296
	ds_read_b128 v[232:235], v145 offset:56320
	global_load_lds_dwordx4 v[140:141], off
	v_lshl_add_u64 v[140:141], v[178:179], 0, s[12:13]
	s_add_i32 m0, s16, 0x2000
	s_add_i32 s16, s42, s34
	global_load_lds_dwordx4 v[140:141], off
	v_lshl_add_u64 v[140:141], v[198:199], 0, s[12:13]
	s_mov_b32 m0, s16
	s_nop 0
	global_load_lds_dwordx4 v[140:141], off
	v_lshl_add_u64 v[140:141], v[202:203], 0, s[12:13]
	s_add_i32 m0, s16, 0x2000
	s_nop 0
	global_load_lds_dwordx4 v[140:141], off
	v_lshl_add_u64 v[140:141], v[236:237], 0, s[12:13]
	s_mov_b32 m0, s46
	s_nop 0
	global_load_lds_dwordx4 v[140:141], off
	v_lshl_add_u64 v[140:141], v[238:239], 0, s[12:13]
	s_mov_b32 m0, s47
	s_nop 0
	global_load_lds_dwordx4 v[140:141], off
	s_waitcnt vmcnt(8)
	s_waitcnt lgkmcnt(0)
	s_barrier
	s_waitcnt lgkmcnt(0)
	v_mfma_f32_16x16x32_bf16 v[92:95], v[146:149], v[194:197], v[92:95]
	v_mfma_f32_16x16x32_bf16 v[88:91], v[154:157], v[194:197], v[88:91]
	v_mfma_f32_16x16x32_bf16 v[84:87], v[146:149], v[210:213], v[84:87]
	v_mfma_f32_16x16x32_bf16 v[80:83], v[154:157], v[210:213], v[80:83]
	v_mfma_f32_16x16x32_bf16 v[76:79], v[146:149], v[220:223], v[76:79]
	v_mfma_f32_16x16x32_bf16 v[72:75], v[154:157], v[220:223], v[72:75]
	v_mfma_f32_16x16x32_bf16 v[68:71], v[146:149], v[228:231], v[68:71]
	v_mfma_f32_16x16x32_bf16 v[64:67], v[154:157], v[228:231], v[64:67]
	v_mfma_f32_16x16x32_bf16 v[92:95], v[150:153], v[206:209], v[92:95]
	v_mfma_f32_16x16x32_bf16 v[88:91], v[158:161], v[206:209], v[88:91]
	v_mfma_f32_16x16x32_bf16 v[84:87], v[150:153], v[214:217], v[84:87]
	v_mfma_f32_16x16x32_bf16 v[80:83], v[158:161], v[214:217], v[80:83]
	v_mfma_f32_16x16x32_bf16 v[76:79], v[150:153], v[224:227], v[76:79]
	v_mfma_f32_16x16x32_bf16 v[72:75], v[158:161], v[224:227], v[72:75]
	v_mfma_f32_16x16x32_bf16 v[68:71], v[150:153], v[232:235], v[68:71]
	v_mfma_f32_16x16x32_bf16 v[64:67], v[158:161], v[232:235], v[64:67]
	v_mfma_f32_16x16x32_bf16 v[28:31], v[162:165], v[194:197], v[28:31]
	v_mfma_f32_16x16x32_bf16 v[24:27], v[170:173], v[194:197], v[24:27]
	v_mfma_f32_16x16x32_bf16 v[20:23], v[162:165], v[210:213], v[20:23]
	v_mfma_f32_16x16x32_bf16 v[16:19], v[170:173], v[210:213], v[16:19]
	v_mfma_f32_16x16x32_bf16 v[12:15], v[162:165], v[220:223], v[12:15]
	v_mfma_f32_16x16x32_bf16 v[8:11], v[170:173], v[220:223], v[8:11]
	v_mfma_f32_16x16x32_bf16 v[4:7], v[162:165], v[228:231], v[4:7]
	v_mfma_f32_16x16x32_bf16 v[0:3], v[170:173], v[228:231], v[0:3]
	v_mfma_f32_16x16x32_bf16 v[28:31], v[166:169], v[206:209], v[28:31]
	v_mfma_f32_16x16x32_bf16 v[24:27], v[174:177], v[206:209], v[24:27]
	v_mfma_f32_16x16x32_bf16 v[20:23], v[166:169], v[214:217], v[20:23]
	v_mfma_f32_16x16x32_bf16 v[16:19], v[174:177], v[214:217], v[16:19]
	v_mfma_f32_16x16x32_bf16 v[12:15], v[166:169], v[224:227], v[12:15]
	v_mfma_f32_16x16x32_bf16 v[8:11], v[174:177], v[224:227], v[8:11]
	v_mfma_f32_16x16x32_bf16 v[4:7], v[166:169], v[232:235], v[4:7]
	v_mfma_f32_16x16x32_bf16 v[0:3], v[174:177], v[232:235], v[0:3]
	s_barrier
	s_add_u32 s26, s26, 0x100
	s_addc_u32 s27, s27, 0
	s_add_u32 s10, s10, 0x100
	s_addc_u32 s11, s11, 0
	s_cmp_ge_i32 s28, s45
	s_mov_b32 s16, s28
	s_cbranch_scc1 .Lpeelx_11

.Lpeelx_11:
.LBB0_824:
	s_and_b64 vcc, exec, s[20:21]
	s_cbranch_vccz .LBB0_826
	s_barrier

.LBB0_842:
	s_andn2_b64 vcc, exec, s[22:23]
	s_cbranch_vccnz .LBB0_845
	s_add_u32 s0, s0, 0x80
	s_addc_u32 s1, s1, 0
	s_add_u32 s10, s30, 0x100
	s_addc_u32 s11, s31, 0
	s_mov_b32 s16, 0
	s_cmp_lg_u32 s100, 0
	s_cbranch_scc0 .Llbb_8
	s_barrier
	s_mov_b32 s100, 0
.Llbb_8:
	s_add_i32 s30, s16, 2
	s_add_u32 s31, s0, 0x80
	s_addc_u32 s17, s1, 0
	s_add_i32 s35, 0, 0x10000
	s_cmp_eq_u32 s57, s16
	s_cselect_b32 s17, s27, s17
	s_cselect_b32 s16, s26, s31
	s_cselect_b32 s43, s29, s11
	s_cselect_b32 s42, s28, s10
	s_add_i32 s31, 0, 0x14000
	v_add_u32_e32 v156, s35, v164
	v_add_u32_e32 v167, s31, v164
	ds_read_b128 v[144:147], v156
	ds_read_b128 v[148:151], v156 offset:1024
	ds_read_b128 v[152:155], v156 offset:2048
	ds_read_b128 v[156:159], v156 offset:3072
	ds_read_b128 v[160:163], v167
	ds_read_b128 v[168:171], v167 offset:1024
	ds_read_b128 v[172:175], v167 offset:2048
	ds_read_b128 v[176:179], v167 offset:3072
	v_lshl_add_u64 v[198:199], s[0:1], 0, v[140:141]
	s_add_i32 m0, s39, 0xc000
	ds_read_b128 v[194:197], v166
	ds_read_b128 v[206:209], v166 offset:1024
	ds_read_b128 v[210:213], v166 offset:2048
	ds_read_b128 v[214:217], v166 offset:3072
	ds_read_b128 v[220:223], v166 offset:4096
	ds_read_b128 v[224:227], v166 offset:5120
	ds_read_b128 v[228:231], v166 offset:6144
	ds_read_b128 v[232:235], v166 offset:7168
	global_load_lds_dwordx4 v[198:199], off
	v_lshl_add_u64 v[198:199], s[0:1], 0, v[142:143]
	s_add_i32 m0, s39, 0xe000
	s_nop 0
	global_load_lds_dwordx4 v[198:199], off
	s_waitcnt vmcnt(8)
	s_waitcnt lgkmcnt(0)
	s_barrier
	s_waitcnt lgkmcnt(0)
	v_mfma_f32_16x16x32_bf16 v[124:127], v[144:147], v[194:197], 0
	v_mfma_f32_16x16x32_bf16 v[120:123], v[152:155], v[194:197], 0
	v_mfma_f32_16x16x32_bf16 v[108:111], v[144:147], v[210:213], 0
	v_mfma_f32_16x16x32_bf16 v[104:107], v[152:155], v[210:213], 0
	v_mfma_f32_16x16x32_bf16 v[92:95], v[144:147], v[220:223], 0
	v_mfma_f32_16x16x32_bf16 v[88:91], v[152:155], v[220:223], 0
	v_mfma_f32_16x16x32_bf16 v[76:79], v[144:147], v[228:231], 0
	v_mfma_f32_16x16x32_bf16 v[72:75], v[152:155], v[228:231], 0
	v_mfma_f32_16x16x32_bf16 v[124:127], v[148:151], v[206:209], v[124:127]
	v_mfma_f32_16x16x32_bf16 v[120:123], v[156:159], v[206:209], v[120:123]
	v_mfma_f32_16x16x32_bf16 v[108:111], v[148:151], v[214:217], v[108:111]
	v_mfma_f32_16x16x32_bf16 v[104:107], v[156:159], v[214:217], v[104:107]
	v_mfma_f32_16x16x32_bf16 v[92:95], v[148:151], v[224:227], v[92:95]
	v_mfma_f32_16x16x32_bf16 v[88:91], v[156:159], v[224:227], v[88:91]
	v_mfma_f32_16x16x32_bf16 v[76:79], v[148:151], v[232:235], v[76:79]
	v_mfma_f32_16x16x32_bf16 v[72:75], v[156:159], v[232:235], v[72:75]
	v_mfma_f32_16x16x32_bf16 v[116:119], v[160:163], v[194:197], 0
	v_mfma_f32_16x16x32_bf16 v[112:115], v[172:175], v[194:197], 0
	v_mfma_f32_16x16x32_bf16 v[100:103], v[160:163], v[210:213], 0
	v_mfma_f32_16x16x32_bf16 v[96:99], v[172:175], v[210:213], 0
	v_mfma_f32_16x16x32_bf16 v[84:87], v[160:163], v[220:223], 0
	v_mfma_f32_16x16x32_bf16 v[80:83], v[172:175], v[220:223], 0
	v_mfma_f32_16x16x32_bf16 v[68:71], v[160:163], v[228:231], 0
	v_mfma_f32_16x16x32_bf16 v[64:67], v[172:175], v[228:231], 0
	v_mfma_f32_16x16x32_bf16 v[116:119], v[168:171], v[206:209], v[116:119]
	v_mfma_f32_16x16x32_bf16 v[112:115], v[176:179], v[206:209], v[112:115]
	v_mfma_f32_16x16x32_bf16 v[100:103], v[168:171], v[214:217], v[100:103]
	v_mfma_f32_16x16x32_bf16 v[96:99], v[176:179], v[214:217], v[96:99]
	v_mfma_f32_16x16x32_bf16 v[84:87], v[168:171], v[224:227], v[84:87]
	v_mfma_f32_16x16x32_bf16 v[80:83], v[176:179], v[224:227], v[80:83]
	v_mfma_f32_16x16x32_bf16 v[68:71], v[168:171], v[232:235], v[68:71]
	v_mfma_f32_16x16x32_bf16 v[64:67], v[176:179], v[232:235], v[64:67]
	s_barrier
	s_add_i32 s35, s35, s38
	v_lshl_add_u64 v[198:199], s[42:43], 0, v[132:133]
	s_mov_b32 m0, s35
	ds_read_b128 v[194:197], v166 offset:16384
	ds_read_b128 v[206:209], v166 offset:17408
	ds_read_b128 v[210:213], v166 offset:18432
	ds_read_b128 v[214:217], v166 offset:19456
	ds_read_b128 v[220:223], v166 offset:20480
	ds_read_b128 v[224:227], v166 offset:21504
	ds_read_b128 v[228:231], v166 offset:22528
	ds_read_b128 v[232:235], v166 offset:23552
	global_load_lds_dwordx4 v[198:199], off
	s_add_i32 m0, s35, 0x2000
	v_lshl_add_u64 v[202:203], s[42:43], 0, v[128:129]
	s_add_u32 s42, s42, s6
	s_addc_u32 s43, s43, s7
	s_add_i32 s31, s31, s38
	global_load_lds_dwordx4 v[202:203], off
	v_lshl_add_u64 v[236:237], s[42:43], 0, v[132:133]
	s_mov_b32 m0, s31
	v_lshl_add_u64 v[238:239], s[42:43], 0, v[128:129]
	global_load_lds_dwordx4 v[236:237], off
	s_add_i32 m0, s31, 0x2000
	v_lshl_add_u64 v[240:241], s[16:17], 0, v[134:135]
	global_load_lds_dwordx4 v[238:239], off
	s_mov_b32 m0, s39
	v_lshl_add_u64 v[242:243], s[16:17], 0, v[130:131]
	global_load_lds_dwordx4 v[240:241], off
	s_mov_b32 m0, s44
	s_nop 0
	global_load_lds_dwordx4 v[242:243], off
	s_waitcnt vmcnt(8)
	s_waitcnt lgkmcnt(0)
	s_barrier
	s_waitcnt lgkmcnt(0)
	v_mfma_f32_16x16x32_bf16 v[60:63], v[144:147], v[194:197], 0
	v_mfma_f32_16x16x32_bf16 v[56:59], v[152:155], v[194:197], 0
	v_mfma_f32_16x16x32_bf16 v[44:47], v[144:147], v[210:213], 0
	v_mfma_f32_16x16x32_bf16 v[40:43], v[152:155], v[210:213], 0
	v_mfma_f32_16x16x32_bf16 v[28:31], v[144:147], v[220:223], 0
	v_mfma_f32_16x16x32_bf16 v[24:27], v[152:155], v[220:223], 0
	v_mfma_f32_16x16x32_bf16 v[12:15], v[144:147], v[228:231], 0
	v_mfma_f32_16x16x32_bf16 v[8:11], v[152:155], v[228:231], 0
	v_mfma_f32_16x16x32_bf16 v[60:63], v[148:151], v[206:209], v[60:63]
	v_mfma_f32_16x16x32_bf16 v[56:59], v[156:159], v[206:209], v[56:59]
	v_mfma_f32_16x16x32_bf16 v[44:47], v[148:151], v[214:217], v[44:47]
	v_mfma_f32_16x16x32_bf16 v[40:43], v[156:159], v[214:217], v[40:43]
	v_mfma_f32_16x16x32_bf16 v[28:31], v[148:151], v[224:227], v[28:31]
	v_mfma_f32_16x16x32_bf16 v[24:27], v[156:159], v[224:227], v[24:27]
	v_mfma_f32_16x16x32_bf16 v[12:15], v[148:151], v[232:235], v[12:15]
	v_mfma_f32_16x16x32_bf16 v[8:11], v[156:159], v[232:235], v[8:11]
	v_mfma_f32_16x16x32_bf16 v[52:55], v[160:163], v[194:197], 0
	v_mfma_f32_16x16x32_bf16 v[48:51], v[172:175], v[194:197], 0
	v_mfma_f32_16x16x32_bf16 v[36:39], v[160:163], v[210:213], 0
	v_mfma_f32_16x16x32_bf16 v[32:35], v[172:175], v[210:213], 0
	v_mfma_f32_16x16x32_bf16 v[20:23], v[160:163], v[220:223], 0
	v_mfma_f32_16x16x32_bf16 v[16:19], v[172:175], v[220:223], 0
	v_mfma_f32_16x16x32_bf16 v[4:7], v[160:163], v[228:231], 0
	v_mfma_f32_16x16x32_bf16 v[0:3], v[172:175], v[228:231], 0
	v_mfma_f32_16x16x32_bf16 v[52:55], v[168:171], v[206:209], v[52:55]
	v_mfma_f32_16x16x32_bf16 v[48:51], v[176:179], v[206:209], v[48:51]
	v_mfma_f32_16x16x32_bf16 v[36:39], v[168:171], v[214:217], v[36:39]
	v_mfma_f32_16x16x32_bf16 v[32:35], v[176:179], v[214:217], v[32:35]
	v_mfma_f32_16x16x32_bf16 v[20:23], v[168:171], v[224:227], v[20:23]
	v_mfma_f32_16x16x32_bf16 v[16:19], v[176:179], v[224:227], v[16:19]
	v_mfma_f32_16x16x32_bf16 v[4:7], v[168:171], v[232:235], v[4:7]
	v_mfma_f32_16x16x32_bf16 v[0:3], v[176:179], v[232:235], v[0:3]
	s_barrier
	s_add_i32 s31, 0, 0x18000
	s_add_i32 s35, 0, 0x1c000
	v_add_u32_e32 v156, s31, v164
	v_add_u32_e32 v167, s35, v164
	ds_read_b128 v[144:147], v156
	ds_read_b128 v[148:151], v156 offset:1024
	ds_read_b128 v[152:155], v156 offset:2048
	ds_read_b128 v[156:159], v156 offset:3072
	ds_read_b128 v[160:163], v167
	ds_read_b128 v[168:171], v167 offset:1024
	ds_read_b128 v[172:175], v167 offset:2048
	ds_read_b128 v[176:179], v167 offset:3072
	s_add_u32 s16, s16, s6
	s_addc_u32 s17, s17, s7
	s_mov_b32 m0, s45
	v_lshl_add_u64 v[244:245], s[16:17], 0, v[134:135]
	ds_read_b128 v[194:197], v166 offset:32768
	ds_read_b128 v[206:209], v166 offset:33792
	ds_read_b128 v[210:213], v166 offset:34816
	ds_read_b128 v[214:217], v166 offset:35840
	ds_read_b128 v[220:223], v166 offset:36864
	ds_read_b128 v[224:227], v166 offset:37888
	ds_read_b128 v[228:231], v166 offset:38912
	ds_read_b128 v[232:235], v166 offset:39936
	global_load_lds_dwordx4 v[244:245], off
	v_lshl_add_u64 v[244:245], s[16:17], 0, v[130:131]
	s_mov_b32 m0, s46
	s_nop 0
	global_load_lds_dwordx4 v[244:245], off
	s_waitcnt vmcnt(8)
	s_waitcnt lgkmcnt(0)
	s_barrier
	s_waitcnt lgkmcnt(0)
	v_mfma_f32_16x16x32_bf16 v[124:127], v[144:147], v[194:197], v[124:127]
	v_mfma_f32_16x16x32_bf16 v[120:123], v[152:155], v[194:197], v[120:123]
	v_mfma_f32_16x16x32_bf16 v[108:111], v[144:147], v[210:213], v[108:111]
	v_mfma_f32_16x16x32_bf16 v[104:107], v[152:155], v[210:213], v[104:107]
	v_mfma_f32_16x16x32_bf16 v[92:95], v[144:147], v[220:223], v[92:95]
	v_mfma_f32_16x16x32_bf16 v[88:91], v[152:155], v[220:223], v[88:91]
	v_mfma_f32_16x16x32_bf16 v[76:79], v[144:147], v[228:231], v[76:79]
	v_mfma_f32_16x16x32_bf16 v[72:75], v[152:155], v[228:231], v[72:75]
	v_mfma_f32_16x16x32_bf16 v[124:127], v[148:151], v[206:209], v[124:127]
	v_mfma_f32_16x16x32_bf16 v[120:123], v[156:159], v[206:209], v[120:123]
	v_mfma_f32_16x16x32_bf16 v[108:111], v[148:151], v[214:217], v[108:111]
	v_mfma_f32_16x16x32_bf16 v[104:107], v[156:159], v[214:217], v[104:107]
	v_mfma_f32_16x16x32_bf16 v[92:95], v[148:151], v[224:227], v[92:95]
	v_mfma_f32_16x16x32_bf16 v[88:91], v[156:159], v[224:227], v[88:91]
	v_mfma_f32_16x16x32_bf16 v[76:79], v[148:151], v[232:235], v[76:79]
	v_mfma_f32_16x16x32_bf16 v[72:75], v[156:159], v[232:235], v[72:75]
	v_mfma_f32_16x16x32_bf16 v[116:119], v[160:163], v[194:197], v[116:119]
	v_mfma_f32_16x16x32_bf16 v[112:115], v[172:175], v[194:197], v[112:115]
	v_mfma_f32_16x16x32_bf16 v[100:103], v[160:163], v[210:213], v[100:103]
	v_mfma_f32_16x16x32_bf16 v[96:99], v[172:175], v[210:213], v[96:99]
	v_mfma_f32_16x16x32_bf16 v[84:87], v[160:163], v[220:223], v[84:87]
	v_mfma_f32_16x16x32_bf16 v[80:83], v[172:175], v[220:223], v[80:83]
	v_mfma_f32_16x16x32_bf16 v[68:71], v[160:163], v[228:231], v[68:71]
	v_mfma_f32_16x16x32_bf16 v[64:67], v[172:175], v[228:231], v[64:67]
	v_mfma_f32_16x16x32_bf16 v[116:119], v[168:171], v[206:209], v[116:119]
	v_mfma_f32_16x16x32_bf16 v[112:115], v[176:179], v[206:209], v[112:115]
	v_mfma_f32_16x16x32_bf16 v[100:103], v[168:171], v[214:217], v[100:103]
	v_mfma_f32_16x16x32_bf16 v[96:99], v[176:179], v[214:217], v[96:99]
	v_mfma_f32_16x16x32_bf16 v[84:87], v[168:171], v[224:227], v[84:87]
	v_mfma_f32_16x16x32_bf16 v[80:83], v[176:179], v[224:227], v[80:83]
	v_mfma_f32_16x16x32_bf16 v[68:71], v[168:171], v[232:235], v[68:71]
	v_mfma_f32_16x16x32_bf16 v[64:67], v[176:179], v[232:235], v[64:67]
	s_barrier
	s_add_i32 s16, s31, s38
	v_lshl_add_u64 v[198:199], v[198:199], 0, s[12:13]
	s_mov_b32 m0, s16
	ds_read_b128 v[194:197], v166 offset:49152
	ds_read_b128 v[206:209], v166 offset:50176
	ds_read_b128 v[210:213], v166 offset:51200
	ds_read_b128 v[214:217], v166 offset:52224
	ds_read_b128 v[220:223], v166 offset:53248
	ds_read_b128 v[224:227], v166 offset:54272
	ds_read_b128 v[228:231], v166 offset:55296
	ds_read_b128 v[232:235], v166 offset:56320
	global_load_lds_dwordx4 v[198:199], off
	v_lshl_add_u64 v[198:199], v[202:203], 0, s[12:13]
	s_add_i32 m0, s16, 0x2000
	s_add_i32 s16, s35, s38
	global_load_lds_dwordx4 v[198:199], off
	v_lshl_add_u64 v[198:199], v[236:237], 0, s[12:13]
	s_mov_b32 m0, s16
	s_nop 0
	global_load_lds_dwordx4 v[198:199], off
	v_lshl_add_u64 v[198:199], v[238:239], 0, s[12:13]
	s_add_i32 m0, s16, 0x2000
	s_nop 0
	global_load_lds_dwordx4 v[198:199], off
	v_lshl_add_u64 v[198:199], v[240:241], 0, s[12:13]
	s_mov_b32 m0, s47
	s_nop 0
	global_load_lds_dwordx4 v[198:199], off
	v_lshl_add_u64 v[198:199], v[242:243], 0, s[12:13]
	s_mov_b32 m0, s48
	s_nop 0
	global_load_lds_dwordx4 v[198:199], off
	s_waitcnt vmcnt(8)
	s_waitcnt lgkmcnt(0)
	s_barrier
	s_waitcnt lgkmcnt(0)
	v_mfma_f32_16x16x32_bf16 v[60:63], v[144:147], v[194:197], v[60:63]
	v_mfma_f32_16x16x32_bf16 v[56:59], v[152:155], v[194:197], v[56:59]
	v_mfma_f32_16x16x32_bf16 v[44:47], v[144:147], v[210:213], v[44:47]
	v_mfma_f32_16x16x32_bf16 v[40:43], v[152:155], v[210:213], v[40:43]
	v_mfma_f32_16x16x32_bf16 v[28:31], v[144:147], v[220:223], v[28:31]
	v_mfma_f32_16x16x32_bf16 v[24:27], v[152:155], v[220:223], v[24:27]
	v_mfma_f32_16x16x32_bf16 v[12:15], v[144:147], v[228:231], v[12:15]
	v_mfma_f32_16x16x32_bf16 v[8:11], v[152:155], v[228:231], v[8:11]
	v_mfma_f32_16x16x32_bf16 v[60:63], v[148:151], v[206:209], v[60:63]
	v_mfma_f32_16x16x32_bf16 v[56:59], v[156:159], v[206:209], v[56:59]
	v_mfma_f32_16x16x32_bf16 v[44:47], v[148:151], v[214:217], v[44:47]
	v_mfma_f32_16x16x32_bf16 v[40:43], v[156:159], v[214:217], v[40:43]
	v_mfma_f32_16x16x32_bf16 v[28:31], v[148:151], v[224:227], v[28:31]
	v_mfma_f32_16x16x32_bf16 v[24:27], v[156:159], v[224:227], v[24:27]
	v_mfma_f32_16x16x32_bf16 v[12:15], v[148:151], v[232:235], v[12:15]
	v_mfma_f32_16x16x32_bf16 v[8:11], v[156:159], v[232:235], v[8:11]
	v_mfma_f32_16x16x32_bf16 v[52:55], v[160:163], v[194:197], v[52:55]
	v_mfma_f32_16x16x32_bf16 v[48:51], v[172:175], v[194:197], v[48:51]
	v_mfma_f32_16x16x32_bf16 v[36:39], v[160:163], v[210:213], v[36:39]
	v_mfma_f32_16x16x32_bf16 v[32:35], v[172:175], v[210:213], v[32:35]
	v_mfma_f32_16x16x32_bf16 v[20:23], v[160:163], v[220:223], v[20:23]
	v_mfma_f32_16x16x32_bf16 v[16:19], v[172:175], v[220:223], v[16:19]
	v_mfma_f32_16x16x32_bf16 v[4:7], v[160:163], v[228:231], v[4:7]
	v_mfma_f32_16x16x32_bf16 v[0:3], v[172:175], v[228:231], v[0:3]
	v_mfma_f32_16x16x32_bf16 v[52:55], v[168:171], v[206:209], v[52:55]
	v_mfma_f32_16x16x32_bf16 v[48:51], v[176:179], v[206:209], v[48:51]
	v_mfma_f32_16x16x32_bf16 v[36:39], v[168:171], v[214:217], v[36:39]
	v_mfma_f32_16x16x32_bf16 v[32:35], v[176:179], v[214:217], v[32:35]
	v_mfma_f32_16x16x32_bf16 v[20:23], v[168:171], v[224:227], v[20:23]
	v_mfma_f32_16x16x32_bf16 v[16:19], v[176:179], v[224:227], v[16:19]
	v_mfma_f32_16x16x32_bf16 v[4:7], v[168:171], v[232:235], v[4:7]
	v_mfma_f32_16x16x32_bf16 v[0:3], v[176:179], v[232:235], v[0:3]
	s_barrier
	s_add_u32 s0, s0, 0x100
	s_addc_u32 s1, s1, 0
	s_add_u32 s10, s10, 0x100
	s_addc_u32 s11, s11, 0
	s_cmp_ge_i32 s30, s49
	s_mov_b32 s16, s30
	s_cbranch_scc1 .Lpeelx_12

.LBB0_1051:
	s_andn2_b64 vcc, exec, s[20:21]
	s_waitcnt lgkmcnt(0)
	s_cbranch_vccnz .LBB0_1054
	s_add_u32 s28, s28, 0x80
	s_addc_u32 s29, s29, 0
	s_add_u32 s10, s30, 0x100
	s_addc_u32 s11, s31, 0
	s_mov_b32 s16, 0
	s_cmp_lg_u32 s100, 0
	s_cbranch_scc0 .Llbb_9
	s_barrier
	s_mov_b32 s100, 0
.Llbb_9:
	s_add_i32 s30, s16, 2
	s_add_u32 s31, s28, 0x80
	s_addc_u32 s17, s29, 0
	s_add_i32 s62, 0, 0x10000
	s_cmp_eq_u32 s56, s16
	s_cselect_b32 s17, s25, s17
	s_cselect_b32 s16, s24, s31
	s_cselect_b32 s45, s27, s11
	s_cselect_b32 s44, s26, s10
	s_add_i32 s31, 0, 0x14000
	v_add_u32_e32 v140, s62, v199
	v_add_u32_e32 v166, s31, v199
	ds_read_b128 v[128:131], v140
	ds_read_b128 v[132:135], v140 offset:1024
	ds_read_b128 v[136:139], v140 offset:2048
	ds_read_b128 v[140:143], v140 offset:3072
	ds_read_b128 v[144:147], v166
	ds_read_b128 v[148:151], v166 offset:1024
	ds_read_b128 v[152:155], v166 offset:2048
	ds_read_b128 v[166:169], v166 offset:3072
	v_lshl_add_u64 v[178:179], s[28:29], 0, v[162:163]
	s_add_i32 m0, s37, 0xc000
	ds_read_b128 v[170:173], v206
	ds_read_b128 v[174:177], v206 offset:1024
	ds_read_b128 v[194:197], v206 offset:2048
	ds_read_b128 v[208:211], v206 offset:3072
	ds_read_b128 v[212:215], v206 offset:4096
	ds_read_b128 v[220:223], v206 offset:5120
	ds_read_b128 v[224:227], v206 offset:6144
	ds_read_b128 v[228:231], v206 offset:7168
	global_load_lds_dwordx4 v[178:179], off
	v_lshl_add_u64 v[178:179], s[28:29], 0, v[164:165]
	s_add_i32 m0, s37, 0xe000
	s_nop 0
	global_load_lds_dwordx4 v[178:179], off
	s_waitcnt vmcnt(8)
	s_waitcnt lgkmcnt(0)
	s_barrier
	s_waitcnt lgkmcnt(0)
	v_mfma_f32_16x16x32_bf16 v[120:123], v[128:131], v[170:173], 0
	v_mfma_f32_16x16x32_bf16 v[124:127], v[136:139], v[170:173], 0
	v_mfma_f32_16x16x32_bf16 v[108:111], v[128:131], v[194:197], 0
	v_mfma_f32_16x16x32_bf16 v[104:107], v[136:139], v[194:197], 0
	v_mfma_f32_16x16x32_bf16 v[92:95], v[128:131], v[212:215], 0
	v_mfma_f32_16x16x32_bf16 v[88:91], v[136:139], v[212:215], 0
	v_mfma_f32_16x16x32_bf16 v[76:79], v[128:131], v[224:227], 0
	v_mfma_f32_16x16x32_bf16 v[72:75], v[136:139], v[224:227], 0
	v_mfma_f32_16x16x32_bf16 v[120:123], v[132:135], v[174:177], v[120:123]
	v_mfma_f32_16x16x32_bf16 v[124:127], v[140:143], v[174:177], v[124:127]
	v_mfma_f32_16x16x32_bf16 v[108:111], v[132:135], v[208:211], v[108:111]
	v_mfma_f32_16x16x32_bf16 v[104:107], v[140:143], v[208:211], v[104:107]
	v_mfma_f32_16x16x32_bf16 v[92:95], v[132:135], v[220:223], v[92:95]
	v_mfma_f32_16x16x32_bf16 v[88:91], v[140:143], v[220:223], v[88:91]
	v_mfma_f32_16x16x32_bf16 v[76:79], v[132:135], v[228:231], v[76:79]
	v_mfma_f32_16x16x32_bf16 v[72:75], v[140:143], v[228:231], v[72:75]
	v_mfma_f32_16x16x32_bf16 v[116:119], v[144:147], v[170:173], 0
	v_mfma_f32_16x16x32_bf16 v[112:115], v[152:155], v[170:173], 0
	v_mfma_f32_16x16x32_bf16 v[100:103], v[144:147], v[194:197], 0
	v_mfma_f32_16x16x32_bf16 v[96:99], v[152:155], v[194:197], 0
	v_mfma_f32_16x16x32_bf16 v[84:87], v[144:147], v[212:215], 0
	v_mfma_f32_16x16x32_bf16 v[80:83], v[152:155], v[212:215], 0
	v_mfma_f32_16x16x32_bf16 v[68:71], v[144:147], v[224:227], 0
	v_mfma_f32_16x16x32_bf16 v[64:67], v[152:155], v[224:227], 0
	v_mfma_f32_16x16x32_bf16 v[116:119], v[148:151], v[174:177], v[116:119]
	v_mfma_f32_16x16x32_bf16 v[112:115], v[166:169], v[174:177], v[112:115]
	v_mfma_f32_16x16x32_bf16 v[100:103], v[148:151], v[208:211], v[100:103]
	v_mfma_f32_16x16x32_bf16 v[96:99], v[166:169], v[208:211], v[96:99]
	v_mfma_f32_16x16x32_bf16 v[84:87], v[148:151], v[220:223], v[84:87]
	v_mfma_f32_16x16x32_bf16 v[80:83], v[166:169], v[220:223], v[80:83]
	v_mfma_f32_16x16x32_bf16 v[68:71], v[148:151], v[228:231], v[68:71]
	v_mfma_f32_16x16x32_bf16 v[64:67], v[166:169], v[228:231], v[64:67]
	s_barrier
	s_add_i32 s62, s62, s36
	v_lshl_add_u64 v[178:179], s[44:45], 0, v[180:181]
	s_mov_b32 m0, s62
	ds_read_b128 v[170:173], v206 offset:16384
	ds_read_b128 v[174:177], v206 offset:17408
	ds_read_b128 v[194:197], v206 offset:18432
	ds_read_b128 v[208:211], v206 offset:19456
	ds_read_b128 v[212:215], v206 offset:20480
	ds_read_b128 v[220:223], v206 offset:21504
	ds_read_b128 v[224:227], v206 offset:22528
	ds_read_b128 v[228:231], v206 offset:23552
	global_load_lds_dwordx4 v[178:179], off
	s_add_i32 m0, s62, 0x2000
	v_lshl_add_u64 v[202:203], s[44:45], 0, v[156:157]
	s_add_u32 s44, s44, s6
	s_addc_u32 s45, s45, s7
	s_add_i32 s31, s31, s36
	global_load_lds_dwordx4 v[202:203], off
	v_lshl_add_u64 v[216:217], s[44:45], 0, v[180:181]
	s_mov_b32 m0, s31
	v_lshl_add_u64 v[232:233], s[44:45], 0, v[156:157]
	global_load_lds_dwordx4 v[216:217], off
	s_add_i32 m0, s31, 0x2000
	v_lshl_add_u64 v[234:235], s[16:17], 0, v[160:161]
	global_load_lds_dwordx4 v[232:233], off
	s_mov_b32 m0, s37
	v_lshl_add_u64 v[236:237], s[16:17], 0, v[158:159]
	global_load_lds_dwordx4 v[234:235], off
	s_mov_b32 m0, s38
	s_nop 0
	global_load_lds_dwordx4 v[236:237], off
	s_waitcnt vmcnt(8)
	s_waitcnt lgkmcnt(0)
	s_barrier
	s_waitcnt lgkmcnt(0)
	v_mfma_f32_16x16x32_bf16 v[60:63], v[128:131], v[170:173], 0
	v_mfma_f32_16x16x32_bf16 v[56:59], v[136:139], v[170:173], 0
	v_mfma_f32_16x16x32_bf16 v[44:47], v[128:131], v[194:197], 0
	v_mfma_f32_16x16x32_bf16 v[40:43], v[136:139], v[194:197], 0
	v_mfma_f32_16x16x32_bf16 v[28:31], v[128:131], v[212:215], 0
	v_mfma_f32_16x16x32_bf16 v[24:27], v[136:139], v[212:215], 0
	v_mfma_f32_16x16x32_bf16 v[12:15], v[128:131], v[224:227], 0
	v_mfma_f32_16x16x32_bf16 v[8:11], v[136:139], v[224:227], 0
	v_mfma_f32_16x16x32_bf16 v[60:63], v[132:135], v[174:177], v[60:63]
	v_mfma_f32_16x16x32_bf16 v[56:59], v[140:143], v[174:177], v[56:59]
	v_mfma_f32_16x16x32_bf16 v[44:47], v[132:135], v[208:211], v[44:47]
	v_mfma_f32_16x16x32_bf16 v[40:43], v[140:143], v[208:211], v[40:43]
	v_mfma_f32_16x16x32_bf16 v[28:31], v[132:135], v[220:223], v[28:31]
	v_mfma_f32_16x16x32_bf16 v[24:27], v[140:143], v[220:223], v[24:27]
	v_mfma_f32_16x16x32_bf16 v[12:15], v[132:135], v[228:231], v[12:15]
	v_mfma_f32_16x16x32_bf16 v[8:11], v[140:143], v[228:231], v[8:11]
	v_mfma_f32_16x16x32_bf16 v[52:55], v[144:147], v[170:173], 0
	v_mfma_f32_16x16x32_bf16 v[48:51], v[152:155], v[170:173], 0
	v_mfma_f32_16x16x32_bf16 v[36:39], v[144:147], v[194:197], 0
	v_mfma_f32_16x16x32_bf16 v[32:35], v[152:155], v[194:197], 0
	v_mfma_f32_16x16x32_bf16 v[20:23], v[144:147], v[212:215], 0
	v_mfma_f32_16x16x32_bf16 v[16:19], v[152:155], v[212:215], 0
	v_mfma_f32_16x16x32_bf16 v[4:7], v[144:147], v[224:227], 0
	v_mfma_f32_16x16x32_bf16 v[0:3], v[152:155], v[224:227], 0
	v_mfma_f32_16x16x32_bf16 v[52:55], v[148:151], v[174:177], v[52:55]
	v_mfma_f32_16x16x32_bf16 v[48:51], v[166:169], v[174:177], v[48:51]
	v_mfma_f32_16x16x32_bf16 v[36:39], v[148:151], v[208:211], v[36:39]
	v_mfma_f32_16x16x32_bf16 v[32:35], v[166:169], v[208:211], v[32:35]
	v_mfma_f32_16x16x32_bf16 v[20:23], v[148:151], v[220:223], v[20:23]
	v_mfma_f32_16x16x32_bf16 v[16:19], v[166:169], v[220:223], v[16:19]
	v_mfma_f32_16x16x32_bf16 v[4:7], v[148:151], v[228:231], v[4:7]
	v_mfma_f32_16x16x32_bf16 v[0:3], v[166:169], v[228:231], v[0:3]
	s_barrier
	s_add_i32 s31, 0, 0x18000
	s_add_i32 s44, 0, 0x1c000
	v_add_u32_e32 v140, s31, v199
	v_add_u32_e32 v166, s44, v199
	ds_read_b128 v[128:131], v140
	ds_read_b128 v[132:135], v140 offset:1024
	ds_read_b128 v[136:139], v140 offset:2048
	ds_read_b128 v[140:143], v140 offset:3072
	ds_read_b128 v[144:147], v166
	ds_read_b128 v[148:151], v166 offset:1024
	ds_read_b128 v[152:155], v166 offset:2048
	ds_read_b128 v[166:169], v166 offset:3072
	s_add_u32 s16, s16, s6
	s_addc_u32 s17, s17, s7
	s_mov_b32 m0, s39
	v_lshl_add_u64 v[238:239], s[16:17], 0, v[160:161]
	ds_read_b128 v[170:173], v206 offset:32768
	ds_read_b128 v[174:177], v206 offset:33792
	ds_read_b128 v[194:197], v206 offset:34816
	ds_read_b128 v[208:211], v206 offset:35840
	ds_read_b128 v[212:215], v206 offset:36864
	ds_read_b128 v[220:223], v206 offset:37888
	ds_read_b128 v[224:227], v206 offset:38912
	ds_read_b128 v[228:231], v206 offset:39936
	global_load_lds_dwordx4 v[238:239], off
	v_lshl_add_u64 v[238:239], s[16:17], 0, v[158:159]
	s_mov_b32 m0, s46
	s_nop 0
	global_load_lds_dwordx4 v[238:239], off
	s_waitcnt vmcnt(8)
	s_waitcnt lgkmcnt(0)
	s_barrier
	s_waitcnt lgkmcnt(0)
	v_mfma_f32_16x16x32_bf16 v[120:123], v[128:131], v[170:173], v[120:123]
	v_mfma_f32_16x16x32_bf16 v[124:127], v[136:139], v[170:173], v[124:127]
	v_mfma_f32_16x16x32_bf16 v[108:111], v[128:131], v[194:197], v[108:111]
	v_mfma_f32_16x16x32_bf16 v[104:107], v[136:139], v[194:197], v[104:107]
	v_mfma_f32_16x16x32_bf16 v[92:95], v[128:131], v[212:215], v[92:95]
	v_mfma_f32_16x16x32_bf16 v[88:91], v[136:139], v[212:215], v[88:91]
	v_mfma_f32_16x16x32_bf16 v[76:79], v[128:131], v[224:227], v[76:79]
	v_mfma_f32_16x16x32_bf16 v[72:75], v[136:139], v[224:227], v[72:75]
	v_mfma_f32_16x16x32_bf16 v[120:123], v[132:135], v[174:177], v[120:123]
	v_mfma_f32_16x16x32_bf16 v[124:127], v[140:143], v[174:177], v[124:127]
	v_mfma_f32_16x16x32_bf16 v[108:111], v[132:135], v[208:211], v[108:111]
	v_mfma_f32_16x16x32_bf16 v[104:107], v[140:143], v[208:211], v[104:107]
	v_mfma_f32_16x16x32_bf16 v[92:95], v[132:135], v[220:223], v[92:95]
	v_mfma_f32_16x16x32_bf16 v[88:91], v[140:143], v[220:223], v[88:91]
	v_mfma_f32_16x16x32_bf16 v[76:79], v[132:135], v[228:231], v[76:79]
	v_mfma_f32_16x16x32_bf16 v[72:75], v[140:143], v[228:231], v[72:75]
	v_mfma_f32_16x16x32_bf16 v[116:119], v[144:147], v[170:173], v[116:119]
	v_mfma_f32_16x16x32_bf16 v[112:115], v[152:155], v[170:173], v[112:115]
	v_mfma_f32_16x16x32_bf16 v[100:103], v[144:147], v[194:197], v[100:103]
	v_mfma_f32_16x16x32_bf16 v[96:99], v[152:155], v[194:197], v[96:99]
	v_mfma_f32_16x16x32_bf16 v[84:87], v[144:147], v[212:215], v[84:87]
	v_mfma_f32_16x16x32_bf16 v[80:83], v[152:155], v[212:215], v[80:83]
	v_mfma_f32_16x16x32_bf16 v[68:71], v[144:147], v[224:227], v[68:71]
	v_mfma_f32_16x16x32_bf16 v[64:67], v[152:155], v[224:227], v[64:67]
	v_mfma_f32_16x16x32_bf16 v[116:119], v[148:151], v[174:177], v[116:119]
	v_mfma_f32_16x16x32_bf16 v[112:115], v[166:169], v[174:177], v[112:115]
	v_mfma_f32_16x16x32_bf16 v[100:103], v[148:151], v[208:211], v[100:103]
	v_mfma_f32_16x16x32_bf16 v[96:99], v[166:169], v[208:211], v[96:99]
	v_mfma_f32_16x16x32_bf16 v[84:87], v[148:151], v[220:223], v[84:87]
	v_mfma_f32_16x16x32_bf16 v[80:83], v[166:169], v[220:223], v[80:83]
	v_mfma_f32_16x16x32_bf16 v[68:71], v[148:151], v[228:231], v[68:71]
	v_mfma_f32_16x16x32_bf16 v[64:67], v[166:169], v[228:231], v[64:67]
	s_barrier
	s_add_i32 s16, s31, s36
	v_lshl_add_u64 v[178:179], v[178:179], 0, s[12:13]
	s_mov_b32 m0, s16
	ds_read_b128 v[170:173], v206 offset:49152
	ds_read_b128 v[174:177], v206 offset:50176
	ds_read_b128 v[194:197], v206 offset:51200
	ds_read_b128 v[208:211], v206 offset:52224
	ds_read_b128 v[212:215], v206 offset:53248
	ds_read_b128 v[220:223], v206 offset:54272
	ds_read_b128 v[224:227], v206 offset:55296
	ds_read_b128 v[228:231], v206 offset:56320
	global_load_lds_dwordx4 v[178:179], off
	v_lshl_add_u64 v[178:179], v[202:203], 0, s[12:13]
	s_add_i32 m0, s16, 0x2000
	s_add_i32 s16, s44, s36
	global_load_lds_dwordx4 v[178:179], off
	v_lshl_add_u64 v[178:179], v[216:217], 0, s[12:13]
	s_mov_b32 m0, s16
	s_nop 0
	global_load_lds_dwordx4 v[178:179], off
	v_lshl_add_u64 v[178:179], v[232:233], 0, s[12:13]
	s_add_i32 m0, s16, 0x2000
	s_nop 0
	global_load_lds_dwordx4 v[178:179], off
	v_lshl_add_u64 v[178:179], v[234:235], 0, s[12:13]
	s_mov_b32 m0, s49
	s_nop 0
	global_load_lds_dwordx4 v[178:179], off
	v_lshl_add_u64 v[178:179], v[236:237], 0, s[12:13]
	s_mov_b32 m0, s52
	s_nop 0
	global_load_lds_dwordx4 v[178:179], off
	s_waitcnt vmcnt(8)
	s_waitcnt lgkmcnt(0)
	s_barrier
	s_waitcnt lgkmcnt(0)
	v_mfma_f32_16x16x32_bf16 v[60:63], v[128:131], v[170:173], v[60:63]
	v_mfma_f32_16x16x32_bf16 v[56:59], v[136:139], v[170:173], v[56:59]
	v_mfma_f32_16x16x32_bf16 v[44:47], v[128:131], v[194:197], v[44:47]
	v_mfma_f32_16x16x32_bf16 v[40:43], v[136:139], v[194:197], v[40:43]
	v_mfma_f32_16x16x32_bf16 v[28:31], v[128:131], v[212:215], v[28:31]
	v_mfma_f32_16x16x32_bf16 v[24:27], v[136:139], v[212:215], v[24:27]
	v_mfma_f32_16x16x32_bf16 v[12:15], v[128:131], v[224:227], v[12:15]
	v_mfma_f32_16x16x32_bf16 v[8:11], v[136:139], v[224:227], v[8:11]
	v_mfma_f32_16x16x32_bf16 v[60:63], v[132:135], v[174:177], v[60:63]
	v_mfma_f32_16x16x32_bf16 v[56:59], v[140:143], v[174:177], v[56:59]
	v_mfma_f32_16x16x32_bf16 v[44:47], v[132:135], v[208:211], v[44:47]
	v_mfma_f32_16x16x32_bf16 v[40:43], v[140:143], v[208:211], v[40:43]
	v_mfma_f32_16x16x32_bf16 v[28:31], v[132:135], v[220:223], v[28:31]
	v_mfma_f32_16x16x32_bf16 v[24:27], v[140:143], v[220:223], v[24:27]
	v_mfma_f32_16x16x32_bf16 v[12:15], v[132:135], v[228:231], v[12:15]
	v_mfma_f32_16x16x32_bf16 v[8:11], v[140:143], v[228:231], v[8:11]
	v_mfma_f32_16x16x32_bf16 v[52:55], v[144:147], v[170:173], v[52:55]
	v_mfma_f32_16x16x32_bf16 v[48:51], v[152:155], v[170:173], v[48:51]
	v_mfma_f32_16x16x32_bf16 v[36:39], v[144:147], v[194:197], v[36:39]
	v_mfma_f32_16x16x32_bf16 v[32:35], v[152:155], v[194:197], v[32:35]
	v_mfma_f32_16x16x32_bf16 v[20:23], v[144:147], v[212:215], v[20:23]
	v_mfma_f32_16x16x32_bf16 v[16:19], v[152:155], v[212:215], v[16:19]
	v_mfma_f32_16x16x32_bf16 v[4:7], v[144:147], v[224:227], v[4:7]
	v_mfma_f32_16x16x32_bf16 v[0:3], v[152:155], v[224:227], v[0:3]
	v_mfma_f32_16x16x32_bf16 v[52:55], v[148:151], v[174:177], v[52:55]
	v_mfma_f32_16x16x32_bf16 v[48:51], v[166:169], v[174:177], v[48:51]
	v_mfma_f32_16x16x32_bf16 v[36:39], v[148:151], v[208:211], v[36:39]
	v_mfma_f32_16x16x32_bf16 v[32:35], v[166:169], v[208:211], v[32:35]
	v_mfma_f32_16x16x32_bf16 v[20:23], v[148:151], v[220:223], v[20:23]
	v_mfma_f32_16x16x32_bf16 v[16:19], v[166:169], v[220:223], v[16:19]
	v_mfma_f32_16x16x32_bf16 v[4:7], v[148:151], v[228:231], v[4:7]
	v_mfma_f32_16x16x32_bf16 v[0:3], v[166:169], v[228:231], v[0:3]
	s_barrier
	s_add_u32 s28, s28, 0x100
	s_addc_u32 s29, s29, 0
	s_add_u32 s10, s10, 0x100
	s_addc_u32 s11, s11, 0
	s_cmp_ge_i32 s30, s48
	s_mov_b32 s16, s30
	s_cbranch_scc1 .Lpeelx_13

.LBB0_1140:
	s_andn2_b64 vcc, exec, s[20:21]
	s_cbranch_vccz .LBB0_1143
	s_and_b64 vcc, exec, s[22:23]
	s_cbranch_vccnz .LBB0_1146

.LBB0_1143:
	s_add_u32 s28, s28, 0x80
	s_addc_u32 s29, s29, 0
	s_add_u32 s10, s30, 0x100
	s_addc_u32 s11, s31, 0
	s_mov_b32 s16, 0
	s_waitcnt vmcnt(0)
	s_cmp_lg_u32 s100, 0
	s_cbranch_scc0 .Llbb_10
	s_barrier
	s_mov_b32 s100, 0
.Llbb_10:
	s_add_i32 s30, s16, 2
	s_add_u32 s31, s28, 0x80
	s_addc_u32 s17, s29, 0
	s_add_i32 s63, 0, 0x10000
	s_cmp_eq_u32 s56, s16
	s_cselect_b32 s17, s25, s17
	s_cselect_b32 s16, s24, s31
	s_cselect_b32 s45, s27, s11
	s_cselect_b32 s44, s26, s10
	s_add_i32 s31, 0, 0x14000
	v_add_u32_e32 v156, s63, v151
	v_add_u32_e32 v172, s31, v151
	ds_read_b128 v[128:131], v156
	ds_read_b128 v[142:145], v156 offset:1024
	ds_read_b128 v[146:149], v156 offset:2048
	ds_read_b128 v[156:159], v156 offset:3072
	ds_read_b128 v[160:163], v172
	ds_read_b128 v[164:167], v172 offset:1024
	ds_read_b128 v[168:171], v172 offset:2048
	ds_read_b128 v[172:175], v172 offset:3072
	v_lshl_add_u64 v[198:199], s[28:29], 0, v[138:139]
	s_add_i32 m0, s37, 0xc000
	ds_read_b128 v[176:179], v155
	ds_read_b128 v[194:197], v155 offset:1024
	ds_read_b128 v[206:209], v155 offset:2048
	ds_read_b128 v[210:213], v155 offset:3072
	ds_read_b128 v[214:217], v155 offset:4096
	ds_read_b128 v[220:223], v155 offset:5120
	ds_read_b128 v[224:227], v155 offset:6144
	ds_read_b128 v[228:231], v155 offset:7168
	global_load_lds_dwordx4 v[198:199], off
	v_lshl_add_u64 v[198:199], s[28:29], 0, v[140:141]
	s_add_i32 m0, s37, 0xe000
	s_nop 0
	global_load_lds_dwordx4 v[198:199], off
	s_waitcnt vmcnt(8)
	s_waitcnt lgkmcnt(0)
	s_barrier
	s_waitcnt lgkmcnt(0)
	v_mfma_f32_16x16x32_bf16 v[120:123], v[128:131], v[176:179], 0
	v_mfma_f32_16x16x32_bf16 v[116:119], v[146:149], v[176:179], 0
	v_mfma_f32_16x16x32_bf16 v[108:111], v[128:131], v[206:209], 0
	v_mfma_f32_16x16x32_bf16 v[100:103], v[146:149], v[206:209], 0
	v_mfma_f32_16x16x32_bf16 v[92:95], v[128:131], v[214:217], 0
	v_mfma_f32_16x16x32_bf16 v[84:87], v[146:149], v[214:217], 0
	v_mfma_f32_16x16x32_bf16 v[76:79], v[128:131], v[224:227], 0
	v_mfma_f32_16x16x32_bf16 v[68:71], v[146:149], v[224:227], 0
	v_mfma_f32_16x16x32_bf16 v[120:123], v[142:145], v[194:197], v[120:123]
	v_mfma_f32_16x16x32_bf16 v[116:119], v[156:159], v[194:197], v[116:119]
	v_mfma_f32_16x16x32_bf16 v[108:111], v[142:145], v[210:213], v[108:111]
	v_mfma_f32_16x16x32_bf16 v[100:103], v[156:159], v[210:213], v[100:103]
	v_mfma_f32_16x16x32_bf16 v[92:95], v[142:145], v[220:223], v[92:95]
	v_mfma_f32_16x16x32_bf16 v[84:87], v[156:159], v[220:223], v[84:87]
	v_mfma_f32_16x16x32_bf16 v[76:79], v[142:145], v[228:231], v[76:79]
	v_mfma_f32_16x16x32_bf16 v[68:71], v[156:159], v[228:231], v[68:71]
	v_mfma_f32_16x16x32_bf16 v[124:127], v[160:163], v[176:179], 0
	v_mfma_f32_16x16x32_bf16 v[112:115], v[168:171], v[176:179], 0
	v_mfma_f32_16x16x32_bf16 v[104:107], v[160:163], v[206:209], 0
	v_mfma_f32_16x16x32_bf16 v[96:99], v[168:171], v[206:209], 0
	v_mfma_f32_16x16x32_bf16 v[88:91], v[160:163], v[214:217], 0
	v_mfma_f32_16x16x32_bf16 v[80:83], v[168:171], v[214:217], 0
	v_mfma_f32_16x16x32_bf16 v[72:75], v[160:163], v[224:227], 0
	v_mfma_f32_16x16x32_bf16 v[64:67], v[168:171], v[224:227], 0
	v_mfma_f32_16x16x32_bf16 v[124:127], v[164:167], v[194:197], v[124:127]
	v_mfma_f32_16x16x32_bf16 v[112:115], v[172:175], v[194:197], v[112:115]
	v_mfma_f32_16x16x32_bf16 v[104:107], v[164:167], v[210:213], v[104:107]
	v_mfma_f32_16x16x32_bf16 v[96:99], v[172:175], v[210:213], v[96:99]
	v_mfma_f32_16x16x32_bf16 v[88:91], v[164:167], v[220:223], v[88:91]
	v_mfma_f32_16x16x32_bf16 v[80:83], v[172:175], v[220:223], v[80:83]
	v_mfma_f32_16x16x32_bf16 v[72:75], v[164:167], v[228:231], v[72:75]
	v_mfma_f32_16x16x32_bf16 v[64:67], v[172:175], v[228:231], v[64:67]
	s_barrier
	s_add_i32 s63, s63, s36
	v_lshl_add_u64 v[198:199], s[44:45], 0, v[180:181]
	s_mov_b32 m0, s63
	ds_read_b128 v[176:179], v155 offset:16384
	ds_read_b128 v[194:197], v155 offset:17408
	ds_read_b128 v[206:209], v155 offset:18432
	ds_read_b128 v[210:213], v155 offset:19456
	ds_read_b128 v[214:217], v155 offset:20480
	ds_read_b128 v[220:223], v155 offset:21504
	ds_read_b128 v[224:227], v155 offset:22528
	ds_read_b128 v[228:231], v155 offset:23552
	global_load_lds_dwordx4 v[198:199], off
	s_add_i32 m0, s63, 0x2000
	v_lshl_add_u64 v[202:203], s[44:45], 0, v[132:133]
	s_add_u32 s44, s44, s6
	s_addc_u32 s45, s45, s7
	s_add_i32 s31, s31, s36
	global_load_lds_dwordx4 v[202:203], off
	v_lshl_add_u64 v[232:233], s[44:45], 0, v[180:181]
	s_mov_b32 m0, s31
	v_lshl_add_u64 v[234:235], s[44:45], 0, v[132:133]
	global_load_lds_dwordx4 v[232:233], off
	s_add_i32 m0, s31, 0x2000
	v_lshl_add_u64 v[236:237], s[16:17], 0, v[136:137]
	global_load_lds_dwordx4 v[234:235], off
	s_mov_b32 m0, s37
	v_lshl_add_u64 v[238:239], s[16:17], 0, v[134:135]
	global_load_lds_dwordx4 v[236:237], off
	s_mov_b32 m0, s38
	s_nop 0
	global_load_lds_dwordx4 v[238:239], off
	s_waitcnt vmcnt(8)
	s_waitcnt lgkmcnt(0)
	s_barrier
	s_waitcnt lgkmcnt(0)
	v_mfma_f32_16x16x32_bf16 v[60:63], v[128:131], v[176:179], 0
	v_mfma_f32_16x16x32_bf16 v[52:55], v[146:149], v[176:179], 0
	v_mfma_f32_16x16x32_bf16 v[44:47], v[128:131], v[206:209], 0
	v_mfma_f32_16x16x32_bf16 v[36:39], v[146:149], v[206:209], 0
	v_mfma_f32_16x16x32_bf16 v[28:31], v[128:131], v[214:217], 0
	v_mfma_f32_16x16x32_bf16 v[20:23], v[146:149], v[214:217], 0
	v_mfma_f32_16x16x32_bf16 v[12:15], v[128:131], v[224:227], 0
	v_mfma_f32_16x16x32_bf16 v[4:7], v[146:149], v[224:227], 0
	v_mfma_f32_16x16x32_bf16 v[60:63], v[142:145], v[194:197], v[60:63]
	v_mfma_f32_16x16x32_bf16 v[52:55], v[156:159], v[194:197], v[52:55]
	v_mfma_f32_16x16x32_bf16 v[44:47], v[142:145], v[210:213], v[44:47]
	v_mfma_f32_16x16x32_bf16 v[36:39], v[156:159], v[210:213], v[36:39]
	v_mfma_f32_16x16x32_bf16 v[28:31], v[142:145], v[220:223], v[28:31]
	v_mfma_f32_16x16x32_bf16 v[20:23], v[156:159], v[220:223], v[20:23]
	v_mfma_f32_16x16x32_bf16 v[12:15], v[142:145], v[228:231], v[12:15]
	v_mfma_f32_16x16x32_bf16 v[4:7], v[156:159], v[228:231], v[4:7]
	v_mfma_f32_16x16x32_bf16 v[56:59], v[160:163], v[176:179], 0
	v_mfma_f32_16x16x32_bf16 v[48:51], v[168:171], v[176:179], 0
	v_mfma_f32_16x16x32_bf16 v[40:43], v[160:163], v[206:209], 0
	v_mfma_f32_16x16x32_bf16 v[32:35], v[168:171], v[206:209], 0
	v_mfma_f32_16x16x32_bf16 v[24:27], v[160:163], v[214:217], 0
	v_mfma_f32_16x16x32_bf16 v[16:19], v[168:171], v[214:217], 0
	v_mfma_f32_16x16x32_bf16 v[8:11], v[160:163], v[224:227], 0
	v_mfma_f32_16x16x32_bf16 v[0:3], v[168:171], v[224:227], 0
	v_mfma_f32_16x16x32_bf16 v[56:59], v[164:167], v[194:197], v[56:59]
	v_mfma_f32_16x16x32_bf16 v[48:51], v[172:175], v[194:197], v[48:51]
	v_mfma_f32_16x16x32_bf16 v[40:43], v[164:167], v[210:213], v[40:43]
	v_mfma_f32_16x16x32_bf16 v[32:35], v[172:175], v[210:213], v[32:35]
	v_mfma_f32_16x16x32_bf16 v[24:27], v[164:167], v[220:223], v[24:27]
	v_mfma_f32_16x16x32_bf16 v[16:19], v[172:175], v[220:223], v[16:19]
	v_mfma_f32_16x16x32_bf16 v[8:11], v[164:167], v[228:231], v[8:11]
	v_mfma_f32_16x16x32_bf16 v[0:3], v[172:175], v[228:231], v[0:3]
	s_barrier
	s_add_i32 s31, 0, 0x18000
	s_add_i32 s44, 0, 0x1c000
	v_add_u32_e32 v156, s31, v151
	v_add_u32_e32 v172, s44, v151
	ds_read_b128 v[128:131], v156
	ds_read_b128 v[142:145], v156 offset:1024
	ds_read_b128 v[146:149], v156 offset:2048
	ds_read_b128 v[156:159], v156 offset:3072
	ds_read_b128 v[160:163], v172
	ds_read_b128 v[164:167], v172 offset:1024
	ds_read_b128 v[168:171], v172 offset:2048
	ds_read_b128 v[172:175], v172 offset:3072
	s_add_u32 s16, s16, s6
	s_addc_u32 s17, s17, s7
	s_mov_b32 m0, s39
	v_lshl_add_u64 v[240:241], s[16:17], 0, v[136:137]
	ds_read_b128 v[176:179], v155 offset:32768
	ds_read_b128 v[194:197], v155 offset:33792
	ds_read_b128 v[206:209], v155 offset:34816
	ds_read_b128 v[210:213], v155 offset:35840
	ds_read_b128 v[214:217], v155 offset:36864
	ds_read_b128 v[220:223], v155 offset:37888
	ds_read_b128 v[224:227], v155 offset:38912
	ds_read_b128 v[228:231], v155 offset:39936
	global_load_lds_dwordx4 v[240:241], off
	v_lshl_add_u64 v[240:241], s[16:17], 0, v[134:135]
	s_mov_b32 m0, s46
	s_nop 0
	global_load_lds_dwordx4 v[240:241], off
	s_waitcnt vmcnt(8)
	s_waitcnt lgkmcnt(0)
	s_barrier
	s_waitcnt lgkmcnt(0)
	v_mfma_f32_16x16x32_bf16 v[120:123], v[128:131], v[176:179], v[120:123]
	v_mfma_f32_16x16x32_bf16 v[116:119], v[146:149], v[176:179], v[116:119]
	v_mfma_f32_16x16x32_bf16 v[108:111], v[128:131], v[206:209], v[108:111]
	v_mfma_f32_16x16x32_bf16 v[100:103], v[146:149], v[206:209], v[100:103]
	v_mfma_f32_16x16x32_bf16 v[92:95], v[128:131], v[214:217], v[92:95]
	v_mfma_f32_16x16x32_bf16 v[84:87], v[146:149], v[214:217], v[84:87]
	v_mfma_f32_16x16x32_bf16 v[76:79], v[128:131], v[224:227], v[76:79]
	v_mfma_f32_16x16x32_bf16 v[68:71], v[146:149], v[224:227], v[68:71]
	v_mfma_f32_16x16x32_bf16 v[120:123], v[142:145], v[194:197], v[120:123]
	v_mfma_f32_16x16x32_bf16 v[116:119], v[156:159], v[194:197], v[116:119]
	v_mfma_f32_16x16x32_bf16 v[108:111], v[142:145], v[210:213], v[108:111]
	v_mfma_f32_16x16x32_bf16 v[100:103], v[156:159], v[210:213], v[100:103]
	v_mfma_f32_16x16x32_bf16 v[92:95], v[142:145], v[220:223], v[92:95]
	v_mfma_f32_16x16x32_bf16 v[84:87], v[156:159], v[220:223], v[84:87]
	v_mfma_f32_16x16x32_bf16 v[76:79], v[142:145], v[228:231], v[76:79]
	v_mfma_f32_16x16x32_bf16 v[68:71], v[156:159], v[228:231], v[68:71]
	v_mfma_f32_16x16x32_bf16 v[124:127], v[160:163], v[176:179], v[124:127]
	v_mfma_f32_16x16x32_bf16 v[112:115], v[168:171], v[176:179], v[112:115]
	v_mfma_f32_16x16x32_bf16 v[104:107], v[160:163], v[206:209], v[104:107]
	v_mfma_f32_16x16x32_bf16 v[96:99], v[168:171], v[206:209], v[96:99]
	v_mfma_f32_16x16x32_bf16 v[88:91], v[160:163], v[214:217], v[88:91]
	v_mfma_f32_16x16x32_bf16 v[80:83], v[168:171], v[214:217], v[80:83]
	v_mfma_f32_16x16x32_bf16 v[72:75], v[160:163], v[224:227], v[72:75]
	v_mfma_f32_16x16x32_bf16 v[64:67], v[168:171], v[224:227], v[64:67]
	v_mfma_f32_16x16x32_bf16 v[124:127], v[164:167], v[194:197], v[124:127]
	v_mfma_f32_16x16x32_bf16 v[112:115], v[172:175], v[194:197], v[112:115]
	v_mfma_f32_16x16x32_bf16 v[104:107], v[164:167], v[210:213], v[104:107]
	v_mfma_f32_16x16x32_bf16 v[96:99], v[172:175], v[210:213], v[96:99]
	v_mfma_f32_16x16x32_bf16 v[88:91], v[164:167], v[220:223], v[88:91]
	v_mfma_f32_16x16x32_bf16 v[80:83], v[172:175], v[220:223], v[80:83]
	v_mfma_f32_16x16x32_bf16 v[72:75], v[164:167], v[228:231], v[72:75]
	v_mfma_f32_16x16x32_bf16 v[64:67], v[172:175], v[228:231], v[64:67]
	s_barrier
	s_add_i32 s16, s31, s36
	v_lshl_add_u64 v[198:199], v[198:199], 0, s[12:13]
	s_mov_b32 m0, s16
	ds_read_b128 v[176:179], v155 offset:49152
	ds_read_b128 v[194:197], v155 offset:50176
	ds_read_b128 v[206:209], v155 offset:51200
	ds_read_b128 v[210:213], v155 offset:52224
	ds_read_b128 v[214:217], v155 offset:53248
	ds_read_b128 v[220:223], v155 offset:54272
	ds_read_b128 v[224:227], v155 offset:55296
	ds_read_b128 v[228:231], v155 offset:56320
	global_load_lds_dwordx4 v[198:199], off
	v_lshl_add_u64 v[198:199], v[202:203], 0, s[12:13]
	s_add_i32 m0, s16, 0x2000
	s_add_i32 s16, s44, s36
	global_load_lds_dwordx4 v[198:199], off
	v_lshl_add_u64 v[198:199], v[232:233], 0, s[12:13]
	s_mov_b32 m0, s16
	s_nop 0
	global_load_lds_dwordx4 v[198:199], off
	v_lshl_add_u64 v[198:199], v[234:235], 0, s[12:13]
	s_add_i32 m0, s16, 0x2000
	s_nop 0
	global_load_lds_dwordx4 v[198:199], off
	v_lshl_add_u64 v[198:199], v[236:237], 0, s[12:13]
	s_mov_b32 m0, s49
	s_nop 0
	global_load_lds_dwordx4 v[198:199], off
	v_lshl_add_u64 v[198:199], v[238:239], 0, s[12:13]
	s_mov_b32 m0, s52
	s_nop 0
	global_load_lds_dwordx4 v[198:199], off
	s_waitcnt vmcnt(8)
	s_waitcnt lgkmcnt(0)
	s_barrier
	s_waitcnt lgkmcnt(0)
	v_mfma_f32_16x16x32_bf16 v[60:63], v[128:131], v[176:179], v[60:63]
	v_mfma_f32_16x16x32_bf16 v[52:55], v[146:149], v[176:179], v[52:55]
	v_mfma_f32_16x16x32_bf16 v[44:47], v[128:131], v[206:209], v[44:47]
	v_mfma_f32_16x16x32_bf16 v[36:39], v[146:149], v[206:209], v[36:39]
	v_mfma_f32_16x16x32_bf16 v[28:31], v[128:131], v[214:217], v[28:31]
	v_mfma_f32_16x16x32_bf16 v[20:23], v[146:149], v[214:217], v[20:23]
	v_mfma_f32_16x16x32_bf16 v[12:15], v[128:131], v[224:227], v[12:15]
	v_mfma_f32_16x16x32_bf16 v[4:7], v[146:149], v[224:227], v[4:7]
	v_mfma_f32_16x16x32_bf16 v[60:63], v[142:145], v[194:197], v[60:63]
	v_mfma_f32_16x16x32_bf16 v[52:55], v[156:159], v[194:197], v[52:55]
	v_mfma_f32_16x16x32_bf16 v[44:47], v[142:145], v[210:213], v[44:47]
	v_mfma_f32_16x16x32_bf16 v[36:39], v[156:159], v[210:213], v[36:39]
	v_mfma_f32_16x16x32_bf16 v[28:31], v[142:145], v[220:223], v[28:31]
	v_mfma_f32_16x16x32_bf16 v[20:23], v[156:159], v[220:223], v[20:23]
	v_mfma_f32_16x16x32_bf16 v[12:15], v[142:145], v[228:231], v[12:15]
	v_mfma_f32_16x16x32_bf16 v[4:7], v[156:159], v[228:231], v[4:7]
	v_mfma_f32_16x16x32_bf16 v[56:59], v[160:163], v[176:179], v[56:59]
	v_mfma_f32_16x16x32_bf16 v[48:51], v[168:171], v[176:179], v[48:51]
	v_mfma_f32_16x16x32_bf16 v[40:43], v[160:163], v[206:209], v[40:43]
	v_mfma_f32_16x16x32_bf16 v[32:35], v[168:171], v[206:209], v[32:35]
	v_mfma_f32_16x16x32_bf16 v[24:27], v[160:163], v[214:217], v[24:27]
	v_mfma_f32_16x16x32_bf16 v[16:19], v[168:171], v[214:217], v[16:19]
	v_mfma_f32_16x16x32_bf16 v[8:11], v[160:163], v[224:227], v[8:11]
	v_mfma_f32_16x16x32_bf16 v[0:3], v[168:171], v[224:227], v[0:3]
	v_mfma_f32_16x16x32_bf16 v[56:59], v[164:167], v[194:197], v[56:59]
	v_mfma_f32_16x16x32_bf16 v[48:51], v[172:175], v[194:197], v[48:51]
	v_mfma_f32_16x16x32_bf16 v[40:43], v[164:167], v[210:213], v[40:43]
	v_mfma_f32_16x16x32_bf16 v[32:35], v[172:175], v[210:213], v[32:35]
	v_mfma_f32_16x16x32_bf16 v[24:27], v[164:167], v[220:223], v[24:27]
	v_mfma_f32_16x16x32_bf16 v[16:19], v[172:175], v[220:223], v[16:19]
	v_mfma_f32_16x16x32_bf16 v[8:11], v[164:167], v[228:231], v[8:11]
	v_mfma_f32_16x16x32_bf16 v[0:3], v[172:175], v[228:231], v[0:3]
	s_barrier
	s_add_u32 s28, s28, 0x100
	s_addc_u32 s29, s29, 0
	s_add_u32 s10, s10, 0x100
	s_addc_u32 s11, s11, 0
	s_cmp_ge_i32 s30, s47
	s_mov_b32 s16, s30
	s_cbranch_scc1 .Lpeelx_14

.Lpeelx_14:
	v_readlane_b32 s63, v253, 0
	s_and_b64 vcc, exec, s[22:23]
	s_cbranch_vccz .LBB0_1142

.LBB0_1222:
	s_andn2_b64 vcc, exec, s[18:19]
	s_waitcnt lgkmcnt(0)
	s_cbranch_vccnz .LBB0_1226
	s_add_u32 s26, s26, 0x80
	s_addc_u32 s27, s27, 0
	s_add_u32 s10, s28, 0x100
	s_addc_u32 s11, s29, 0
	s_mov_b32 s28, 0
	s_cmp_lg_u32 s100, 0
	s_cbranch_scc0 .Llbb_11
	s_barrier
	s_mov_b32 s100, 0
.Llbb_11:
	s_add_i32 s44, s28, 2
	s_add_u32 s45, s26, 0x80
	s_addc_u32 s29, s27, 0
	s_add_i32 s62, 0, 0x10000
	s_cmp_eq_u32 s49, s28
	s_cselect_b32 s29, s23, s29
	s_cselect_b32 s28, s22, s45
	s_cselect_b32 s61, s25, s11
	s_cselect_b32 s60, s24, s10
	s_add_i32 s45, 0, 0x14000
	v_add_u32_e32 v140, s62, v199
	v_add_u32_e32 v166, s45, v199
	ds_read_b128 v[128:131], v140
	ds_read_b128 v[132:135], v140 offset:1024
	ds_read_b128 v[136:139], v140 offset:2048
	ds_read_b128 v[140:143], v140 offset:3072
	ds_read_b128 v[144:147], v166
	ds_read_b128 v[148:151], v166 offset:1024
	ds_read_b128 v[152:155], v166 offset:2048
	ds_read_b128 v[166:169], v166 offset:3072
	v_lshl_add_u64 v[178:179], s[26:27], 0, v[162:163]
	s_add_i32 m0, s35, 0xc000
	ds_read_b128 v[170:173], v206
	ds_read_b128 v[174:177], v206 offset:1024
	ds_read_b128 v[194:197], v206 offset:2048
	ds_read_b128 v[208:211], v206 offset:3072
	ds_read_b128 v[212:215], v206 offset:4096
	ds_read_b128 v[220:223], v206 offset:5120
	ds_read_b128 v[224:227], v206 offset:6144
	ds_read_b128 v[228:231], v206 offset:7168
	global_load_lds_dwordx4 v[178:179], off
	v_lshl_add_u64 v[178:179], s[26:27], 0, v[164:165]
	s_add_i32 m0, s35, 0xe000
	s_nop 0
	global_load_lds_dwordx4 v[178:179], off
	s_waitcnt vmcnt(8)
	s_waitcnt lgkmcnt(0)
	s_barrier
	s_waitcnt lgkmcnt(0)
	v_mfma_f32_16x16x32_bf16 v[120:123], v[128:131], v[170:173], 0
	v_mfma_f32_16x16x32_bf16 v[124:127], v[136:139], v[170:173], 0
	v_mfma_f32_16x16x32_bf16 v[108:111], v[128:131], v[194:197], 0
	v_mfma_f32_16x16x32_bf16 v[104:107], v[136:139], v[194:197], 0
	v_mfma_f32_16x16x32_bf16 v[92:95], v[128:131], v[212:215], 0
	v_mfma_f32_16x16x32_bf16 v[88:91], v[136:139], v[212:215], 0
	v_mfma_f32_16x16x32_bf16 v[76:79], v[128:131], v[224:227], 0
	v_mfma_f32_16x16x32_bf16 v[72:75], v[136:139], v[224:227], 0
	v_mfma_f32_16x16x32_bf16 v[120:123], v[132:135], v[174:177], v[120:123]
	v_mfma_f32_16x16x32_bf16 v[124:127], v[140:143], v[174:177], v[124:127]
	v_mfma_f32_16x16x32_bf16 v[108:111], v[132:135], v[208:211], v[108:111]
	v_mfma_f32_16x16x32_bf16 v[104:107], v[140:143], v[208:211], v[104:107]
	v_mfma_f32_16x16x32_bf16 v[92:95], v[132:135], v[220:223], v[92:95]
	v_mfma_f32_16x16x32_bf16 v[88:91], v[140:143], v[220:223], v[88:91]
	v_mfma_f32_16x16x32_bf16 v[76:79], v[132:135], v[228:231], v[76:79]
	v_mfma_f32_16x16x32_bf16 v[72:75], v[140:143], v[228:231], v[72:75]
	v_mfma_f32_16x16x32_bf16 v[116:119], v[144:147], v[170:173], 0
	v_mfma_f32_16x16x32_bf16 v[112:115], v[152:155], v[170:173], 0
	v_mfma_f32_16x16x32_bf16 v[100:103], v[144:147], v[194:197], 0
	v_mfma_f32_16x16x32_bf16 v[96:99], v[152:155], v[194:197], 0
	v_mfma_f32_16x16x32_bf16 v[84:87], v[144:147], v[212:215], 0
	v_mfma_f32_16x16x32_bf16 v[80:83], v[152:155], v[212:215], 0
	v_mfma_f32_16x16x32_bf16 v[68:71], v[144:147], v[224:227], 0
	v_mfma_f32_16x16x32_bf16 v[64:67], v[152:155], v[224:227], 0
	v_mfma_f32_16x16x32_bf16 v[116:119], v[148:151], v[174:177], v[116:119]
	v_mfma_f32_16x16x32_bf16 v[112:115], v[166:169], v[174:177], v[112:115]
	v_mfma_f32_16x16x32_bf16 v[100:103], v[148:151], v[208:211], v[100:103]
	v_mfma_f32_16x16x32_bf16 v[96:99], v[166:169], v[208:211], v[96:99]
	v_mfma_f32_16x16x32_bf16 v[84:87], v[148:151], v[220:223], v[84:87]
	v_mfma_f32_16x16x32_bf16 v[80:83], v[166:169], v[220:223], v[80:83]
	v_mfma_f32_16x16x32_bf16 v[68:71], v[148:151], v[228:231], v[68:71]
	v_mfma_f32_16x16x32_bf16 v[64:67], v[166:169], v[228:231], v[64:67]
	s_barrier
	s_add_i32 s62, s62, s34
	v_lshl_add_u64 v[178:179], s[60:61], 0, v[180:181]
	s_mov_b32 m0, s62
	ds_read_b128 v[170:173], v206 offset:16384
	ds_read_b128 v[174:177], v206 offset:17408
	ds_read_b128 v[194:197], v206 offset:18432
	ds_read_b128 v[208:211], v206 offset:19456
	ds_read_b128 v[212:215], v206 offset:20480
	ds_read_b128 v[220:223], v206 offset:21504
	ds_read_b128 v[224:227], v206 offset:22528
	ds_read_b128 v[228:231], v206 offset:23552
	global_load_lds_dwordx4 v[178:179], off
	s_add_i32 m0, s62, 0x2000
	v_lshl_add_u64 v[202:203], s[60:61], 0, v[156:157]
	s_add_u32 s60, s60, s6
	s_addc_u32 s61, s61, s7
	s_add_i32 s45, s45, s34
	global_load_lds_dwordx4 v[202:203], off
	v_lshl_add_u64 v[216:217], s[60:61], 0, v[180:181]
	s_mov_b32 m0, s45
	v_lshl_add_u64 v[232:233], s[60:61], 0, v[156:157]
	global_load_lds_dwordx4 v[216:217], off
	s_add_i32 m0, s45, 0x2000
	v_lshl_add_u64 v[234:235], s[28:29], 0, v[160:161]
	global_load_lds_dwordx4 v[232:233], off
	s_mov_b32 m0, s35
	v_lshl_add_u64 v[236:237], s[28:29], 0, v[158:159]
	global_load_lds_dwordx4 v[234:235], off
	s_mov_b32 m0, s36
	s_nop 0
	global_load_lds_dwordx4 v[236:237], off
	s_waitcnt vmcnt(8)
	s_waitcnt lgkmcnt(0)
	s_barrier
	s_waitcnt lgkmcnt(0)
	v_mfma_f32_16x16x32_bf16 v[60:63], v[128:131], v[170:173], 0
	v_mfma_f32_16x16x32_bf16 v[56:59], v[136:139], v[170:173], 0
	v_mfma_f32_16x16x32_bf16 v[44:47], v[128:131], v[194:197], 0
	v_mfma_f32_16x16x32_bf16 v[40:43], v[136:139], v[194:197], 0
	v_mfma_f32_16x16x32_bf16 v[28:31], v[128:131], v[212:215], 0
	v_mfma_f32_16x16x32_bf16 v[24:27], v[136:139], v[212:215], 0
	v_mfma_f32_16x16x32_bf16 v[12:15], v[128:131], v[224:227], 0
	v_mfma_f32_16x16x32_bf16 v[8:11], v[136:139], v[224:227], 0
	v_mfma_f32_16x16x32_bf16 v[60:63], v[132:135], v[174:177], v[60:63]
	v_mfma_f32_16x16x32_bf16 v[56:59], v[140:143], v[174:177], v[56:59]
	v_mfma_f32_16x16x32_bf16 v[44:47], v[132:135], v[208:211], v[44:47]
	v_mfma_f32_16x16x32_bf16 v[40:43], v[140:143], v[208:211], v[40:43]
	v_mfma_f32_16x16x32_bf16 v[28:31], v[132:135], v[220:223], v[28:31]
	v_mfma_f32_16x16x32_bf16 v[24:27], v[140:143], v[220:223], v[24:27]
	v_mfma_f32_16x16x32_bf16 v[12:15], v[132:135], v[228:231], v[12:15]
	v_mfma_f32_16x16x32_bf16 v[8:11], v[140:143], v[228:231], v[8:11]
	v_mfma_f32_16x16x32_bf16 v[52:55], v[144:147], v[170:173], 0
	v_mfma_f32_16x16x32_bf16 v[48:51], v[152:155], v[170:173], 0
	v_mfma_f32_16x16x32_bf16 v[36:39], v[144:147], v[194:197], 0
	v_mfma_f32_16x16x32_bf16 v[32:35], v[152:155], v[194:197], 0
	v_mfma_f32_16x16x32_bf16 v[20:23], v[144:147], v[212:215], 0
	v_mfma_f32_16x16x32_bf16 v[16:19], v[152:155], v[212:215], 0
	v_mfma_f32_16x16x32_bf16 v[4:7], v[144:147], v[224:227], 0
	v_mfma_f32_16x16x32_bf16 v[0:3], v[152:155], v[224:227], 0
	v_mfma_f32_16x16x32_bf16 v[52:55], v[148:151], v[174:177], v[52:55]
	v_mfma_f32_16x16x32_bf16 v[48:51], v[166:169], v[174:177], v[48:51]
	v_mfma_f32_16x16x32_bf16 v[36:39], v[148:151], v[208:211], v[36:39]
	v_mfma_f32_16x16x32_bf16 v[32:35], v[166:169], v[208:211], v[32:35]
	v_mfma_f32_16x16x32_bf16 v[20:23], v[148:151], v[220:223], v[20:23]
	v_mfma_f32_16x16x32_bf16 v[16:19], v[166:169], v[220:223], v[16:19]
	v_mfma_f32_16x16x32_bf16 v[4:7], v[148:151], v[228:231], v[4:7]
	v_mfma_f32_16x16x32_bf16 v[0:3], v[166:169], v[228:231], v[0:3]
	s_barrier
	s_add_i32 s45, 0, 0x18000
	s_add_i32 s60, 0, 0x1c000
	v_add_u32_e32 v140, s45, v199
	v_add_u32_e32 v166, s60, v199
	ds_read_b128 v[128:131], v140
	ds_read_b128 v[132:135], v140 offset:1024
	ds_read_b128 v[136:139], v140 offset:2048
	ds_read_b128 v[140:143], v140 offset:3072
	ds_read_b128 v[144:147], v166
	ds_read_b128 v[148:151], v166 offset:1024
	ds_read_b128 v[152:155], v166 offset:2048
	ds_read_b128 v[166:169], v166 offset:3072
	s_add_u32 s28, s28, s6
	s_addc_u32 s29, s29, s7
	s_mov_b32 m0, s37
	v_lshl_add_u64 v[238:239], s[28:29], 0, v[160:161]
	ds_read_b128 v[170:173], v206 offset:32768
	ds_read_b128 v[174:177], v206 offset:33792
	ds_read_b128 v[194:197], v206 offset:34816
	ds_read_b128 v[208:211], v206 offset:35840
	ds_read_b128 v[212:215], v206 offset:36864
	ds_read_b128 v[220:223], v206 offset:37888
	ds_read_b128 v[224:227], v206 offset:38912
	ds_read_b128 v[228:231], v206 offset:39936
	global_load_lds_dwordx4 v[238:239], off
	v_lshl_add_u64 v[238:239], s[28:29], 0, v[158:159]
	s_mov_b32 m0, s38
	s_nop 0
	global_load_lds_dwordx4 v[238:239], off
	s_waitcnt vmcnt(8)
	s_waitcnt lgkmcnt(0)
	s_barrier
	s_waitcnt lgkmcnt(0)
	v_mfma_f32_16x16x32_bf16 v[120:123], v[128:131], v[170:173], v[120:123]
	v_mfma_f32_16x16x32_bf16 v[124:127], v[136:139], v[170:173], v[124:127]
	v_mfma_f32_16x16x32_bf16 v[108:111], v[128:131], v[194:197], v[108:111]
	v_mfma_f32_16x16x32_bf16 v[104:107], v[136:139], v[194:197], v[104:107]
	v_mfma_f32_16x16x32_bf16 v[92:95], v[128:131], v[212:215], v[92:95]
	v_mfma_f32_16x16x32_bf16 v[88:91], v[136:139], v[212:215], v[88:91]
	v_mfma_f32_16x16x32_bf16 v[76:79], v[128:131], v[224:227], v[76:79]
	v_mfma_f32_16x16x32_bf16 v[72:75], v[136:139], v[224:227], v[72:75]
	v_mfma_f32_16x16x32_bf16 v[120:123], v[132:135], v[174:177], v[120:123]
	v_mfma_f32_16x16x32_bf16 v[124:127], v[140:143], v[174:177], v[124:127]
	v_mfma_f32_16x16x32_bf16 v[108:111], v[132:135], v[208:211], v[108:111]
	v_mfma_f32_16x16x32_bf16 v[104:107], v[140:143], v[208:211], v[104:107]
	v_mfma_f32_16x16x32_bf16 v[92:95], v[132:135], v[220:223], v[92:95]
	v_mfma_f32_16x16x32_bf16 v[88:91], v[140:143], v[220:223], v[88:91]
	v_mfma_f32_16x16x32_bf16 v[76:79], v[132:135], v[228:231], v[76:79]
	v_mfma_f32_16x16x32_bf16 v[72:75], v[140:143], v[228:231], v[72:75]
	v_mfma_f32_16x16x32_bf16 v[116:119], v[144:147], v[170:173], v[116:119]
	v_mfma_f32_16x16x32_bf16 v[112:115], v[152:155], v[170:173], v[112:115]
	v_mfma_f32_16x16x32_bf16 v[100:103], v[144:147], v[194:197], v[100:103]
	v_mfma_f32_16x16x32_bf16 v[96:99], v[152:155], v[194:197], v[96:99]
	v_mfma_f32_16x16x32_bf16 v[84:87], v[144:147], v[212:215], v[84:87]
	v_mfma_f32_16x16x32_bf16 v[80:83], v[152:155], v[212:215], v[80:83]
	v_mfma_f32_16x16x32_bf16 v[68:71], v[144:147], v[224:227], v[68:71]
	v_mfma_f32_16x16x32_bf16 v[64:67], v[152:155], v[224:227], v[64:67]
	v_mfma_f32_16x16x32_bf16 v[116:119], v[148:151], v[174:177], v[116:119]
	v_mfma_f32_16x16x32_bf16 v[112:115], v[166:169], v[174:177], v[112:115]
	v_mfma_f32_16x16x32_bf16 v[100:103], v[148:151], v[208:211], v[100:103]
	v_mfma_f32_16x16x32_bf16 v[96:99], v[166:169], v[208:211], v[96:99]
	v_mfma_f32_16x16x32_bf16 v[84:87], v[148:151], v[220:223], v[84:87]
	v_mfma_f32_16x16x32_bf16 v[80:83], v[166:169], v[220:223], v[80:83]
	v_mfma_f32_16x16x32_bf16 v[68:71], v[148:151], v[228:231], v[68:71]
	v_mfma_f32_16x16x32_bf16 v[64:67], v[166:169], v[228:231], v[64:67]
	s_barrier
	s_add_i32 s28, s45, s34
	v_lshl_add_u64 v[178:179], v[178:179], 0, s[12:13]
	s_mov_b32 m0, s28
	ds_read_b128 v[170:173], v206 offset:49152
	ds_read_b128 v[174:177], v206 offset:50176
	ds_read_b128 v[194:197], v206 offset:51200
	ds_read_b128 v[208:211], v206 offset:52224
	ds_read_b128 v[212:215], v206 offset:53248
	ds_read_b128 v[220:223], v206 offset:54272
	ds_read_b128 v[224:227], v206 offset:55296
	ds_read_b128 v[228:231], v206 offset:56320
	global_load_lds_dwordx4 v[178:179], off
	v_lshl_add_u64 v[178:179], v[202:203], 0, s[12:13]
	s_add_i32 m0, s28, 0x2000
	s_add_i32 s28, s60, s34
	global_load_lds_dwordx4 v[178:179], off
	v_lshl_add_u64 v[178:179], v[216:217], 0, s[12:13]
	s_mov_b32 m0, s28
	s_nop 0
	global_load_lds_dwordx4 v[178:179], off
	v_lshl_add_u64 v[178:179], v[232:233], 0, s[12:13]
	s_add_i32 m0, s28, 0x2000
	s_nop 0
	global_load_lds_dwordx4 v[178:179], off
	v_lshl_add_u64 v[178:179], v[234:235], 0, s[12:13]
	s_mov_b32 m0, s47
	s_nop 0
	global_load_lds_dwordx4 v[178:179], off
	v_lshl_add_u64 v[178:179], v[236:237], 0, s[12:13]
	s_mov_b32 m0, s48
	s_nop 0
	global_load_lds_dwordx4 v[178:179], off
	s_waitcnt vmcnt(8)
	s_waitcnt lgkmcnt(0)
	s_barrier
	s_waitcnt lgkmcnt(0)
	v_mfma_f32_16x16x32_bf16 v[60:63], v[128:131], v[170:173], v[60:63]
	v_mfma_f32_16x16x32_bf16 v[56:59], v[136:139], v[170:173], v[56:59]
	v_mfma_f32_16x16x32_bf16 v[44:47], v[128:131], v[194:197], v[44:47]
	v_mfma_f32_16x16x32_bf16 v[40:43], v[136:139], v[194:197], v[40:43]
	v_mfma_f32_16x16x32_bf16 v[28:31], v[128:131], v[212:215], v[28:31]
	v_mfma_f32_16x16x32_bf16 v[24:27], v[136:139], v[212:215], v[24:27]
	v_mfma_f32_16x16x32_bf16 v[12:15], v[128:131], v[224:227], v[12:15]
	v_mfma_f32_16x16x32_bf16 v[8:11], v[136:139], v[224:227], v[8:11]
	v_mfma_f32_16x16x32_bf16 v[60:63], v[132:135], v[174:177], v[60:63]
	v_mfma_f32_16x16x32_bf16 v[56:59], v[140:143], v[174:177], v[56:59]
	v_mfma_f32_16x16x32_bf16 v[44:47], v[132:135], v[208:211], v[44:47]
	v_mfma_f32_16x16x32_bf16 v[40:43], v[140:143], v[208:211], v[40:43]
	v_mfma_f32_16x16x32_bf16 v[28:31], v[132:135], v[220:223], v[28:31]
	v_mfma_f32_16x16x32_bf16 v[24:27], v[140:143], v[220:223], v[24:27]
	v_mfma_f32_16x16x32_bf16 v[12:15], v[132:135], v[228:231], v[12:15]
	v_mfma_f32_16x16x32_bf16 v[8:11], v[140:143], v[228:231], v[8:11]
	v_mfma_f32_16x16x32_bf16 v[52:55], v[144:147], v[170:173], v[52:55]
	v_mfma_f32_16x16x32_bf16 v[48:51], v[152:155], v[170:173], v[48:51]
	v_mfma_f32_16x16x32_bf16 v[36:39], v[144:147], v[194:197], v[36:39]
	v_mfma_f32_16x16x32_bf16 v[32:35], v[152:155], v[194:197], v[32:35]
	v_mfma_f32_16x16x32_bf16 v[20:23], v[144:147], v[212:215], v[20:23]
	v_mfma_f32_16x16x32_bf16 v[16:19], v[152:155], v[212:215], v[16:19]
	v_mfma_f32_16x16x32_bf16 v[4:7], v[144:147], v[224:227], v[4:7]
	v_mfma_f32_16x16x32_bf16 v[0:3], v[152:155], v[224:227], v[0:3]
	v_mfma_f32_16x16x32_bf16 v[52:55], v[148:151], v[174:177], v[52:55]
	v_mfma_f32_16x16x32_bf16 v[48:51], v[166:169], v[174:177], v[48:51]
	v_mfma_f32_16x16x32_bf16 v[36:39], v[148:151], v[208:211], v[36:39]
	v_mfma_f32_16x16x32_bf16 v[32:35], v[166:169], v[208:211], v[32:35]
	v_mfma_f32_16x16x32_bf16 v[20:23], v[148:151], v[220:223], v[20:23]
	v_mfma_f32_16x16x32_bf16 v[16:19], v[166:169], v[220:223], v[16:19]
	v_mfma_f32_16x16x32_bf16 v[4:7], v[148:151], v[228:231], v[4:7]
	v_mfma_f32_16x16x32_bf16 v[0:3], v[166:169], v[228:231], v[0:3]
	s_barrier
	s_add_u32 s26, s26, 0x100
	s_addc_u32 s27, s27, 0
	s_add_u32 s10, s10, 0x100
	s_addc_u32 s11, s11, 0
	s_cmp_ge_i32 s44, s46
	s_mov_b32 s28, s44
	s_cbranch_scc1 .Lpeelx_15

.Lpeelx_15:
	v_readlane_b32 s60, v253, 16
	v_readlane_b32 s61, v253, 17
